# v78 + same priority exchange (MFMA 2 > softmax 1 > loads 0) in the tail tiles
# baseline (speedup 1.0000x reference)
; #define LAS __attribute__((address_space(3)))
; DI void expsum(f32x16& p, float& l_reg, bf16x8& pa0, bf16x8& pa1) {
; #pragma unroll
;     for (int r = 0; r < 16; ++r) p[r] = __builtin_amdgcn_exp2f(p[r]);
;     float ps = 0.f;
; #pragma unroll
;     for (int r = 0; r < 16; ++r) ps += p[r];
;     l_reg += ps; asm volatile("" : "+v"(l_reg));
;     ...
;     ATT_PK4(p, 0, pa0); ATT_PK4(p, 8, pa1);
;     ...
; }
; DI int v_rd_base(int lane) { return ((lane & 3) << 3) | (((lane >> 2) & 3) << 6) | (((lane >> 4) & 1) << 5) | (((lane >> 5) & 1) << 8); }
; template <int OFF> DI s16x4 tr_read(int vb) { s16x4 r; asm volatile("ds_read_b64_tr_b16 %0, %1 offset:%2" : "=&v"(r) : "v"(vb), "i"(OFF) : "memory"); return r; }
; template <int H> DI void v_reads(s16x4* vf, int vb) {
;     vf[0] = tr_read<v_rd_off(0, 2 * H, 0)>(vb); vf[1] = tr_read<v_rd_off(0, 2 * H, 1)>(vb); vf[2] = tr_read<v_rd_off(0, 2 * H + 1, 0)>(vb); vf[3] = tr_read<v_rd_off(0, 2 * H + 1, 1)>(vb);
;     vf[4] = tr_read<v_rd_off(1, 2 * H, 0)>(vb); vf[5] = tr_read<v_rd_off(1, 2 * H, 1)>(vb); vf[6] = tr_read<v_rd_off(1, 2 * H + 1, 0)>(vb); vf[7] = tr_read<v_rd_off(1, 2 * H + 1, 1)>(vb);
;     vf[8] = tr_read<v_rd_off(2, 2 * H, 0)>(vb); vf[9] = tr_read<v_rd_off(2, 2 * H, 1)>(vb); vf[10] = tr_read<v_rd_off(2, 2 * H + 1, 0)>(vb); vf[11] = tr_read<v_rd_off(2, 2 * H + 1, 1)>(vb);
;     vf[12] = tr_read<v_rd_off(3, 2 * H, 0)>(vb); vf[13] = tr_read<v_rd_off(3, 2 * H, 1)>(vb); vf[14] = tr_read<v_rd_off(3, 2 * H + 1, 0)>(vb); vf[15] = tr_read<v_rd_off(3, 2 * H + 1, 1)>(vb);
; }
; DI void pv_mma(f32x16* o, const s16x4* vf, bf16x8 pa0, bf16x8 pa1) {
;     ...
; #pragma unroll
;     for (int d0 = 0; d0 < 4; ++d0) {
;         o[d0] = __builtin_amdgcn_mfma_f32_32x32x16_bf16(pa0, ATT_PK(vf[4 * d0], vf[4 * d0 + 1]), o[d0], 0, 0, 0);
;         o[d0] = __builtin_amdgcn_mfma_f32_32x32x16_bf16(pa1, ATT_PK(vf[4 * d0 + 2], vf[4 * d0 + 3]), o[d0], 0, 0, 0); }
;     ...
; }
; template <int DQK, int D0A, int D0B> DI void k_reads(bf16x8* kf, const LAS unsigned char* Ks, int half, int r32, int hi) {
; #pragma unroll
;     for (int d0 = D0A; d0 < D0B; ++d0) kf[d0 - D0A] = *(const LAS bf16x8*)(Ks + half * (32 * DQK * 2) + kswz<DQK>(r32, (d0 * 16 + hi * 8) * 2));
; }
; template <int D0A, int D0B> DI void qk_mma(f32x16& p, const bf16x8* kf, const bf16x8* qr) {
; #pragma unroll
;     for (int d0 = D0A; d0 < D0B; ++d0) {
.LBB0_1930:
	s_mov_b64 s[96:97], 0xc00
	ds_read_b128 v[98:101], v107 offset:12288
	ds_read_b128 v[102:105], v108 offset:12288
	ds_read_b128 v[114:117], v109 offset:12288
	ds_read_b128 v[122:125], v110 offset:12288
	v_lshl_add_u32 v96, s64, 14, v106
	ds_read_b64_tr_b16 v[132:133], v96 offset:0
	ds_read_b64_tr_b16 v[134:135], v96 offset:0x800
	ds_read_b64_tr_b16 v[136:137], v96 offset:0x1000
	ds_read_b64_tr_b16 v[138:139], v96 offset:0x1800
	ds_read_b64_tr_b16 v[140:141], v96 offset:0x200
	ds_read_b64_tr_b16 v[142:143], v96 offset:0xa00
	ds_read_b64_tr_b16 v[144:145], v96 offset:0x1200
	ds_read_b64_tr_b16 v[146:147], v96 offset:0x1a00
	ds_read_b64_tr_b16 v[148:149], v96 offset:0x400
	ds_read_b64_tr_b16 v[150:151], v96 offset:0xc00
	ds_read_b64_tr_b16 v[152:153], v96 offset:0x1400
	ds_read_b64_tr_b16 v[154:155], v96 offset:0x1c00
	ds_read_b64_tr_b16 v[156:157], v96 offset:0x600
	ds_read_b64_tr_b16 v[158:159], v96 offset:0xe00
	ds_read_b64_tr_b16 v[162:163], v96 offset:0x1600
	ds_read_b64_tr_b16 v[164:165], v96 offset:0x1e00
	s_setprio 1
	v_exp_f32_e32 v64, v64
	v_exp_f32_e32 v65, v65
	v_exp_f32_e32 v66, v66
	v_exp_f32_e32 v67, v67
	v_exp_f32_e32 v68, v68
	v_exp_f32_e32 v69, v69
	v_add_f32_e32 v97, v65, v64
	v_exp_f32_e32 v70, v70
	v_add_f32_e32 v97, v66, v97
	v_exp_f32_e32 v71, v71
	v_add_f32_e32 v97, v67, v97
	v_exp_f32_e32 v72, v72
	v_add_f32_e32 v97, v68, v97
	v_exp_f32_e32 v73, v73
	v_add_f32_e32 v97, v69, v97
	v_exp_f32_e32 v74, v74
	v_add_f32_e32 v97, v70, v97
	v_exp_f32_e32 v75, v75
	v_add_f32_e32 v97, v71, v97
	v_exp_f32_e32 v76, v76
	v_add_f32_e32 v97, v72, v97
	v_exp_f32_e32 v77, v77
	v_add_f32_e32 v97, v73, v97
	v_exp_f32_e32 v78, v78
	v_add_f32_e32 v97, v74, v97
	v_exp_f32_e32 v79, v79
	v_add_f32_e32 v97, v75, v97
	v_add_f32_e32 v97, v76, v97
	v_add_f32_e32 v97, v77, v97
	v_add_f32_e32 v97, v78, v97
	v_add_f32_e32 v97, v79, v97
	v_add_f32_e32 v97, v97, v120
	v_cvt_pk_bf16_f32 v64, v64, v65
	v_cvt_pk_bf16_f32 v65, v66, v67
	v_cvt_pk_bf16_f32 v66, v68, v69
	v_cvt_pk_bf16_f32 v67, v70, v71
	v_cvt_pk_bf16_f32 v68, v72, v73
	v_cvt_pk_bf16_f32 v69, v74, v75
	v_cvt_pk_bf16_f32 v70, v76, v77
	v_cvt_pk_bf16_f32 v71, v78, v79
	s_waitcnt lgkmcnt(0)
	s_setprio 2
	v_mfma_f32_32x32x16_bf16 v[0:15], v[64:67], v[132:135], v[0:15]
	s_cmp_gt_i32 s55, 61
	s_cselect_b64 s[0:1], -1, 0
	s_cmp_lt_i32 s58, 62
	s_cselect_b64 s[2:3], -1, 0
	s_or_b64 s[0:1], s[0:1], s[2:3]
	s_and_b64 vcc, exec, s[0:1]
	v_mfma_f32_32x32x16_bf16 v[48:63], v[64:67], v[140:143], v[48:63]
	v_mfma_f32_32x32x16_bf16 v[32:47], v[64:67], v[148:151], v[32:47]
	v_mfma_f32_32x32x16_bf16 v[16:31], v[64:67], v[156:159], v[16:31]
	v_mfma_f32_32x32x16_bf16 v[0:15], v[68:71], v[136:139], v[0:15]
	v_mfma_f32_32x32x16_bf16 v[48:63], v[68:71], v[144:147], v[48:63]
	v_mfma_f32_32x32x16_bf16 v[32:47], v[68:71], v[152:155], v[32:47]
	v_mfma_f32_32x32x16_bf16 v[16:31], v[68:71], v[162:165], v[16:31]
	s_waitcnt lgkmcnt(0)
	v_mfma_f32_32x32x16_bf16 v[64:79], v[98:101], v[92:95], 0
	v_mfma_f32_32x32x16_bf16 v[64:79], v[102:105], v[88:91], v[64:79]
	v_mfma_f32_32x32x16_bf16 v[64:79], v[114:117], v[84:87], v[64:79]
	v_mfma_f32_32x32x16_bf16 v[64:79], v[122:125], v[80:83], v[64:79]
	s_setprio 0
	s_cbranch_vccnz .LBB0_1932
	v_sub_u32_e32 v98, 0xf40, v111
	v_lshlrev_b32_e32 v98, 2, v98
	v_add3_u32 v98, s88, v98, v130
	v_add_u32_e32 v114, 0x400, v98
	v_add_u32_e32 v116, 0x408, v98
	v_add_u32_e32 v118, 0x420, v98
	v_add_u32_e32 v120, 0x428, v98
	v_add_u32_e32 v99, 0x440, v98
	v_add_u32_e32 v100, 0x448, v98
	v_add_u32_e32 v102, 0x460, v98
	v_add_u32_e32 v104, 0x468, v98
	ds_read2_b32 v[98:99], v99 offset1:1
	ds_read2_b32 v[100:101], v100 offset1:1
	ds_read2_b32 v[102:103], v102 offset1:1
	ds_read2_b32 v[104:105], v104 offset1:1
	ds_read2_b32 v[114:115], v114 offset1:1
	ds_read2_b32 v[116:117], v116 offset1:1
	ds_read2_b32 v[118:119], v118 offset1:1
	ds_read2_b32 v[120:121], v120 offset1:1
	s_waitcnt lgkmcnt(0)
	v_pk_add_f32 v[78:79], v[78:79], v[104:105]
	v_pk_add_f32 v[76:77], v[76:77], v[102:103]
	v_pk_add_f32 v[74:75], v[74:75], v[100:101]
	v_pk_add_f32 v[72:73], v[72:73], v[98:99]
	v_pk_add_f32 v[70:71], v[70:71], v[120:121]
	v_pk_add_f32 v[68:69], v[68:69], v[118:119]
	v_pk_add_f32 v[66:67], v[66:67], v[116:117]
	v_pk_add_f32 v[64:65], v[64:65], v[114:115]
.LBB0_1932:
	s_movk_i32 s64, 0x70
	ds_read_b128 v[98:101], v107 offset:16384
	ds_read_b128 v[102:105], v108 offset:16384
	ds_read_b128 v[114:117], v109 offset:16384
	ds_read_b128 v[118:121], v110 offset:16384
	ds_read_b64_tr_b16 v[122:123], v96 offset:0x2000
	ds_read_b64_tr_b16 v[124:125], v96 offset:0x2800
	ds_read_b64_tr_b16 v[132:133], v96 offset:0x3000
	ds_read_b64_tr_b16 v[134:135], v96 offset:0x3800
	ds_read_b64_tr_b16 v[136:137], v96 offset:0x2200
	ds_read_b64_tr_b16 v[138:139], v96 offset:0x2a00
	ds_read_b64_tr_b16 v[140:141], v96 offset:0x3200
	ds_read_b64_tr_b16 v[142:143], v96 offset:0x3a00
	ds_read_b64_tr_b16 v[144:145], v96 offset:0x2400
	ds_read_b64_tr_b16 v[146:147], v96 offset:0x2c00
	ds_read_b64_tr_b16 v[148:149], v96 offset:0x3400
	ds_read_b64_tr_b16 v[150:151], v96 offset:0x3c00
	ds_read_b64_tr_b16 v[152:153], v96 offset:0x2600
	ds_read_b64_tr_b16 v[154:155], v96 offset:0x2e00
	ds_read_b64_tr_b16 v[156:157], v96 offset:0x3600
	ds_read_b64_tr_b16 v[158:159], v96 offset:0x3e00
	s_nop 5
	s_setprio 1
	v_exp_f32_e32 v64, v64
	v_exp_f32_e32 v65, v65
	v_exp_f32_e32 v66, v66
	v_exp_f32_e32 v67, v67
	v_exp_f32_e32 v68, v68
	v_exp_f32_e32 v69, v69
	v_add_f32_e32 v96, v65, v64
	v_exp_f32_e32 v70, v70
	v_add_f32_e32 v96, v66, v96
	v_exp_f32_e32 v71, v71
	v_add_f32_e32 v96, v67, v96
	v_exp_f32_e32 v72, v72
	v_add_f32_e32 v96, v68, v96
	v_exp_f32_e32 v73, v73
	v_add_f32_e32 v96, v69, v96
	v_exp_f32_e32 v74, v74
	v_add_f32_e32 v96, v70, v96
	v_exp_f32_e32 v75, v75
	v_add_f32_e32 v96, v71, v96
	v_exp_f32_e32 v76, v76
	v_add_f32_e32 v96, v72, v96
	v_exp_f32_e32 v77, v77
	v_add_f32_e32 v96, v73, v96
	v_exp_f32_e32 v78, v78
	v_add_f32_e32 v96, v74, v96
	v_exp_f32_e32 v79, v79
	v_add_f32_e32 v96, v75, v96
	v_add_f32_e32 v96, v76, v96
	v_add_f32_e32 v96, v77, v96
	v_add_f32_e32 v96, v78, v96
	v_add_f32_e32 v96, v79, v96
	v_add_f32_e32 v96, v97, v96
	v_cvt_pk_bf16_f32 v64, v64, v65
	v_cvt_pk_bf16_f32 v65, v66, v67
	v_cvt_pk_bf16_f32 v66, v68, v69
	v_cvt_pk_bf16_f32 v67, v70, v71
	v_cvt_pk_bf16_f32 v68, v72, v73
	v_cvt_pk_bf16_f32 v69, v74, v75
	v_cvt_pk_bf16_f32 v70, v76, v77
	v_cvt_pk_bf16_f32 v71, v78, v79
	s_waitcnt lgkmcnt(0)
	s_setprio 2
	s_cmp_lt_u32 s33, 0x100
	s_cbranch_scc1 .Lstg_d0_m61_13
	s_waitcnt vmcnt(0)
	s_barrier

; #define LAS __attribute__((address_space(3)))
; DI void expsum(f32x16& p, float& l_reg, bf16x8& pa0, bf16x8& pa1) {
; #pragma unroll
;     for (int r = 0; r < 16; ++r) p[r] = __builtin_amdgcn_exp2f(p[r]);
;     float ps = 0.f;
; #pragma unroll
;     for (int r = 0; r < 16; ++r) ps += p[r];
;     l_reg += ps; asm volatile("" : "+v"(l_reg));
;     ...
;     ATT_PK4(p, 0, pa0); ATT_PK4(p, 8, pa1);
;     ...
; }
; DI int v_rd_base(int lane) { return ((lane & 3) << 3) | (((lane >> 2) & 3) << 6) | (((lane >> 4) & 1) << 5) | (((lane >> 5) & 1) << 8); }
; template <int OFF> DI s16x4 tr_read(int vb) { s16x4 r; asm volatile("ds_read_b64_tr_b16 %0, %1 offset:%2" : "=&v"(r) : "v"(vb), "i"(OFF) : "memory"); return r; }
; template <int H> DI void v_reads(s16x4* vf, int vb) {
;     vf[0] = tr_read<v_rd_off(0, 2 * H, 0)>(vb); vf[1] = tr_read<v_rd_off(0, 2 * H, 1)>(vb); vf[2] = tr_read<v_rd_off(0, 2 * H + 1, 0)>(vb); vf[3] = tr_read<v_rd_off(0, 2 * H + 1, 1)>(vb);
;     vf[4] = tr_read<v_rd_off(1, 2 * H, 0)>(vb); vf[5] = tr_read<v_rd_off(1, 2 * H, 1)>(vb); vf[6] = tr_read<v_rd_off(1, 2 * H + 1, 0)>(vb); vf[7] = tr_read<v_rd_off(1, 2 * H + 1, 1)>(vb);
;     vf[8] = tr_read<v_rd_off(2, 2 * H, 0)>(vb); vf[9] = tr_read<v_rd_off(2, 2 * H, 1)>(vb); vf[10] = tr_read<v_rd_off(2, 2 * H + 1, 0)>(vb); vf[11] = tr_read<v_rd_off(2, 2 * H + 1, 1)>(vb);
;     vf[12] = tr_read<v_rd_off(3, 2 * H, 0)>(vb); vf[13] = tr_read<v_rd_off(3, 2 * H, 1)>(vb); vf[14] = tr_read<v_rd_off(3, 2 * H + 1, 0)>(vb); vf[15] = tr_read<v_rd_off(3, 2 * H + 1, 1)>(vb);
; }
; DI void pv_mma(f32x16* o, const s16x4* vf, bf16x8 pa0, bf16x8 pa1) {
;     ...
; #pragma unroll
;     for (int d0 = 0; d0 < 4; ++d0) {
;         o[d0] = __builtin_amdgcn_mfma_f32_32x32x16_bf16(pa0, ATT_PK(vf[4 * d0], vf[4 * d0 + 1]), o[d0], 0, 0, 0);
;         o[d0] = __builtin_amdgcn_mfma_f32_32x32x16_bf16(pa1, ATT_PK(vf[4 * d0 + 2], vf[4 * d0 + 3]), o[d0], 0, 0, 0); }
;     ...
; }
; template <int DQK, int D0A, int D0B> DI void k_reads(bf16x8* kf, const LAS unsigned char* Ks, int half, int r32, int hi) {
; #pragma unroll
;     for (int d0 = D0A; d0 < D0B; ++d0) kf[d0 - D0A] = *(const LAS bf16x8*)(Ks + half * (32 * DQK * 2) + kswz<DQK>(r32, (d0 * 16 + hi * 8) * 2));
; }
; template <int D0A, int D0B> DI void qk_mma(f32x16& p, const bf16x8* kf, const bf16x8* qr) {
; #pragma unroll
;     for (int d0 = D0A; d0 < D0B; ++d0) {
.LBB0_1936:
	ds_read_b128 v[100:103], v107 offset:20480
	ds_read_b128 v[114:117], v108 offset:20480
	ds_read_b128 v[118:121], v109 offset:20480
	ds_read_b128 v[122:125], v110 offset:20480
	v_add_u32_e32 v98, 0x8000, v106
	ds_read_b64_tr_b16 v[132:133], v98 offset:0
	ds_read_b64_tr_b16 v[134:135], v98 offset:0x800
	ds_read_b64_tr_b16 v[136:137], v98 offset:0x1000
	ds_read_b64_tr_b16 v[138:139], v98 offset:0x1800
	ds_read_b64_tr_b16 v[140:141], v98 offset:0x200
	ds_read_b64_tr_b16 v[142:143], v98 offset:0xa00
	ds_read_b64_tr_b16 v[144:145], v98 offset:0x1200
	ds_read_b64_tr_b16 v[146:147], v98 offset:0x1a00
	ds_read_b64_tr_b16 v[148:149], v98 offset:0x400
	ds_read_b64_tr_b16 v[150:151], v98 offset:0xc00
	ds_read_b64_tr_b16 v[152:153], v98 offset:0x1400
	ds_read_b64_tr_b16 v[154:155], v98 offset:0x1c00
	ds_read_b64_tr_b16 v[156:157], v98 offset:0x600
	ds_read_b64_tr_b16 v[158:159], v98 offset:0xe00
	ds_read_b64_tr_b16 v[162:163], v98 offset:0x1600
	ds_read_b64_tr_b16 v[164:165], v98 offset:0x1e00
	s_setprio 1
	v_exp_f32_e32 v64, v64
	v_exp_f32_e32 v65, v65
	v_exp_f32_e32 v66, v66
	v_exp_f32_e32 v67, v67
	v_exp_f32_e32 v68, v68
	v_exp_f32_e32 v69, v69
	v_add_f32_e32 v99, v65, v64
	v_exp_f32_e32 v70, v70
	v_add_f32_e32 v99, v66, v99
	v_exp_f32_e32 v71, v71
	v_add_f32_e32 v99, v67, v99
	v_exp_f32_e32 v72, v72
	v_add_f32_e32 v99, v68, v99
	v_exp_f32_e32 v73, v73
	v_add_f32_e32 v99, v69, v99
	v_exp_f32_e32 v74, v74
	v_add_f32_e32 v99, v70, v99
	v_exp_f32_e32 v75, v75
	v_add_f32_e32 v99, v71, v99
	v_exp_f32_e32 v76, v76
	v_add_f32_e32 v99, v72, v99
	v_exp_f32_e32 v77, v77
	v_add_f32_e32 v99, v73, v99
	v_exp_f32_e32 v78, v78
	v_add_f32_e32 v99, v74, v99
	v_exp_f32_e32 v79, v79
	v_add_f32_e32 v99, v75, v99
	v_add_f32_e32 v99, v76, v99
	v_add_f32_e32 v99, v77, v99
	v_add_f32_e32 v99, v78, v99
	v_add_f32_e32 v99, v79, v99
	v_add_f32_e32 v96, v99, v96
	v_cvt_pk_bf16_f32 v64, v64, v65
	v_cvt_pk_bf16_f32 v65, v66, v67
	v_cvt_pk_bf16_f32 v66, v68, v69
	v_cvt_pk_bf16_f32 v67, v70, v71
	v_cvt_pk_bf16_f32 v68, v72, v73
	v_cvt_pk_bf16_f32 v69, v74, v75
	v_cvt_pk_bf16_f32 v70, v76, v77
	v_cvt_pk_bf16_f32 v71, v78, v79
	s_waitcnt lgkmcnt(0)
	s_setprio 2
	v_mfma_f32_32x32x16_bf16 v[0:15], v[64:67], v[132:135], v[0:15]
	s_and_b64 vcc, exec, s[2:3]
	v_mfma_f32_32x32x16_bf16 v[48:63], v[64:67], v[140:143], v[48:63]
	v_mfma_f32_32x32x16_bf16 v[32:47], v[64:67], v[148:151], v[32:47]
	v_mfma_f32_32x32x16_bf16 v[16:31], v[64:67], v[156:159], v[16:31]
	v_mfma_f32_32x32x16_bf16 v[0:15], v[68:71], v[136:139], v[0:15]
	v_mfma_f32_32x32x16_bf16 v[48:63], v[68:71], v[144:147], v[48:63]
	v_mfma_f32_32x32x16_bf16 v[32:47], v[68:71], v[152:155], v[32:47]
	v_mfma_f32_32x32x16_bf16 v[16:31], v[68:71], v[162:165], v[16:31]
	s_waitcnt lgkmcnt(0)
	v_mfma_f32_32x32x16_bf16 v[64:79], v[100:103], v[92:95], 0
	v_mfma_f32_32x32x16_bf16 v[64:79], v[114:117], v[88:91], v[64:79]
	v_mfma_f32_32x32x16_bf16 v[64:79], v[118:121], v[84:87], v[64:79]
	v_mfma_f32_32x32x16_bf16 v[64:79], v[122:125], v[80:83], v[64:79]
	s_setprio 0
	s_cbranch_vccnz .LBB0_1938
	v_add3_u32 v97, s88, v97, v130
	v_add_u32_e32 v118, 0x408, v97
	v_add_u32_e32 v120, 0x420, v97
	v_add_u32_e32 v122, 0x428, v97
	v_add_u32_e32 v100, 0x440, v97
	v_add_u32_e32 v102, 0x448, v97
	v_add_u32_e32 v104, 0x460, v97
	v_add_u32_e32 v99, 0x400, v97
	v_add_u32_e32 v97, 0x468, v97
	ds_read2_b32 v[100:101], v100 offset1:1
	ds_read2_b32 v[102:103], v102 offset1:1
	ds_read2_b32 v[104:105], v104 offset1:1
	ds_read2_b32 v[114:115], v97 offset1:1
	ds_read2_b32 v[116:117], v99 offset1:1
	ds_read2_b32 v[118:119], v118 offset1:1
	ds_read2_b32 v[120:121], v120 offset1:1
	ds_read2_b32 v[122:123], v122 offset1:1
	s_waitcnt lgkmcnt(0)
	v_pk_add_f32 v[78:79], v[78:79], v[114:115]
	v_pk_add_f32 v[76:77], v[76:77], v[104:105]
	v_pk_add_f32 v[74:75], v[74:75], v[102:103]
	v_pk_add_f32 v[72:73], v[72:73], v[100:101]
	v_pk_add_f32 v[70:71], v[70:71], v[122:123]
	v_pk_add_f32 v[68:69], v[68:69], v[120:121]
	v_pk_add_f32 v[66:67], v[66:67], v[118:119]
	v_pk_add_f32 v[64:65], v[64:65], v[116:117]
.LBB0_1938:
	ds_read_b128 v[100:103], v107 offset:24576
	ds_read_b128 v[114:117], v108 offset:24576
	ds_read_b128 v[118:121], v109 offset:24576
	ds_read_b128 v[122:125], v110 offset:24576
	ds_read_b64_tr_b16 v[132:133], v98 offset:0x2000
	ds_read_b64_tr_b16 v[134:135], v98 offset:0x2800
	ds_read_b64_tr_b16 v[136:137], v98 offset:0x3000
	ds_read_b64_tr_b16 v[138:139], v98 offset:0x3800
	ds_read_b64_tr_b16 v[140:141], v98 offset:0x2200
	ds_read_b64_tr_b16 v[142:143], v98 offset:0x2a00
	ds_read_b64_tr_b16 v[144:145], v98 offset:0x3200
	ds_read_b64_tr_b16 v[146:147], v98 offset:0x3a00
	ds_read_b64_tr_b16 v[148:149], v98 offset:0x2400
	ds_read_b64_tr_b16 v[150:151], v98 offset:0x2c00
	ds_read_b64_tr_b16 v[152:153], v98 offset:0x3400
	ds_read_b64_tr_b16 v[154:155], v98 offset:0x3c00
	ds_read_b64_tr_b16 v[156:157], v98 offset:0x2600
	ds_read_b64_tr_b16 v[158:159], v98 offset:0x2e00
	ds_read_b64_tr_b16 v[162:163], v98 offset:0x3600
	ds_read_b64_tr_b16 v[164:165], v98 offset:0x3e00
	s_nop 6
	s_setprio 1
	v_exp_f32_e32 v64, v64
	v_exp_f32_e32 v65, v65
	v_exp_f32_e32 v66, v66
	v_exp_f32_e32 v67, v67
	v_exp_f32_e32 v68, v68
	v_exp_f32_e32 v69, v69
	v_add_f32_e32 v97, v65, v64
	v_exp_f32_e32 v70, v70
	v_add_f32_e32 v97, v66, v97
	v_exp_f32_e32 v71, v71
	v_add_f32_e32 v97, v67, v97
	v_exp_f32_e32 v72, v72
	v_add_f32_e32 v97, v68, v97
	v_exp_f32_e32 v73, v73
	v_add_f32_e32 v97, v69, v97
	v_exp_f32_e32 v74, v74
	v_add_f32_e32 v97, v70, v97
	v_exp_f32_e32 v75, v75
	v_add_f32_e32 v97, v71, v97
	v_exp_f32_e32 v76, v76
	v_add_f32_e32 v97, v72, v97
	v_exp_f32_e32 v77, v77
	v_add_f32_e32 v97, v73, v97
	v_exp_f32_e32 v78, v78
	v_add_f32_e32 v97, v74, v97
	v_exp_f32_e32 v79, v79
	v_add_f32_e32 v97, v75, v97
	v_add_f32_e32 v97, v76, v97
	v_add_f32_e32 v97, v77, v97
	v_add_f32_e32 v97, v78, v97
	v_add_f32_e32 v97, v79, v97
	v_add_f32_e32 v96, v96, v97
	v_cvt_pk_bf16_f32 v64, v64, v65
	v_cvt_pk_bf16_f32 v65, v66, v67
	v_cvt_pk_bf16_f32 v66, v68, v69
	v_cvt_pk_bf16_f32 v67, v70, v71
	v_cvt_pk_bf16_f32 v68, v72, v73
	v_cvt_pk_bf16_f32 v69, v74, v75
	v_cvt_pk_bf16_f32 v70, v76, v77
	v_cvt_pk_bf16_f32 v71, v78, v79
	s_waitcnt lgkmcnt(0)
	s_setprio 2
	s_cmp_lt_u32 s33, 0x100
	s_cbranch_scc1 .Lstg_d0_m62_15
	s_waitcnt vmcnt(0)
	s_barrier

; #define LAS __attribute__((address_space(3)))
; DI void expsum(f32x16& p, float& l_reg, bf16x8& pa0, bf16x8& pa1) {
; #pragma unroll
;     for (int r = 0; r < 16; ++r) p[r] = __builtin_amdgcn_exp2f(p[r]);
;     float ps = 0.f;
; #pragma unroll
;     for (int r = 0; r < 16; ++r) ps += p[r];
;     l_reg += ps; asm volatile("" : "+v"(l_reg));
;     ...
;     ATT_PK4(p, 0, pa0); ATT_PK4(p, 8, pa1);
;     ...
; }
; DI int v_rd_base(int lane) { return ((lane & 3) << 3) | (((lane >> 2) & 3) << 6) | (((lane >> 4) & 1) << 5) | (((lane >> 5) & 1) << 8); }
; template <int OFF> DI s16x4 tr_read(int vb) { s16x4 r; asm volatile("ds_read_b64_tr_b16 %0, %1 offset:%2" : "=&v"(r) : "v"(vb), "i"(OFF) : "memory"); return r; }
; template <int H> DI void v_reads(s16x4* vf, int vb) {
;     vf[0] = tr_read<v_rd_off(0, 2 * H, 0)>(vb); vf[1] = tr_read<v_rd_off(0, 2 * H, 1)>(vb); vf[2] = tr_read<v_rd_off(0, 2 * H + 1, 0)>(vb); vf[3] = tr_read<v_rd_off(0, 2 * H + 1, 1)>(vb);
;     vf[4] = tr_read<v_rd_off(1, 2 * H, 0)>(vb); vf[5] = tr_read<v_rd_off(1, 2 * H, 1)>(vb); vf[6] = tr_read<v_rd_off(1, 2 * H + 1, 0)>(vb); vf[7] = tr_read<v_rd_off(1, 2 * H + 1, 1)>(vb);
;     vf[8] = tr_read<v_rd_off(2, 2 * H, 0)>(vb); vf[9] = tr_read<v_rd_off(2, 2 * H, 1)>(vb); vf[10] = tr_read<v_rd_off(2, 2 * H + 1, 0)>(vb); vf[11] = tr_read<v_rd_off(2, 2 * H + 1, 1)>(vb);
;     vf[12] = tr_read<v_rd_off(3, 2 * H, 0)>(vb); vf[13] = tr_read<v_rd_off(3, 2 * H, 1)>(vb); vf[14] = tr_read<v_rd_off(3, 2 * H + 1, 0)>(vb); vf[15] = tr_read<v_rd_off(3, 2 * H + 1, 1)>(vb);
; }
; DI void pv_mma(f32x16* o, const s16x4* vf, bf16x8 pa0, bf16x8 pa1) {
;     ...
; #pragma unroll
;     for (int d0 = 0; d0 < 4; ++d0) {
;         o[d0] = __builtin_amdgcn_mfma_f32_32x32x16_bf16(pa0, ATT_PK(vf[4 * d0], vf[4 * d0 + 1]), o[d0], 0, 0, 0);
;         o[d0] = __builtin_amdgcn_mfma_f32_32x32x16_bf16(pa1, ATT_PK(vf[4 * d0 + 2], vf[4 * d0 + 3]), o[d0], 0, 0, 0); }
;     ...
; }
; template <int DQK, int D0A, int D0B> DI void k_reads(bf16x8* kf, const LAS unsigned char* Ks, int half, int r32, int hi) {
; #pragma unroll
;     for (int d0 = D0A; d0 < D0B; ++d0) kf[d0 - D0A] = *(const LAS bf16x8*)(Ks + half * (32 * DQK * 2) + kswz<DQK>(r32, (d0 * 16 + hi * 8) * 2));
; }
; template <int D0A, int D0B> DI void qk_mma(f32x16& p, const bf16x8* kf, const bf16x8* qr) {
; #pragma unroll
;     for (int d0 = D0A; d0 < D0B; ++d0) {
.LBB0_1942:
	ds_read_b128 v[98:101], v107 offset:28672
	ds_read_b128 v[102:105], v108 offset:28672
	ds_read_b128 v[112:115], v109 offset:28672
	ds_read_b128 v[108:111], v110 offset:28672
	ds_read_b64_tr_b16 v[116:117], v106 offset:0
	ds_read_b64_tr_b16 v[118:119], v106 offset:0x800
	ds_read_b64_tr_b16 v[120:121], v106 offset:0x1000
	ds_read_b64_tr_b16 v[122:123], v106 offset:0x1800
	ds_read_b64_tr_b16 v[124:125], v106 offset:0x200
	ds_read_b64_tr_b16 v[126:127], v106 offset:0xa00
	ds_read_b64_tr_b16 v[132:133], v106 offset:0x1200
	ds_read_b64_tr_b16 v[134:135], v106 offset:0x1a00
	ds_read_b64_tr_b16 v[136:137], v106 offset:0x400
	ds_read_b64_tr_b16 v[138:139], v106 offset:0xc00
	ds_read_b64_tr_b16 v[140:141], v106 offset:0x1400
	ds_read_b64_tr_b16 v[142:143], v106 offset:0x1c00
	ds_read_b64_tr_b16 v[144:145], v106 offset:0x600
	ds_read_b64_tr_b16 v[146:147], v106 offset:0xe00
	ds_read_b64_tr_b16 v[148:149], v106 offset:0x1600
	ds_read_b64_tr_b16 v[150:151], v106 offset:0x1e00
	s_setprio 1
	v_exp_f32_e32 v64, v64
	v_exp_f32_e32 v65, v65
	v_exp_f32_e32 v66, v66
	v_exp_f32_e32 v67, v67
	v_exp_f32_e32 v68, v68
	v_exp_f32_e32 v69, v69
	v_add_f32_e32 v107, v65, v64
	v_exp_f32_e32 v70, v70
	v_add_f32_e32 v107, v66, v107
	v_exp_f32_e32 v71, v71
	v_add_f32_e32 v107, v67, v107
	v_exp_f32_e32 v72, v72
	v_add_f32_e32 v107, v68, v107
	v_exp_f32_e32 v73, v73
	v_add_f32_e32 v107, v69, v107
	v_exp_f32_e32 v74, v74
	v_add_f32_e32 v107, v70, v107
	v_exp_f32_e32 v75, v75
	v_add_f32_e32 v107, v71, v107
	v_exp_f32_e32 v76, v76
	v_add_f32_e32 v107, v72, v107
	v_exp_f32_e32 v77, v77
	v_add_f32_e32 v107, v73, v107
	v_exp_f32_e32 v78, v78
	v_add_f32_e32 v107, v74, v107
	v_exp_f32_e32 v79, v79
	v_add_f32_e32 v107, v75, v107
	v_add_f32_e32 v107, v76, v107
	v_add_f32_e32 v107, v77, v107
	v_add_f32_e32 v107, v78, v107
	v_add_f32_e32 v107, v79, v107
	v_add_f32_e32 v96, v107, v96
	v_cvt_pk_bf16_f32 v64, v64, v65
	v_cvt_pk_bf16_f32 v65, v66, v67
	v_cvt_pk_bf16_f32 v66, v68, v69
	v_cvt_pk_bf16_f32 v67, v70, v71
	v_cvt_pk_bf16_f32 v68, v72, v73
	v_cvt_pk_bf16_f32 v69, v74, v75
	v_cvt_pk_bf16_f32 v70, v76, v77
	v_cvt_pk_bf16_f32 v71, v78, v79
	s_waitcnt lgkmcnt(0)
	s_setprio 2
	v_mfma_f32_32x32x16_bf16 v[0:15], v[64:67], v[116:119], v[0:15]
	s_and_b64 vcc, exec, s[2:3]
	v_mfma_f32_32x32x16_bf16 v[48:63], v[64:67], v[124:127], v[48:63]
	v_mfma_f32_32x32x16_bf16 v[32:47], v[64:67], v[136:139], v[32:47]
	v_mfma_f32_32x32x16_bf16 v[16:31], v[64:67], v[144:147], v[16:31]
	v_mfma_f32_32x32x16_bf16 v[0:15], v[68:71], v[120:123], v[0:15]
	v_mfma_f32_32x32x16_bf16 v[48:63], v[68:71], v[132:135], v[48:63]
	v_mfma_f32_32x32x16_bf16 v[32:47], v[68:71], v[140:143], v[32:47]
	v_mfma_f32_32x32x16_bf16 v[16:31], v[68:71], v[148:151], v[16:31]
	s_waitcnt lgkmcnt(0)
	v_mfma_f32_32x32x16_bf16 v[64:79], v[98:101], v[92:95], 0
	v_mfma_f32_32x32x16_bf16 v[64:79], v[102:105], v[88:91], v[64:79]
	v_mfma_f32_32x32x16_bf16 v[64:79], v[112:115], v[84:87], v[64:79]
	v_mfma_f32_32x32x16_bf16 v[64:79], v[108:111], v[80:83], v[64:79]
	s_setprio 0
	s_cbranch_vccnz .LBB0_1944
	v_add3_u32 v80, s88, v97, v130
	v_add_u32_e32 v88, 0x400, v80
	v_add_u32_e32 v90, 0x408, v80
	v_add_u32_e32 v92, 0x420, v80
	v_add_u32_e32 v94, 0x428, v80
	v_add_u32_e32 v81, 0x440, v80
	v_add_u32_e32 v82, 0x448, v80
	v_add_u32_e32 v84, 0x460, v80
	v_add_u32_e32 v86, 0x468, v80
	ds_read2_b32 v[80:81], v81 offset1:1
	ds_read2_b32 v[82:83], v82 offset1:1
	ds_read2_b32 v[84:85], v84 offset1:1
	ds_read2_b32 v[86:87], v86 offset1:1
	ds_read2_b32 v[88:89], v88 offset1:1
	ds_read2_b32 v[90:91], v90 offset1:1
	ds_read2_b32 v[92:93], v92 offset1:1
	ds_read2_b32 v[94:95], v94 offset1:1
	s_waitcnt lgkmcnt(0)
	v_pk_add_f32 v[78:79], v[78:79], v[86:87]
	v_pk_add_f32 v[76:77], v[76:77], v[84:85]
	v_pk_add_f32 v[74:75], v[74:75], v[82:83]
	v_pk_add_f32 v[72:73], v[72:73], v[80:81]
	v_pk_add_f32 v[70:71], v[70:71], v[94:95]
	v_pk_add_f32 v[68:69], v[68:69], v[92:93]
	v_pk_add_f32 v[66:67], v[66:67], v[90:91]
	v_pk_add_f32 v[64:65], v[64:65], v[88:89]
.LBB0_1944:
	s_lshl_b32 s0, s54, 2
	s_add_i32 s0, s0, 0
	s_add_i32 s0, s0, 0x24000
	ds_read_b64_tr_b16 v[80:81], v106 offset:0x2000
	ds_read_b64_tr_b16 v[82:83], v106 offset:0x2800
	ds_read_b64_tr_b16 v[84:85], v106 offset:0x3000
	ds_read_b64_tr_b16 v[86:87], v106 offset:0x3800
	ds_read_b64_tr_b16 v[88:89], v106 offset:0x2200
	ds_read_b64_tr_b16 v[90:91], v106 offset:0x2a00
	ds_read_b64_tr_b16 v[92:93], v106 offset:0x3200
	ds_read_b64_tr_b16 v[94:95], v106 offset:0x3a00
	ds_read_b64_tr_b16 v[98:99], v106 offset:0x2400
	ds_read_b64_tr_b16 v[100:101], v106 offset:0x2c00
	ds_read_b64_tr_b16 v[102:103], v106 offset:0x3400
	ds_read_b64_tr_b16 v[104:105], v106 offset:0x3c00
	ds_read_b64_tr_b16 v[108:109], v106 offset:0x2600
	ds_read_b64_tr_b16 v[110:111], v106 offset:0x2e00
	ds_read_b64_tr_b16 v[112:113], v106 offset:0x3600
	ds_read_b64_tr_b16 v[114:115], v106 offset:0x3e00
	s_nop 7
	s_setprio 1
	v_exp_f32_e32 v97, v64
	v_exp_f32_e32 v65, v65
	v_exp_f32_e32 v106, v66
	v_exp_f32_e32 v67, v67
	v_exp_f32_e32 v68, v68
	v_exp_f32_e32 v69, v69
	v_add_f32_e32 v64, v65, v97
	v_exp_f32_e32 v70, v70
	v_add_f32_e32 v64, v106, v64
	v_exp_f32_e32 v71, v71
	v_add_f32_e32 v64, v67, v64
	v_exp_f32_e32 v72, v72
	v_add_f32_e32 v64, v68, v64
	v_exp_f32_e32 v73, v73
	v_add_f32_e32 v64, v69, v64
	v_exp_f32_e32 v74, v74
	v_add_f32_e32 v64, v70, v64
	v_exp_f32_e32 v75, v75
	v_add_f32_e32 v64, v71, v64
	v_exp_f32_e32 v76, v76
	v_add_f32_e32 v64, v72, v64
	v_exp_f32_e32 v77, v77
	v_add_f32_e32 v64, v73, v64
	v_exp_f32_e32 v78, v78
	v_add_f32_e32 v64, v74, v64
	v_exp_f32_e32 v79, v79
	v_add_f32_e32 v64, v75, v64
	v_add_f32_e32 v64, v76, v64
	v_add_f32_e32 v64, v77, v64
	v_add_f32_e32 v64, v78, v64
	v_add_f32_e32 v64, v79, v64
	v_add_f32_e32 v64, v96, v64
	v_cvt_pk_bf16_f32 v66, v97, v65
	v_cvt_pk_bf16_f32 v67, v106, v67
	v_cvt_pk_bf16_f32 v68, v68, v69
	v_cvt_pk_bf16_f32 v69, v70, v71
	v_cvt_pk_bf16_f32 v70, v72, v73
	v_cvt_pk_bf16_f32 v71, v74, v75
	v_cvt_pk_bf16_f32 v72, v76, v77
	v_cvt_pk_bf16_f32 v73, v78, v79
	s_waitcnt lgkmcnt(0)
; template <int TAG = 0> DI int fresh_tid(int wv) { int l; asm volatile("v_mbcnt_lo_u32_b32 %0, -1, 0\n\tv_mbcnt_hi_u32_b32 %0, -1, %0 ; site %1" : "=v"(l) : "n"(TAG)); return wv * 64 + l; }
; DI unsigned short f2bf(float x) { unsigned u = __float_as_uint(x); u += 0x7fffu + ((u >> 16) & 1u); return (unsigned short)(u >> 16); }
; DI int crow(int r, int hi) { return (r & 3) + 8 * (r >> 2) + 4 * hi; }
; DI float swap_sum(float v) { auto rr = __builtin_amdgcn_permlane32_swap(__float_as_uint(v), __float_as_uint(v), false, false); return __uint_as_float(rr[0]) + __uint_as_float(rr[1]); }
; template <int DQK, int MODE, int LDQ, int LDK, int LDV> ...
;     ...
;     l_reg = swap_sum(l_reg);
;     { const int lane2 = fresh_tid<110 + MODE>(wv) & 63, r32 = lane2 & 31, hi = lane2 >> 5;
;     if (hi == 0) li_l[r32] = l_reg;
;     asm volatile("s_waitcnt lgkmcnt(0)" ::: "memory");
;     float s0v[MODE == 2 ? 16 : 1][4];
;     if constexpr (MODE == 2) {
; #pragma unroll
;         for (int r = 0; r < 16; ++r)
; #pragma unroll
;             for (int d0 = 0; d0 < 4; ++d0) s0v[r][d0] = S0[(size_t)(wid * 32 + crow(r, hi)) * 512 + d0 * 32 + r32];
;     }
; #pragma unroll
;     for (int r = 0; r < 16; ++r) { const int orow = wid * 32 + crow(r, hi); const float rl = __builtin_amdgcn_rcpf(li_l[crow(r, hi)]);
;         if constexpr (MODE == 0) {
; #pragma unroll
;             for (int d0 = 0; d0 < 4; ++d0) AOb[(size_t)orow * 1024 + d0 * 32 + r32] = f2bf(o[d0][r] * rl);
;         } else if constexpr (MODE == 1) {
; #pragma unroll
;             for (int d0 = 0; d0 < 4; ++d0) S0[(size_t)orow * 512 + d0 * 32 + r32] = o[d0][r] * rl;
	s_setprio 2
	v_mfma_f32_32x32x16_bf16 v[0:15], v[66:69], v[80:83], v[0:15]
	v_mfma_f32_32x32x16_bf16 v[48:63], v[66:69], v[88:91], v[48:63]
	v_mfma_f32_32x32x16_bf16 v[32:47], v[66:69], v[98:101], v[32:47]
	v_mfma_f32_32x32x16_bf16 v[16:31], v[66:69], v[108:111], v[16:31]
	v_mfma_f32_32x32x16_bf16 v[0:15], v[70:73], v[84:87], v[0:15]
	v_mfma_f32_32x32x16_bf16 v[48:63], v[70:73], v[92:95], v[48:63]
	v_mfma_f32_32x32x16_bf16 v[32:47], v[70:73], v[102:105], v[32:47]
	v_mfma_f32_32x32x16_bf16 v[16:31], v[70:73], v[112:115], v[16:31]
	s_setprio 0
	v_mbcnt_lo_u32_b32 v66, -1, 0
	v_mbcnt_hi_u32_b32 v66, -1, v66
	v_mov_b32_e32 v67, v64
	v_and_b32_e32 v65, 31, v66
	v_bfe_u32 v66, v66, 5, 1
	v_permlane32_swap_b32_e32 v64, v67
	v_cmp_eq_u32_e32 vcc, 0, v66
	s_and_saveexec_b64 s[2:3], vcc
	v_lshl_add_u32 v68, v65, 2, s0
	v_add_f32_e32 v64, v64, v67
	ds_write_b32 v68, v64
	s_or_b64 exec, exec, s[2:3]
	s_waitcnt lgkmcnt(0)
	v_lshl_add_u32 v68, v66, 4, s0
	ds_read_b128 v[70:73], v68
	ds_read_b128 v[74:77], v68 offset:32
	s_lshl_b64 s[58:59], s[40:41], 11
	v_readlane_b32 s1, v255, 2
	s_add_u32 s1, s1, s58
	v_readlane_b32 s2, v255, 0
	s_addc_u32 s2, s2, s59
	s_lshl_b32 s3, s87, 2
	s_waitcnt lgkmcnt(0)
	v_rcp_f32_e32 v69, v70
	s_add_u32 s54, s1, s3
	v_lshl_or_b32 v66, v66, 2, s94
	s_addc_u32 s55, s2, 0
	v_lshlrev_b32_e32 v130, 2, v65
	v_ashrrev_i32_e32 v67, 31, v66
	v_lshl_add_u64 v[64:65], s[54:55], 0, v[130:131]
	v_lshlrev_b64 v[78:79], 11, v[66:67]
	v_lshl_add_u64 v[78:79], v[64:65], 0, v[78:79]
	v_mul_f32_e32 v0, v0, v69
	global_store_dword v[78:79], v0, off
	v_mul_f32_e32 v0, v48, v69
	global_store_dword v[78:79], v0, off offset:128
	v_mul_f32_e32 v0, v32, v69
	global_store_dword v[78:79], v0, off offset:256
	v_mul_f32_e32 v0, v16, v69
	global_store_dword v[78:79], v0, off offset:384
	v_rcp_f32_e32 v0, v71
	v_or_b32_e32 v70, 1, v66
	v_ashrrev_i32_e32 v71, 31, v70
	v_lshlrev_b64 v[70:71], 11, v[70:71]
	v_lshl_add_u64 v[70:71], v[64:65], 0, v[70:71]
	v_mul_f32_e32 v1, v1, v0
	global_store_dword v[70:71], v1, off
	v_mul_f32_e32 v1, v49, v0
	global_store_dword v[70:71], v1, off offset:128
	v_mul_f32_e32 v1, v33, v0
	v_mul_f32_e32 v0, v17, v0
	v_rcp_f32_e32 v16, v72
	global_store_dword v[70:71], v0, off offset:384
	v_or_b32_e32 v0, 2, v66
	global_store_dword v[70:71], v1, off offset:256
	v_ashrrev_i32_e32 v1, 31, v0
	v_lshlrev_b64 v[0:1], 11, v[0:1]
	v_lshl_add_u64 v[0:1], v[64:65], 0, v[0:1]
	v_mul_f32_e32 v2, v2, v16
	global_store_dword v[0:1], v2, off
	v_mul_f32_e32 v2, v50, v16
	global_store_dword v[0:1], v2, off offset:128
	v_mul_f32_e32 v2, v34, v16
	global_store_dword v[0:1], v2, off offset:256
	v_mul_f32_e32 v2, v18, v16
	global_store_dword v[0:1], v2, off offset:384
	v_rcp_f32_e32 v2, v73
	v_or_b32_e32 v0, 3, v66
	v_ashrrev_i32_e32 v1, 31, v0
	v_lshlrev_b64 v[0:1], 11, v[0:1]
	v_lshl_add_u64 v[0:1], v[64:65], 0, v[0:1]
	v_mul_f32_e32 v3, v3, v2
	global_store_dword v[0:1], v3, off
	v_mul_f32_e32 v3, v51, v2
	global_store_dword v[0:1], v3, off offset:128
	v_mul_f32_e32 v3, v35, v2
	v_mul_f32_e32 v2, v19, v2
	global_store_dword v[0:1], v2, off offset:384
	v_rcp_f32_e32 v2, v74
	global_store_dword v[0:1], v3, off offset:256
	v_or_b32_e32 v0, 8, v66
	v_ashrrev_i32_e32 v1, 31, v0
	v_lshlrev_b64 v[0:1], 11, v[0:1]
	v_lshl_add_u64 v[0:1], v[64:65], 0, v[0:1]
	v_mul_f32_e32 v3, v4, v2
	global_store_dword v[0:1], v3, off
	v_mul_f32_e32 v3, v52, v2
	global_store_dword v[0:1], v3, off offset:128
	v_mul_f32_e32 v3, v36, v2
	v_mul_f32_e32 v2, v20, v2
	global_store_dword v[0:1], v2, off offset:384
	v_rcp_f32_e32 v2, v75
	global_store_dword v[0:1], v3, off offset:256
	v_or_b32_e32 v0, 9, v66
	v_ashrrev_i32_e32 v1, 31, v0
	v_lshlrev_b64 v[0:1], 11, v[0:1]
	v_lshl_add_u64 v[0:1], v[64:65], 0, v[0:1]
	v_mul_f32_e32 v3, v5, v2
	global_store_dword v[0:1], v3, off
	v_mul_f32_e32 v3, v53, v2
	global_store_dword v[0:1], v3, off offset:128
	v_mul_f32_e32 v3, v37, v2
	v_mul_f32_e32 v2, v21, v2
	global_store_dword v[0:1], v2, off offset:384
	v_rcp_f32_e32 v2, v76
	global_store_dword v[0:1], v3, off offset:256
	v_or_b32_e32 v0, 10, v66
	v_ashrrev_i32_e32 v1, 31, v0
	v_lshlrev_b64 v[0:1], 11, v[0:1]
	v_lshl_add_u64 v[0:1], v[64:65], 0, v[0:1]
	v_mul_f32_e32 v3, v6, v2
	global_store_dword v[0:1], v3, off
	v_mul_f32_e32 v3, v54, v2
	global_store_dword v[0:1], v3, off offset:128
	v_mul_f32_e32 v3, v38, v2
	v_mul_f32_e32 v2, v22, v2
	v_rcp_f32_e32 v6, v77
	global_store_dword v[0:1], v3, off offset:256
	global_store_dword v[0:1], v2, off offset:384
	v_or_b32_e32 v0, 11, v66
	v_ashrrev_i32_e32 v1, 31, v0
	v_lshlrev_b64 v[0:1], 11, v[0:1]
	v_lshl_add_u64 v[4:5], v[64:65], 0, v[0:1]
	v_mul_f32_e32 v0, v7, v6
	global_store_dword v[4:5], v0, off
	v_mul_f32_e32 v0, v55, v6
	global_store_dword v[4:5], v0, off offset:128
	v_mul_f32_e32 v0, v39, v6
	global_store_dword v[4:5], v0, off offset:256
	ds_read_b128 v[0:3], v68 offset:64
	v_mul_f32_e32 v6, v23, v6
	global_store_dword v[4:5], v6, off offset:384
	ds_read_b128 v[4:7], v68 offset:96
	v_or_b32_e32 v16, 16, v66
	s_waitcnt lgkmcnt(0)
; DI unsigned short f2bf(float x) { unsigned u = __float_as_uint(x); u += 0x7fffu + ((u >> 16) & 1u); return (unsigned short)(u >> 16); }
; DI int crow(int r, int hi) { return (r & 3) + 8 * (r >> 2) + 4 * hi; }
; template <int DQK, int MODE, int LDQ, int LDK, int LDV> ...
;     ...
;     for (int r = 0; r < 16; ++r) { const int orow = wid * 32 + crow(r, hi); const float rl = __builtin_amdgcn_rcpf(li_l[crow(r, hi)]);
;         if constexpr (MODE == 0) {
; #pragma unroll
;             for (int d0 = 0; d0 < 4; ++d0) AOb[(size_t)orow * 1024 + d0 * 32 + r32] = f2bf(o[d0][r] * rl);
;         } else if constexpr (MODE == 1) {
; #pragma unroll
;             for (int d0 = 0; d0 < 4; ++d0) S0[(size_t)orow * 512 + d0 * 32 + r32] = o[d0][r] * rl;
	v_rcp_f32_e32 v0, v0
	v_ashrrev_i32_e32 v17, 31, v16
	v_lshlrev_b64 v[16:17], 11, v[16:17]
	v_lshl_add_u64 v[16:17], v[64:65], 0, v[16:17]
	v_mul_f32_e32 v8, v8, v0
	global_store_dword v[16:17], v8, off
	v_mul_f32_e32 v8, v56, v0
	global_store_dword v[16:17], v8, off offset:128
	v_mul_f32_e32 v8, v40, v0
	global_store_dword v[16:17], v8, off offset:256
	v_mul_f32_e32 v0, v24, v0
	v_rcp_f32_e32 v8, v1
	global_store_dword v[16:17], v0, off offset:384
	v_or_b32_e32 v0, 17, v66
	v_ashrrev_i32_e32 v1, 31, v0
	v_lshlrev_b64 v[0:1], 11, v[0:1]
	v_lshl_add_u64 v[0:1], v[64:65], 0, v[0:1]
	v_mul_f32_e32 v9, v9, v8
	global_store_dword v[0:1], v9, off
	v_mul_f32_e32 v9, v57, v8
	global_store_dword v[0:1], v9, off offset:128
	v_mul_f32_e32 v9, v41, v8
	v_mul_f32_e32 v8, v25, v8
	v_rcp_f32_e32 v2, v2
	global_store_dword v[0:1], v9, off offset:256
	global_store_dword v[0:1], v8, off offset:384
	v_or_b32_e32 v0, 18, v66
	v_ashrrev_i32_e32 v1, 31, v0
	v_lshlrev_b64 v[0:1], 11, v[0:1]
	v_lshl_add_u64 v[0:1], v[64:65], 0, v[0:1]
	v_mul_f32_e32 v8, v10, v2
	global_store_dword v[0:1], v8, off
	v_mul_f32_e32 v8, v58, v2
	global_store_dword v[0:1], v8, off offset:128
	v_mul_f32_e32 v8, v42, v2
	v_mul_f32_e32 v2, v26, v2
	global_store_dword v[0:1], v2, off offset:384
	v_rcp_f32_e32 v2, v3
	global_store_dword v[0:1], v8, off offset:256
	v_or_b32_e32 v0, 19, v66
	v_ashrrev_i32_e32 v1, 31, v0
	v_lshlrev_b64 v[0:1], 11, v[0:1]
	v_lshl_add_u64 v[0:1], v[64:65], 0, v[0:1]
	v_mul_f32_e32 v3, v11, v2
	global_store_dword v[0:1], v3, off
	v_mul_f32_e32 v3, v59, v2
	global_store_dword v[0:1], v3, off offset:128
	v_mul_f32_e32 v3, v43, v2
	v_mul_f32_e32 v2, v27, v2
	global_store_dword v[0:1], v2, off offset:384
	v_rcp_f32_e32 v2, v4
	global_store_dword v[0:1], v3, off offset:256
	v_or_b32_e32 v0, 24, v66
	v_ashrrev_i32_e32 v1, 31, v0
	v_lshlrev_b64 v[0:1], 11, v[0:1]
	v_lshl_add_u64 v[0:1], v[64:65], 0, v[0:1]
	v_mul_f32_e32 v3, v12, v2
	global_store_dword v[0:1], v3, off
	v_mul_f32_e32 v3, v60, v2
	global_store_dword v[0:1], v3, off offset:128
	v_mul_f32_e32 v3, v44, v2
	v_mul_f32_e32 v2, v28, v2
	global_store_dword v[0:1], v2, off offset:384
	v_rcp_f32_e32 v2, v5
	global_store_dword v[0:1], v3, off offset:256
	v_or_b32_e32 v0, 25, v66
	v_ashrrev_i32_e32 v1, 31, v0
	v_lshlrev_b64 v[0:1], 11, v[0:1]
	v_lshl_add_u64 v[0:1], v[64:65], 0, v[0:1]
	v_mul_f32_e32 v3, v13, v2
	global_store_dword v[0:1], v3, off
	v_mul_f32_e32 v3, v61, v2
	global_store_dword v[0:1], v3, off offset:128
	v_mul_f32_e32 v3, v45, v2
	v_mul_f32_e32 v2, v29, v2
	global_store_dword v[0:1], v2, off offset:384
	v_rcp_f32_e32 v2, v6
	global_store_dword v[0:1], v3, off offset:256
	v_or_b32_e32 v0, 26, v66
	v_ashrrev_i32_e32 v1, 31, v0
	v_lshlrev_b64 v[0:1], 11, v[0:1]
	v_lshl_add_u64 v[0:1], v[64:65], 0, v[0:1]
	v_mul_f32_e32 v3, v14, v2
	global_store_dword v[0:1], v3, off
	v_mul_f32_e32 v3, v62, v2
	global_store_dword v[0:1], v3, off offset:128
	v_mul_f32_e32 v3, v46, v2
	v_mul_f32_e32 v2, v30, v2
	global_store_dword v[0:1], v2, off offset:384
	v_rcp_f32_e32 v2, v7
	global_store_dword v[0:1], v3, off offset:256
	v_or_b32_e32 v0, 27, v66
	v_ashrrev_i32_e32 v1, 31, v0
	v_lshlrev_b64 v[0:1], 11, v[0:1]
	v_lshl_add_u64 v[0:1], v[64:65], 0, v[0:1]
	v_mul_f32_e32 v3, v15, v2
	global_store_dword v[0:1], v3, off
	v_mul_f32_e32 v3, v63, v2
	global_store_dword v[0:1], v3, off offset:128
	v_mul_f32_e32 v3, v47, v2
	v_mul_f32_e32 v2, v31, v2
	global_store_dword v[0:1], v3, off offset:256
	global_store_dword v[0:1], v2, off offset:384
	s_waitcnt vmcnt(0)
	s_barrier
; DI float bf2f(unsigned short h) { return __uint_as_float((unsigned)h << 16); }
; template <int DQK, int MODE, int LDQ, int LDK, int LDV> ...
;     ...
;     int kgo[NKP], vgo[2];
; #pragma unroll
;     for (int i = 0; i < NKP; ++i) { const int L = (wid + 8 * i) * 64 + lane, row = L / CPR, slot = L % CPR, cc = (slot & ~7) | ((slot & 7) ^ ((row >> 1) & 7)); kgo[i] = row * LDK + cc * 8; }
; #pragma unroll
;     for (int i = 0; i < 2; ++i) { const int L = (2 * wid + i) * 64 + lane, st = L >> 5, w5 = L & 31, kk = (st >> 2) * 8 + (w5 >> 2), c = (st & 3) * 32 + (w5 & 3) * 8;
;         const int k = (kk & ~0xC) | ((kk & 4) << 1) | ((kk & 8) >> 1); vgo[i] = k * LDV + c; }
;     ...
;     ATT_DMA_K(0); ATT_DMA_K(1); ATT_DMA_V(0, 0); ATT_DMA_K(2); ATT_DMA_V(1, 1);
;     bf16x8 qr[ND0];
;     { const bf16_t* Qw = Qb + (size_t)(wid * 32 + r32) * LDQ + hi * 8;
; #pragma unroll
;       for (int d0 = 0; d0 < ND0; ++d0) qr[d0] = *(const bf16x8*)(Qw + d0 * 16);
;       if constexpr (MODE == 0) {
;           float ss = 0.f;
; #pragma unroll
;           for (int d0 = 0; d0 < ND0; ++d0)
; #pragma unroll
;               for (int j = 0; j < 8; ++j) { const float f = bf2f((unsigned short)qr[d0][j]); ss += f * f; }
;           ss = swap_sum(ss);
;           const float rstd = rsqrtf(ss * (1.f / DQK) + EPS) * C;
; #pragma unroll
;           for (int d0 = 0; d0 < ND0; ++d0) { const float* g = gq + d0 * 16 + hi * 8;
;               { float f[8]; _Pragma("unroll") for (int j = 0; j < 8; ++j) f[j] = bf2f((unsigned short)qr[d0][j]) * rstd * g[j];
;                 u32x4 w = {cvtpk(f[0], f[1]), cvtpk(f[2], f[3]), cvtpk(f[4], f[5]), cvtpk(f[6], f[7])}; qr[d0] = __builtin_bit_cast(bf16x8, w); asm volatile("" ::: "memory"); } }
;       } }
;     const int qlo = q0 + wid * 32, qpos = qlo + r32;
;     const int tL = MODE == 0 ? 0 : (qlo >= 191 ? (qlo - 127) >> 6 : 0), tR = MODE == 0 ? NT : min(NT, (qlo + 222) >> 6);
;     float fL = 1.f, fR = 1.f; if constexpr (MODE != 0) { fL = __builtin_amdgcn_exp2f(bt[0]); fR = __builtin_amdgcn_exp2f(-bt[448]); }
;     ...
;     ATT_TOP(NKP + 2);
;     { bf16x8 kf[NDA]; k_reads<DQK, 0, NDA>(kf, lds, 0, r32, hi); ATT_LGKM0(); qk_mma<0, NDA>(pA, kf, qr);
;       if constexpr (ND0 > NDA) { bf16x8 kg[ND0 - NDA]; k_reads<DQK, NDA, ND0>(kg, lds, 0, r32, hi); ATT_LGKM0(); qk_mma<NDA, ND0>(pA, kg, qr); }
;       ATT_BIAS(pA, 0, 0); }
	v_mbcnt_lo_u32_b32 v7, -1, 0
	v_mbcnt_hi_u32_b32 v7, -1, v7
	s_mov_b64 s[4:5], 0x880
	v_add_u32_e32 v0, s33, v7
	v_bfe_u32 v4, v0, 2, 2
	v_readfirstlane_b32 s0, v0
	s_ashr_i32 s2, s0, 31
	s_ashr_i32 s1, s0, 6
	v_mov_b32_e32 v1, s0
	v_bfi_b32 v1, s63, v1, v7
	s_lshr_b32 s2, s2, 29
	v_add_u32_e32 v3, s2, v1
	s_lshl_b32 s2, s1, 7
	v_ashrrev_i32_e32 v9, 3, v3
	v_and_b32_e32 v3, 0x1ffffff8, v3
	s_ashr_i32 s3, s2, 4
	v_lshrrev_b32_e32 v0, 2, v0
	v_sub_u32_e32 v1, v1, v3
	v_lshrrev_b32_e32 v3, 1, v9
	v_lshlrev_b32_e32 v18, 3, v7
	s_and_b32 s2, s3, -16
	v_and_b32_e32 v6, 4, v0
	s_lshr_b32 s3, s3, 0
	v_bitop3_b32 v1, v3, v1, 7 bitop3:0x6c
	v_and_b32_e32 v3, 32, v7
	v_and_b32_e32 v5, 24, v18
	s_and_b32 s3, s3, 8
	v_or3_b32 v0, v6, v4, s2
	v_or_b32_e32 v10, v3, v5
	v_or_b32_e32 v0, s3, v0
	v_lshl_or_b32 v96, v0, 11, v10
	v_lshlrev_b32_e32 v0, 11, v9
	v_lshl_add_u32 v0, v1, 3, v0
	v_ashrrev_i32_e32 v1, 31, v0
	v_lshlrev_b64 v[10:11], 1, v[0:1]
	v_lshl_add_u64 v[12:13], s[46:47], 0, v[10:11]
	v_lshl_add_u64 v[12:13], v[12:13], 0, s[4:5]
	s_lshl_b32 s4, s1, 10
	s_add_i32 s94, s4, 0
	s_mov_b32 m0, s94
	v_lshl_add_u64 v[10:11], s[48:49], 0, v[10:11]
	s_mov_b64 s[4:5], 0x40080
	global_load_lds_dwordx4 v[12:13], off
	v_lshl_add_u64 v[12:13], v[10:11], 0, s[4:5]
	s_add_i32 m0, s94, 0x2000
	s_lshl_b32 s4, s1, 11
	v_ashrrev_i32_e32 v97, 31, v96
	global_load_lds_dwordx4 v[12:13], off
	s_add_i32 s6, s4, 0
	v_lshlrev_b64 v[12:13], 1, v[96:97]
	s_add_i32 s48, s6, 0x18000
	v_lshl_add_u64 v[14:15], s[46:47], 0, v[12:13]
	v_lshl_add_u64 v[16:17], v[14:15], 0, s[96:97]
	s_mov_b32 m0, s48
	s_mov_b64 s[4:5], 0xc80
	global_load_lds_dwordx4 v[16:17], off
	v_lshl_add_u64 v[14:15], v[14:15], 0, s[4:5]
	s_add_i32 m0, s6, 0x18400
	s_mov_b64 s[4:5], 0x80080
	v_or_b32_e32 v98, 64, v96
	global_load_lds_dwordx4 v[14:15], off
	v_lshl_add_u64 v[10:11], v[10:11], 0, s[4:5]
	s_add_i32 m0, s94, 0x4000
	v_ashrrev_i32_e32 v99, 31, v98
	global_load_lds_dwordx4 v[10:11], off
	s_add_i32 m0, s6, 0x1c000
	v_lshl_add_u64 v[10:11], s[52:53], 0, v[12:13]
	v_and_b32_e32 v2, 31, v7
	global_load_lds_dwordx4 v[10:11], off
	v_lshl_add_u64 v[10:11], v[98:99], 1, s[52:53]
	s_add_i32 m0, s6, 0x1c400
	s_lshl_b32 s46, s1, 5
	global_load_lds_dwordx4 v[10:11], off
	v_or_b32_e32 v10, s46, v2
	v_ashrrev_i32_e32 v11, 31, v10
	v_bfe_u32 v8, v7, 5, 1
	v_lshlrev_b64 v[10:11], 12, v[10:11]
	v_lshl_add_u64 v[10:11], s[44:45], 0, v[10:11]
	v_lshlrev_b32_e32 v130, 4, v8
	v_lshl_add_u64 v[10:11], v[10:11], 0, v[130:131]
	global_load_dwordx4 v[92:95], v[10:11], off offset:1152
	global_load_dwordx4 v[88:91], v[10:11], off offset:1184
	global_load_dwordx4 v[84:87], v[10:11], off offset:1216
	global_load_dwordx4 v[80:83], v[10:11], off offset:1248
	v_and_b32_e32 v11, 0x70, v18
	v_mov_b32_e32 v9, s88
	v_mov_b32_e32 v10, s81
	v_lshl_add_u32 v114, v2, 7, 0
	v_bitop3_b32 v115, v130, v18, s64 bitop3:0x78
	v_bitop3_b32 v117, v130, v11, 64 bitop3:0x36
	s_add_i32 s4, s46, s89
	ds_read_b32 v9, v9
	ds_read_b32 v10, v10
	s_waitcnt vmcnt(3)
	s_barrier
	v_add_u32_e32 v107, v114, v115
	v_bitop3_b32 v116, v130, v11, 32 bitop3:0x36
	v_add_u32_e32 v109, v114, v117
	v_bitop3_b32 v118, v130, v11, s65 bitop3:0x36
	s_add_i32 s5, s4, 0xffffff81
	v_add_u32_e32 v108, v114, v116
	ds_read_b128 v[12:15], v107
	ds_read_b128 v[16:19], v108
	v_add_u32_e32 v110, v114, v118
	ds_read_b128 v[20:23], v109
	ds_read_b128 v[24:27], v110
	s_ashr_i32 s5, s5, 6
	s_cmpk_gt_i32 s4, 0xbe
	v_or_b32_e32 v111, s4, v2
	s_cselect_b32 s47, s5, 0
	s_addk_i32 s4, 0xde
	s_ashr_i32 s45, s4, 6
	s_waitcnt lgkmcnt(0)
	s_waitcnt vmcnt(0) lgkmcnt(0)
	v_mfma_f32_32x32x16_bf16 v[64:79], v[12:15], v[92:95], 0
	s_cmp_gt_i32 s47, 0
	s_cselect_b64 s[4:5], -1, 0
	s_cmp_lt_i32 s45, 1
	s_cselect_b64 s[6:7], -1, 0
	s_or_b64 s[4:5], s[6:7], s[4:5]
	s_and_b64 vcc, exec, s[4:5]
	v_mfma_f32_32x32x16_bf16 v[64:79], v[16:19], v[88:91], v[64:79]
	v_mfma_f32_32x32x16_bf16 v[64:79], v[20:23], v[84:87], v[64:79]
	v_mfma_f32_32x32x16_bf16 v[64:79], v[24:27], v[80:83], v[64:79]
	s_cbranch_vccnz .LBB0_1948
	v_lshlrev_b32_e32 v8, 2, v8
	v_sub_u32_e32 v8, v8, v111
	v_lshl_add_u32 v8, v8, 2, s88
	ds_read2_b32 v[12:13], v8 offset0:240 offset1:241
	ds_read2_b32 v[14:15], v8 offset0:242 offset1:243
	ds_read2_b32 v[16:17], v8 offset0:248 offset1:249
	ds_read2_b32 v[18:19], v8 offset0:250 offset1:251
	ds_read2_b32 v[20:21], v8 offset0:224 offset1:225
	ds_read2_b32 v[22:23], v8 offset0:226 offset1:227
	ds_read2_b32 v[24:25], v8 offset0:232 offset1:233
	ds_read2_b32 v[26:27], v8 offset0:234 offset1:235
	s_waitcnt lgkmcnt(4)
	v_pk_add_f32 v[78:79], v[78:79], v[18:19]
	v_pk_add_f32 v[76:77], v[76:77], v[16:17]
	v_pk_add_f32 v[74:75], v[74:75], v[14:15]
	v_pk_add_f32 v[72:73], v[72:73], v[12:13]
	s_waitcnt lgkmcnt(0)
	v_pk_add_f32 v[70:71], v[70:71], v[26:27]
	v_pk_add_f32 v[68:69], v[68:69], v[24:25]
	v_pk_add_f32 v[66:67], v[66:67], v[22:23]
	v_pk_add_f32 v[64:65], v[64:65], v[20:21]

; #define LAS __attribute__((address_space(3)))
; DI void expsum(f32x16& p, float& l_reg, bf16x8& pa0, bf16x8& pa1) {
; #pragma unroll
;     for (int r = 0; r < 16; ++r) p[r] = __builtin_amdgcn_exp2f(p[r]);
;     float ps = 0.f;
; #pragma unroll
;     for (int r = 0; r < 16; ++r) ps += p[r];
;     l_reg += ps; asm volatile("" : "+v"(l_reg));
;     ...
;     ATT_PK4(p, 0, pa0); ATT_PK4(p, 8, pa1);
;     ...
; }
; DI int v_rd_base(int lane) { return ((lane & 3) << 3) | (((lane >> 2) & 3) << 6) | (((lane >> 4) & 1) << 5) | (((lane >> 5) & 1) << 8); }
; template <int OFF> DI s16x4 tr_read(int vb) { s16x4 r; asm volatile("ds_read_b64_tr_b16 %0, %1 offset:%2" : "=&v"(r) : "v"(vb), "i"(OFF) : "memory"); return r; }
; template <int H> DI void v_reads(s16x4* vf, int vb) {
;     vf[0] = tr_read<v_rd_off(0, 2 * H, 0)>(vb); vf[1] = tr_read<v_rd_off(0, 2 * H, 1)>(vb); vf[2] = tr_read<v_rd_off(0, 2 * H + 1, 0)>(vb); vf[3] = tr_read<v_rd_off(0, 2 * H + 1, 1)>(vb);
;     vf[4] = tr_read<v_rd_off(1, 2 * H, 0)>(vb); vf[5] = tr_read<v_rd_off(1, 2 * H, 1)>(vb); vf[6] = tr_read<v_rd_off(1, 2 * H + 1, 0)>(vb); vf[7] = tr_read<v_rd_off(1, 2 * H + 1, 1)>(vb);
;     vf[8] = tr_read<v_rd_off(2, 2 * H, 0)>(vb); vf[9] = tr_read<v_rd_off(2, 2 * H, 1)>(vb); vf[10] = tr_read<v_rd_off(2, 2 * H + 1, 0)>(vb); vf[11] = tr_read<v_rd_off(2, 2 * H + 1, 1)>(vb);
;     vf[12] = tr_read<v_rd_off(3, 2 * H, 0)>(vb); vf[13] = tr_read<v_rd_off(3, 2 * H, 1)>(vb); vf[14] = tr_read<v_rd_off(3, 2 * H + 1, 0)>(vb); vf[15] = tr_read<v_rd_off(3, 2 * H + 1, 1)>(vb);
; }
; DI void pv_mma(f32x16* o, const s16x4* vf, bf16x8 pa0, bf16x8 pa1) {
;     ...
; #pragma unroll
;     for (int d0 = 0; d0 < 4; ++d0) {
;         o[d0] = __builtin_amdgcn_mfma_f32_32x32x16_bf16(pa0, ATT_PK(vf[4 * d0], vf[4 * d0 + 1]), o[d0], 0, 0, 0);
;         o[d0] = __builtin_amdgcn_mfma_f32_32x32x16_bf16(pa1, ATT_PK(vf[4 * d0 + 2], vf[4 * d0 + 3]), o[d0], 0, 0, 0); }
;     ...
; }
; template <int DQK, int D0A, int D0B> DI void k_reads(bf16x8* kf, const LAS unsigned char* Ks, int half, int r32, int hi) {
; #pragma unroll
;     for (int d0 = D0A; d0 < D0B; ++d0) kf[d0 - D0A] = *(const LAS bf16x8*)(Ks + half * (32 * DQK * 2) + kswz<DQK>(r32, (d0 * 16 + hi * 8) * 2));
; }
; template <int D0A, int D0B> DI void qk_mma(f32x16& p, const bf16x8* kf, const bf16x8* qr) {
; #pragma unroll
;     for (int d0 = D0A; d0 < D0B; ++d0) {
.LBB0_1961:
	ds_read_b128 v[98:101], v107 offset:12288
	ds_read_b128 v[102:105], v108 offset:12288
	ds_read_b128 v[114:117], v109 offset:12288
	ds_read_b128 v[122:125], v110 offset:12288
	v_lshl_add_u32 v96, s49, 14, v106
	ds_read_b64_tr_b16 v[132:133], v96 offset:0
	ds_read_b64_tr_b16 v[134:135], v96 offset:0x800
	ds_read_b64_tr_b16 v[136:137], v96 offset:0x1000
	ds_read_b64_tr_b16 v[138:139], v96 offset:0x1800
	ds_read_b64_tr_b16 v[140:141], v96 offset:0x200
	ds_read_b64_tr_b16 v[142:143], v96 offset:0xa00
	ds_read_b64_tr_b16 v[144:145], v96 offset:0x1200
	ds_read_b64_tr_b16 v[146:147], v96 offset:0x1a00
	ds_read_b64_tr_b16 v[148:149], v96 offset:0x400
	ds_read_b64_tr_b16 v[150:151], v96 offset:0xc00
	ds_read_b64_tr_b16 v[152:153], v96 offset:0x1400
	ds_read_b64_tr_b16 v[154:155], v96 offset:0x1c00
	ds_read_b64_tr_b16 v[156:157], v96 offset:0x600
	ds_read_b64_tr_b16 v[158:159], v96 offset:0xe00
	ds_read_b64_tr_b16 v[162:163], v96 offset:0x1600
	ds_read_b64_tr_b16 v[164:165], v96 offset:0x1e00
	s_setprio 1
	v_exp_f32_e32 v64, v64
	v_exp_f32_e32 v65, v65
	v_exp_f32_e32 v66, v66
	v_exp_f32_e32 v67, v67
	v_exp_f32_e32 v68, v68
	v_exp_f32_e32 v69, v69
	v_add_f32_e32 v97, v65, v64
	v_exp_f32_e32 v70, v70
	v_add_f32_e32 v97, v66, v97
	v_exp_f32_e32 v71, v71
	v_add_f32_e32 v97, v67, v97
	v_exp_f32_e32 v72, v72
	v_add_f32_e32 v97, v68, v97
	v_exp_f32_e32 v73, v73
	v_add_f32_e32 v97, v69, v97
	v_exp_f32_e32 v74, v74
	v_add_f32_e32 v97, v70, v97
	v_exp_f32_e32 v75, v75
	v_add_f32_e32 v97, v71, v97
	v_exp_f32_e32 v76, v76
	v_add_f32_e32 v97, v72, v97
	v_exp_f32_e32 v77, v77
	v_add_f32_e32 v97, v73, v97
	v_exp_f32_e32 v78, v78
	v_add_f32_e32 v97, v74, v97
	v_exp_f32_e32 v79, v79
	v_add_f32_e32 v97, v75, v97
	v_add_f32_e32 v97, v76, v97
	v_add_f32_e32 v97, v77, v97
	v_add_f32_e32 v97, v78, v97
	v_add_f32_e32 v97, v79, v97
	v_add_f32_e32 v97, v97, v120
	v_cvt_pk_bf16_f32 v64, v64, v65
	v_cvt_pk_bf16_f32 v65, v66, v67
	v_cvt_pk_bf16_f32 v66, v68, v69
	v_cvt_pk_bf16_f32 v67, v70, v71
	v_cvt_pk_bf16_f32 v68, v72, v73
	v_cvt_pk_bf16_f32 v69, v74, v75
	v_cvt_pk_bf16_f32 v70, v76, v77
	v_cvt_pk_bf16_f32 v71, v78, v79
	s_waitcnt lgkmcnt(0)
	s_setprio 2
	v_mfma_f32_32x32x16_bf16 v[0:15], v[64:67], v[132:135], v[0:15]
	s_cmp_gt_i32 s47, 61
	s_cselect_b64 s[0:1], -1, 0
	s_cmp_lt_i32 s45, 62
	s_cselect_b64 s[2:3], -1, 0
	s_or_b64 s[0:1], s[0:1], s[2:3]
	s_and_b64 vcc, exec, s[0:1]
	v_mfma_f32_32x32x16_bf16 v[48:63], v[64:67], v[140:143], v[48:63]
	v_mfma_f32_32x32x16_bf16 v[16:31], v[64:67], v[148:151], v[16:31]
	v_mfma_f32_32x32x16_bf16 v[32:47], v[64:67], v[156:159], v[32:47]
	v_mfma_f32_32x32x16_bf16 v[0:15], v[68:71], v[136:139], v[0:15]
	v_mfma_f32_32x32x16_bf16 v[48:63], v[68:71], v[144:147], v[48:63]
	v_mfma_f32_32x32x16_bf16 v[16:31], v[68:71], v[152:155], v[16:31]
	v_mfma_f32_32x32x16_bf16 v[32:47], v[68:71], v[162:165], v[32:47]
	s_waitcnt lgkmcnt(0)
	v_mfma_f32_32x32x16_bf16 v[64:79], v[98:101], v[92:95], 0
	v_mfma_f32_32x32x16_bf16 v[64:79], v[102:105], v[88:91], v[64:79]
	v_mfma_f32_32x32x16_bf16 v[64:79], v[114:117], v[84:87], v[64:79]
	v_mfma_f32_32x32x16_bf16 v[64:79], v[122:125], v[80:83], v[64:79]
	s_setprio 0
	s_cbranch_vccnz .LBB0_1963
	v_sub_u32_e32 v98, 0xf40, v111
	v_lshlrev_b32_e32 v98, 2, v98
	v_add3_u32 v98, s88, v98, v130
	v_add_u32_e32 v114, 0x400, v98
	v_add_u32_e32 v116, 0x408, v98
	v_add_u32_e32 v118, 0x420, v98
	v_add_u32_e32 v120, 0x428, v98
	v_add_u32_e32 v99, 0x440, v98
	v_add_u32_e32 v100, 0x448, v98
	v_add_u32_e32 v102, 0x460, v98
	v_add_u32_e32 v104, 0x468, v98
	ds_read2_b32 v[98:99], v99 offset1:1
	ds_read2_b32 v[100:101], v100 offset1:1
	ds_read2_b32 v[102:103], v102 offset1:1
	ds_read2_b32 v[104:105], v104 offset1:1
	ds_read2_b32 v[114:115], v114 offset1:1
	ds_read2_b32 v[116:117], v116 offset1:1
	ds_read2_b32 v[118:119], v118 offset1:1
	ds_read2_b32 v[120:121], v120 offset1:1
	s_waitcnt lgkmcnt(0)
	v_pk_add_f32 v[78:79], v[78:79], v[104:105]
	v_pk_add_f32 v[76:77], v[76:77], v[102:103]
	v_pk_add_f32 v[74:75], v[74:75], v[100:101]
	v_pk_add_f32 v[72:73], v[72:73], v[98:99]
	v_pk_add_f32 v[70:71], v[70:71], v[120:121]
	v_pk_add_f32 v[68:69], v[68:69], v[118:119]
	v_pk_add_f32 v[66:67], v[66:67], v[116:117]
	v_pk_add_f32 v[64:65], v[64:65], v[114:115]
.LBB0_1963:
	ds_read_b128 v[98:101], v107 offset:16384
	ds_read_b128 v[102:105], v108 offset:16384
	ds_read_b128 v[114:117], v109 offset:16384
	ds_read_b128 v[118:121], v110 offset:16384
	ds_read_b64_tr_b16 v[122:123], v96 offset:0x2000
	ds_read_b64_tr_b16 v[124:125], v96 offset:0x2800
	ds_read_b64_tr_b16 v[132:133], v96 offset:0x3000
	ds_read_b64_tr_b16 v[134:135], v96 offset:0x3800
	ds_read_b64_tr_b16 v[136:137], v96 offset:0x2200
	ds_read_b64_tr_b16 v[138:139], v96 offset:0x2a00
	ds_read_b64_tr_b16 v[140:141], v96 offset:0x3200
	ds_read_b64_tr_b16 v[142:143], v96 offset:0x3a00
	ds_read_b64_tr_b16 v[144:145], v96 offset:0x2400
	ds_read_b64_tr_b16 v[146:147], v96 offset:0x2c00
	ds_read_b64_tr_b16 v[148:149], v96 offset:0x3400
	ds_read_b64_tr_b16 v[150:151], v96 offset:0x3c00
	ds_read_b64_tr_b16 v[152:153], v96 offset:0x2600
	ds_read_b64_tr_b16 v[154:155], v96 offset:0x2e00
	ds_read_b64_tr_b16 v[156:157], v96 offset:0x3600
	ds_read_b64_tr_b16 v[158:159], v96 offset:0x3e00
	s_nop 6
	s_setprio 1
	v_exp_f32_e32 v64, v64
	v_exp_f32_e32 v65, v65
	v_exp_f32_e32 v66, v66
	v_exp_f32_e32 v67, v67
	v_exp_f32_e32 v68, v68
	v_exp_f32_e32 v69, v69
	v_add_f32_e32 v96, v65, v64
	v_exp_f32_e32 v70, v70
	v_add_f32_e32 v96, v66, v96
	v_exp_f32_e32 v71, v71
	v_add_f32_e32 v96, v67, v96
	v_exp_f32_e32 v72, v72
	v_add_f32_e32 v96, v68, v96
	v_exp_f32_e32 v73, v73
	v_add_f32_e32 v96, v69, v96
	v_exp_f32_e32 v74, v74
	v_add_f32_e32 v96, v70, v96
	v_exp_f32_e32 v75, v75
	v_add_f32_e32 v96, v71, v96
	v_exp_f32_e32 v76, v76
	v_add_f32_e32 v96, v72, v96
	v_exp_f32_e32 v77, v77
	v_add_f32_e32 v96, v73, v96
	v_exp_f32_e32 v78, v78
	v_add_f32_e32 v96, v74, v96
	v_exp_f32_e32 v79, v79
	v_add_f32_e32 v96, v75, v96
	v_add_f32_e32 v96, v76, v96
	v_add_f32_e32 v96, v77, v96
	v_add_f32_e32 v96, v78, v96
	v_add_f32_e32 v96, v79, v96
	v_add_f32_e32 v96, v97, v96
	v_cvt_pk_bf16_f32 v64, v64, v65
	v_cvt_pk_bf16_f32 v65, v66, v67
	v_cvt_pk_bf16_f32 v66, v68, v69
	v_cvt_pk_bf16_f32 v67, v70, v71
	v_cvt_pk_bf16_f32 v68, v72, v73
	v_cvt_pk_bf16_f32 v69, v74, v75
	v_cvt_pk_bf16_f32 v70, v76, v77
	v_cvt_pk_bf16_f32 v71, v78, v79
	s_waitcnt lgkmcnt(0)
	s_setprio 2
	s_cmp_lt_u32 s33, 0x100
	s_cbranch_scc1 .Lstg_d1_m61_21
	s_waitcnt vmcnt(0)
	s_barrier

; #define LAS __attribute__((address_space(3)))
; DI void expsum(f32x16& p, float& l_reg, bf16x8& pa0, bf16x8& pa1) {
; #pragma unroll
;     for (int r = 0; r < 16; ++r) p[r] = __builtin_amdgcn_exp2f(p[r]);
;     float ps = 0.f;
; #pragma unroll
;     for (int r = 0; r < 16; ++r) ps += p[r];
;     l_reg += ps; asm volatile("" : "+v"(l_reg));
;     ...
;     ATT_PK4(p, 0, pa0); ATT_PK4(p, 8, pa1);
;     ...
; }
; DI int v_rd_base(int lane) { return ((lane & 3) << 3) | (((lane >> 2) & 3) << 6) | (((lane >> 4) & 1) << 5) | (((lane >> 5) & 1) << 8); }
; template <int OFF> DI s16x4 tr_read(int vb) { s16x4 r; asm volatile("ds_read_b64_tr_b16 %0, %1 offset:%2" : "=&v"(r) : "v"(vb), "i"(OFF) : "memory"); return r; }
; template <int H> DI void v_reads(s16x4* vf, int vb) {
;     vf[0] = tr_read<v_rd_off(0, 2 * H, 0)>(vb); vf[1] = tr_read<v_rd_off(0, 2 * H, 1)>(vb); vf[2] = tr_read<v_rd_off(0, 2 * H + 1, 0)>(vb); vf[3] = tr_read<v_rd_off(0, 2 * H + 1, 1)>(vb);
;     vf[4] = tr_read<v_rd_off(1, 2 * H, 0)>(vb); vf[5] = tr_read<v_rd_off(1, 2 * H, 1)>(vb); vf[6] = tr_read<v_rd_off(1, 2 * H + 1, 0)>(vb); vf[7] = tr_read<v_rd_off(1, 2 * H + 1, 1)>(vb);
;     vf[8] = tr_read<v_rd_off(2, 2 * H, 0)>(vb); vf[9] = tr_read<v_rd_off(2, 2 * H, 1)>(vb); vf[10] = tr_read<v_rd_off(2, 2 * H + 1, 0)>(vb); vf[11] = tr_read<v_rd_off(2, 2 * H + 1, 1)>(vb);
;     vf[12] = tr_read<v_rd_off(3, 2 * H, 0)>(vb); vf[13] = tr_read<v_rd_off(3, 2 * H, 1)>(vb); vf[14] = tr_read<v_rd_off(3, 2 * H + 1, 0)>(vb); vf[15] = tr_read<v_rd_off(3, 2 * H + 1, 1)>(vb);
; }
; DI void pv_mma(f32x16* o, const s16x4* vf, bf16x8 pa0, bf16x8 pa1) {
;     ...
; #pragma unroll
;     for (int d0 = 0; d0 < 4; ++d0) {
;         o[d0] = __builtin_amdgcn_mfma_f32_32x32x16_bf16(pa0, ATT_PK(vf[4 * d0], vf[4 * d0 + 1]), o[d0], 0, 0, 0);
;         o[d0] = __builtin_amdgcn_mfma_f32_32x32x16_bf16(pa1, ATT_PK(vf[4 * d0 + 2], vf[4 * d0 + 3]), o[d0], 0, 0, 0); }
;     ...
; }
; template <int DQK, int D0A, int D0B> DI void k_reads(bf16x8* kf, const LAS unsigned char* Ks, int half, int r32, int hi) {
; #pragma unroll
;     for (int d0 = D0A; d0 < D0B; ++d0) kf[d0 - D0A] = *(const LAS bf16x8*)(Ks + half * (32 * DQK * 2) + kswz<DQK>(r32, (d0 * 16 + hi * 8) * 2));
; }
; template <int D0A, int D0B> DI void qk_mma(f32x16& p, const bf16x8* kf, const bf16x8* qr) {
; #pragma unroll
;     for (int d0 = D0A; d0 < D0B; ++d0) {
.LBB0_1967:
	ds_read_b128 v[100:103], v107 offset:20480
	ds_read_b128 v[114:117], v108 offset:20480
	ds_read_b128 v[118:121], v109 offset:20480
	ds_read_b128 v[122:125], v110 offset:20480
	v_add_u32_e32 v98, 0x8000, v106
	ds_read_b64_tr_b16 v[132:133], v98 offset:0
	ds_read_b64_tr_b16 v[134:135], v98 offset:0x800
	ds_read_b64_tr_b16 v[136:137], v98 offset:0x1000
	ds_read_b64_tr_b16 v[138:139], v98 offset:0x1800
	ds_read_b64_tr_b16 v[140:141], v98 offset:0x200
	ds_read_b64_tr_b16 v[142:143], v98 offset:0xa00
	ds_read_b64_tr_b16 v[144:145], v98 offset:0x1200
	ds_read_b64_tr_b16 v[146:147], v98 offset:0x1a00
	ds_read_b64_tr_b16 v[148:149], v98 offset:0x400
	ds_read_b64_tr_b16 v[150:151], v98 offset:0xc00
	ds_read_b64_tr_b16 v[152:153], v98 offset:0x1400
	ds_read_b64_tr_b16 v[154:155], v98 offset:0x1c00
	ds_read_b64_tr_b16 v[156:157], v98 offset:0x600
	ds_read_b64_tr_b16 v[158:159], v98 offset:0xe00
	ds_read_b64_tr_b16 v[162:163], v98 offset:0x1600
	ds_read_b64_tr_b16 v[164:165], v98 offset:0x1e00
	s_setprio 1
	v_exp_f32_e32 v64, v64
	v_exp_f32_e32 v65, v65
	v_exp_f32_e32 v66, v66
	v_exp_f32_e32 v67, v67
	v_exp_f32_e32 v68, v68
	v_exp_f32_e32 v69, v69
	v_add_f32_e32 v99, v65, v64
	v_exp_f32_e32 v70, v70
	v_add_f32_e32 v99, v66, v99
	v_exp_f32_e32 v71, v71
	v_add_f32_e32 v99, v67, v99
	v_exp_f32_e32 v72, v72
	v_add_f32_e32 v99, v68, v99
	v_exp_f32_e32 v73, v73
	v_add_f32_e32 v99, v69, v99
	v_exp_f32_e32 v74, v74
	v_add_f32_e32 v99, v70, v99
	v_exp_f32_e32 v75, v75
	v_add_f32_e32 v99, v71, v99
	v_exp_f32_e32 v76, v76
	v_add_f32_e32 v99, v72, v99
	v_exp_f32_e32 v77, v77
	v_add_f32_e32 v99, v73, v99
	v_exp_f32_e32 v78, v78
	v_add_f32_e32 v99, v74, v99
	v_exp_f32_e32 v79, v79
	v_add_f32_e32 v99, v75, v99
	v_add_f32_e32 v99, v76, v99
	v_add_f32_e32 v99, v77, v99
	v_add_f32_e32 v99, v78, v99
	v_add_f32_e32 v99, v79, v99
	v_add_f32_e32 v96, v99, v96
	v_cvt_pk_bf16_f32 v64, v64, v65
	v_cvt_pk_bf16_f32 v65, v66, v67
	v_cvt_pk_bf16_f32 v66, v68, v69
	v_cvt_pk_bf16_f32 v67, v70, v71
	v_cvt_pk_bf16_f32 v68, v72, v73
	v_cvt_pk_bf16_f32 v69, v74, v75
	v_cvt_pk_bf16_f32 v70, v76, v77
	v_cvt_pk_bf16_f32 v71, v78, v79
	s_waitcnt lgkmcnt(0)
	s_setprio 2
	v_mfma_f32_32x32x16_bf16 v[0:15], v[64:67], v[132:135], v[0:15]
	s_and_b64 vcc, exec, s[2:3]
	v_mfma_f32_32x32x16_bf16 v[48:63], v[64:67], v[140:143], v[48:63]
	v_mfma_f32_32x32x16_bf16 v[16:31], v[64:67], v[148:151], v[16:31]
	v_mfma_f32_32x32x16_bf16 v[32:47], v[64:67], v[156:159], v[32:47]
	v_mfma_f32_32x32x16_bf16 v[0:15], v[68:71], v[136:139], v[0:15]
	v_mfma_f32_32x32x16_bf16 v[48:63], v[68:71], v[144:147], v[48:63]
	v_mfma_f32_32x32x16_bf16 v[16:31], v[68:71], v[152:155], v[16:31]
	v_mfma_f32_32x32x16_bf16 v[32:47], v[68:71], v[162:165], v[32:47]
	s_waitcnt lgkmcnt(0)
	v_mfma_f32_32x32x16_bf16 v[64:79], v[100:103], v[92:95], 0
	v_mfma_f32_32x32x16_bf16 v[64:79], v[114:117], v[88:91], v[64:79]
	v_mfma_f32_32x32x16_bf16 v[64:79], v[118:121], v[84:87], v[64:79]
	v_mfma_f32_32x32x16_bf16 v[64:79], v[122:125], v[80:83], v[64:79]
	s_setprio 0
	s_cbranch_vccnz .LBB0_1969
	v_add3_u32 v97, s88, v97, v130
	v_add_u32_e32 v118, 0x408, v97
	v_add_u32_e32 v120, 0x420, v97
	v_add_u32_e32 v122, 0x428, v97
	v_add_u32_e32 v100, 0x440, v97
	v_add_u32_e32 v102, 0x448, v97
	v_add_u32_e32 v104, 0x460, v97
	v_add_u32_e32 v99, 0x400, v97
	v_add_u32_e32 v97, 0x468, v97
	ds_read2_b32 v[100:101], v100 offset1:1
	ds_read2_b32 v[102:103], v102 offset1:1
	ds_read2_b32 v[104:105], v104 offset1:1
	ds_read2_b32 v[114:115], v97 offset1:1
	ds_read2_b32 v[116:117], v99 offset1:1
	ds_read2_b32 v[118:119], v118 offset1:1
	ds_read2_b32 v[120:121], v120 offset1:1
	ds_read2_b32 v[122:123], v122 offset1:1
	s_waitcnt lgkmcnt(0)
	v_pk_add_f32 v[78:79], v[78:79], v[114:115]
	v_pk_add_f32 v[76:77], v[76:77], v[104:105]
	v_pk_add_f32 v[74:75], v[74:75], v[102:103]
	v_pk_add_f32 v[72:73], v[72:73], v[100:101]
	v_pk_add_f32 v[70:71], v[70:71], v[122:123]
	v_pk_add_f32 v[68:69], v[68:69], v[120:121]
	v_pk_add_f32 v[66:67], v[66:67], v[118:119]
	v_pk_add_f32 v[64:65], v[64:65], v[116:117]

; #define LAS __attribute__((address_space(3)))
; DI void expsum(f32x16& p, float& l_reg, bf16x8& pa0, bf16x8& pa1) {
; #pragma unroll
;     for (int r = 0; r < 16; ++r) p[r] = __builtin_amdgcn_exp2f(p[r]);
;     float ps = 0.f;
; #pragma unroll
;     for (int r = 0; r < 16; ++r) ps += p[r];
;     l_reg += ps; asm volatile("" : "+v"(l_reg));
;     ...
;     ATT_PK4(p, 0, pa0); ATT_PK4(p, 8, pa1);
;     ...
; }
; DI int v_rd_base(int lane) { return ((lane & 3) << 3) | (((lane >> 2) & 3) << 6) | (((lane >> 4) & 1) << 5) | (((lane >> 5) & 1) << 8); }
; template <int OFF> DI s16x4 tr_read(int vb) { s16x4 r; asm volatile("ds_read_b64_tr_b16 %0, %1 offset:%2" : "=&v"(r) : "v"(vb), "i"(OFF) : "memory"); return r; }
; template <int H> DI void v_reads(s16x4* vf, int vb) {
;     vf[0] = tr_read<v_rd_off(0, 2 * H, 0)>(vb); vf[1] = tr_read<v_rd_off(0, 2 * H, 1)>(vb); vf[2] = tr_read<v_rd_off(0, 2 * H + 1, 0)>(vb); vf[3] = tr_read<v_rd_off(0, 2 * H + 1, 1)>(vb);
;     vf[4] = tr_read<v_rd_off(1, 2 * H, 0)>(vb); vf[5] = tr_read<v_rd_off(1, 2 * H, 1)>(vb); vf[6] = tr_read<v_rd_off(1, 2 * H + 1, 0)>(vb); vf[7] = tr_read<v_rd_off(1, 2 * H + 1, 1)>(vb);
;     vf[8] = tr_read<v_rd_off(2, 2 * H, 0)>(vb); vf[9] = tr_read<v_rd_off(2, 2 * H, 1)>(vb); vf[10] = tr_read<v_rd_off(2, 2 * H + 1, 0)>(vb); vf[11] = tr_read<v_rd_off(2, 2 * H + 1, 1)>(vb);
;     vf[12] = tr_read<v_rd_off(3, 2 * H, 0)>(vb); vf[13] = tr_read<v_rd_off(3, 2 * H, 1)>(vb); vf[14] = tr_read<v_rd_off(3, 2 * H + 1, 0)>(vb); vf[15] = tr_read<v_rd_off(3, 2 * H + 1, 1)>(vb);
; }
; DI void pv_mma(f32x16* o, const s16x4* vf, bf16x8 pa0, bf16x8 pa1) {
;     ...
; #pragma unroll
;     for (int d0 = 0; d0 < 4; ++d0) {
;         o[d0] = __builtin_amdgcn_mfma_f32_32x32x16_bf16(pa0, ATT_PK(vf[4 * d0], vf[4 * d0 + 1]), o[d0], 0, 0, 0);
;         o[d0] = __builtin_amdgcn_mfma_f32_32x32x16_bf16(pa1, ATT_PK(vf[4 * d0 + 2], vf[4 * d0 + 3]), o[d0], 0, 0, 0); }
;     ...
; }
; template <int DQK, int D0A, int D0B> DI void k_reads(bf16x8* kf, const LAS unsigned char* Ks, int half, int r32, int hi) {
; #pragma unroll
;     for (int d0 = D0A; d0 < D0B; ++d0) kf[d0 - D0A] = *(const LAS bf16x8*)(Ks + half * (32 * DQK * 2) + kswz<DQK>(r32, (d0 * 16 + hi * 8) * 2));
; }
; template <int D0A, int D0B> DI void qk_mma(f32x16& p, const bf16x8* kf, const bf16x8* qr) {
; #pragma unroll
;     for (int d0 = D0A; d0 < D0B; ++d0) {
.LBB0_1973:
	ds_read_b128 v[98:101], v107 offset:28672
	ds_read_b128 v[102:105], v108 offset:28672
	ds_read_b128 v[112:115], v109 offset:28672
	ds_read_b128 v[108:111], v110 offset:28672
	ds_read_b64_tr_b16 v[116:117], v106 offset:0
	ds_read_b64_tr_b16 v[118:119], v106 offset:0x800
	ds_read_b64_tr_b16 v[120:121], v106 offset:0x1000
	ds_read_b64_tr_b16 v[122:123], v106 offset:0x1800
	ds_read_b64_tr_b16 v[124:125], v106 offset:0x200
	ds_read_b64_tr_b16 v[126:127], v106 offset:0xa00
	ds_read_b64_tr_b16 v[132:133], v106 offset:0x1200
	ds_read_b64_tr_b16 v[134:135], v106 offset:0x1a00
	ds_read_b64_tr_b16 v[136:137], v106 offset:0x400
	ds_read_b64_tr_b16 v[138:139], v106 offset:0xc00
	ds_read_b64_tr_b16 v[140:141], v106 offset:0x1400
	ds_read_b64_tr_b16 v[142:143], v106 offset:0x1c00
	ds_read_b64_tr_b16 v[144:145], v106 offset:0x600
	ds_read_b64_tr_b16 v[146:147], v106 offset:0xe00
	ds_read_b64_tr_b16 v[148:149], v106 offset:0x1600
	ds_read_b64_tr_b16 v[150:151], v106 offset:0x1e00
	s_setprio 1
	v_exp_f32_e32 v64, v64
	v_exp_f32_e32 v65, v65
	v_exp_f32_e32 v66, v66
	v_exp_f32_e32 v67, v67
	v_exp_f32_e32 v68, v68
	v_exp_f32_e32 v69, v69
	v_add_f32_e32 v107, v65, v64
	v_exp_f32_e32 v70, v70
	v_add_f32_e32 v107, v66, v107
	v_exp_f32_e32 v71, v71
	v_add_f32_e32 v107, v67, v107
	v_exp_f32_e32 v72, v72
	v_add_f32_e32 v107, v68, v107
	v_exp_f32_e32 v73, v73
	v_add_f32_e32 v107, v69, v107
	v_exp_f32_e32 v74, v74
	v_add_f32_e32 v107, v70, v107
	v_exp_f32_e32 v75, v75
	v_add_f32_e32 v107, v71, v107
	v_exp_f32_e32 v76, v76
	v_add_f32_e32 v107, v72, v107
	v_exp_f32_e32 v77, v77
	v_add_f32_e32 v107, v73, v107
	v_exp_f32_e32 v78, v78
	v_add_f32_e32 v107, v74, v107
	v_exp_f32_e32 v79, v79
	v_add_f32_e32 v107, v75, v107
	v_add_f32_e32 v107, v76, v107
	v_add_f32_e32 v107, v77, v107
	v_add_f32_e32 v107, v78, v107
	v_add_f32_e32 v107, v79, v107
	v_add_f32_e32 v96, v107, v96
	v_cvt_pk_bf16_f32 v64, v64, v65
	v_cvt_pk_bf16_f32 v65, v66, v67
	v_cvt_pk_bf16_f32 v66, v68, v69
	v_cvt_pk_bf16_f32 v67, v70, v71
	v_cvt_pk_bf16_f32 v68, v72, v73
	v_cvt_pk_bf16_f32 v69, v74, v75
	v_cvt_pk_bf16_f32 v70, v76, v77
	v_cvt_pk_bf16_f32 v71, v78, v79
	s_waitcnt lgkmcnt(0)
	s_setprio 2
	v_mfma_f32_32x32x16_bf16 v[0:15], v[64:67], v[116:119], v[0:15]
	s_and_b64 vcc, exec, s[2:3]
	v_mfma_f32_32x32x16_bf16 v[48:63], v[64:67], v[124:127], v[48:63]
	v_mfma_f32_32x32x16_bf16 v[16:31], v[64:67], v[136:139], v[16:31]
	v_mfma_f32_32x32x16_bf16 v[32:47], v[64:67], v[144:147], v[32:47]
	v_mfma_f32_32x32x16_bf16 v[0:15], v[68:71], v[120:123], v[0:15]
	v_mfma_f32_32x32x16_bf16 v[48:63], v[68:71], v[132:135], v[48:63]
	v_mfma_f32_32x32x16_bf16 v[16:31], v[68:71], v[140:143], v[16:31]
	v_mfma_f32_32x32x16_bf16 v[32:47], v[68:71], v[148:151], v[32:47]
	s_waitcnt lgkmcnt(0)
	v_mfma_f32_32x32x16_bf16 v[64:79], v[98:101], v[92:95], 0
	v_mfma_f32_32x32x16_bf16 v[64:79], v[102:105], v[88:91], v[64:79]
	v_mfma_f32_32x32x16_bf16 v[64:79], v[112:115], v[84:87], v[64:79]
	v_mfma_f32_32x32x16_bf16 v[64:79], v[108:111], v[80:83], v[64:79]
	s_setprio 0
	s_cbranch_vccnz .LBB0_1975
	v_add3_u32 v80, s88, v97, v130
	v_add_u32_e32 v88, 0x400, v80
	v_add_u32_e32 v90, 0x408, v80
	v_add_u32_e32 v92, 0x420, v80
	v_add_u32_e32 v94, 0x428, v80
	v_add_u32_e32 v81, 0x440, v80
	v_add_u32_e32 v82, 0x448, v80
	v_add_u32_e32 v84, 0x460, v80
	v_add_u32_e32 v86, 0x468, v80
	ds_read2_b32 v[80:81], v81 offset1:1
	ds_read2_b32 v[82:83], v82 offset1:1
	ds_read2_b32 v[84:85], v84 offset1:1
	ds_read2_b32 v[86:87], v86 offset1:1
	ds_read2_b32 v[88:89], v88 offset1:1
	ds_read2_b32 v[90:91], v90 offset1:1
	ds_read2_b32 v[92:93], v92 offset1:1
	ds_read2_b32 v[94:95], v94 offset1:1
	s_waitcnt lgkmcnt(0)
	v_pk_add_f32 v[78:79], v[78:79], v[86:87]
	v_pk_add_f32 v[76:77], v[76:77], v[84:85]
	v_pk_add_f32 v[74:75], v[74:75], v[82:83]
	v_pk_add_f32 v[72:73], v[72:73], v[80:81]
	v_pk_add_f32 v[70:71], v[70:71], v[94:95]
	v_pk_add_f32 v[68:69], v[68:69], v[92:93]
	v_pk_add_f32 v[66:67], v[66:67], v[90:91]
	v_pk_add_f32 v[64:65], v[64:65], v[88:89]
.LBB0_1975:
	s_lshl_b32 s0, s44, 2
	s_add_i32 s0, s0, 0
	s_add_i32 s0, s0, 0x24000
	ds_read_b64_tr_b16 v[80:81], v106 offset:0x2000
	ds_read_b64_tr_b16 v[82:83], v106 offset:0x2800
	ds_read_b64_tr_b16 v[84:85], v106 offset:0x3000
	ds_read_b64_tr_b16 v[86:87], v106 offset:0x3800
	ds_read_b64_tr_b16 v[88:89], v106 offset:0x2200
	ds_read_b64_tr_b16 v[90:91], v106 offset:0x2a00
	ds_read_b64_tr_b16 v[92:93], v106 offset:0x3200
	ds_read_b64_tr_b16 v[94:95], v106 offset:0x3a00
	ds_read_b64_tr_b16 v[98:99], v106 offset:0x2400
	ds_read_b64_tr_b16 v[100:101], v106 offset:0x2c00
	ds_read_b64_tr_b16 v[102:103], v106 offset:0x3400
	ds_read_b64_tr_b16 v[104:105], v106 offset:0x3c00
	ds_read_b64_tr_b16 v[108:109], v106 offset:0x2600
	ds_read_b64_tr_b16 v[110:111], v106 offset:0x2e00
	ds_read_b64_tr_b16 v[112:113], v106 offset:0x3600
	ds_read_b64_tr_b16 v[114:115], v106 offset:0x3e00
	s_nop 7
	s_setprio 1
	v_exp_f32_e32 v97, v64
	v_exp_f32_e32 v65, v65
	v_exp_f32_e32 v106, v66
	v_exp_f32_e32 v67, v67
	v_exp_f32_e32 v68, v68
	v_exp_f32_e32 v69, v69
	v_add_f32_e32 v64, v65, v97
	v_exp_f32_e32 v70, v70
	v_add_f32_e32 v64, v106, v64
	v_exp_f32_e32 v71, v71
	v_add_f32_e32 v64, v67, v64
	v_exp_f32_e32 v72, v72
	v_add_f32_e32 v64, v68, v64
	v_exp_f32_e32 v73, v73
	v_add_f32_e32 v64, v69, v64
	v_exp_f32_e32 v74, v74
	v_add_f32_e32 v64, v70, v64
	v_exp_f32_e32 v75, v75
	v_add_f32_e32 v64, v71, v64
	v_exp_f32_e32 v76, v76
	v_add_f32_e32 v64, v72, v64
	v_exp_f32_e32 v77, v77
	v_add_f32_e32 v64, v73, v64
	v_exp_f32_e32 v78, v78
	v_add_f32_e32 v64, v74, v64
	v_exp_f32_e32 v79, v79
	v_add_f32_e32 v64, v75, v64
	v_add_f32_e32 v64, v76, v64
	v_add_f32_e32 v64, v77, v64
	v_add_f32_e32 v64, v78, v64
	v_add_f32_e32 v64, v79, v64
	v_add_f32_e32 v64, v96, v64
	v_cvt_pk_bf16_f32 v66, v97, v65
	v_cvt_pk_bf16_f32 v67, v106, v67
	v_cvt_pk_bf16_f32 v68, v68, v69
	v_cvt_pk_bf16_f32 v69, v70, v71
	v_cvt_pk_bf16_f32 v70, v72, v73
	v_cvt_pk_bf16_f32 v71, v74, v75
	v_cvt_pk_bf16_f32 v72, v76, v77
	v_cvt_pk_bf16_f32 v73, v78, v79
	s_waitcnt lgkmcnt(0)
; template <int TAG = 0> DI int fresh_tid(int wv) { int l; asm volatile("v_mbcnt_lo_u32_b32 %0, -1, 0\n\tv_mbcnt_hi_u32_b32 %0, -1, %0 ; site %1" : "=v"(l) : "n"(TAG)); return wv * 64 + l; }
; DI int crow(int r, int hi) { return (r & 3) + 8 * (r >> 2) + 4 * hi; }
; DI float swap_sum(float v) { auto rr = __builtin_amdgcn_permlane32_swap(__float_as_uint(v), __float_as_uint(v), false, false); return __uint_as_float(rr[0]) + __uint_as_float(rr[1]); }
; template <int DQK, int MODE, int LDQ, int LDK, int LDV> ...
;     ...
;     l_reg = swap_sum(l_reg);
;     { const int lane2 = fresh_tid<110 + MODE>(wv) & 63, r32 = lane2 & 31, hi = lane2 >> 5;
;     if (hi == 0) li_l[r32] = l_reg;
;     asm volatile("s_waitcnt lgkmcnt(0)" ::: "memory");
;     float s0v[MODE == 2 ? 16 : 1][4];
;     if constexpr (MODE == 2) {
; #pragma unroll
;         for (int r = 0; r < 16; ++r)
; #pragma unroll
;             for (int d0 = 0; d0 < 4; ++d0) s0v[r][d0] = S0[(size_t)(wid * 32 + crow(r, hi)) * 512 + d0 * 32 + r32];
;     }
	s_setprio 2
	v_mfma_f32_32x32x16_bf16 v[0:15], v[66:69], v[80:83], v[0:15]
	v_mfma_f32_32x32x16_bf16 v[48:63], v[66:69], v[88:91], v[48:63]
	v_mfma_f32_32x32x16_bf16 v[16:31], v[66:69], v[98:101], v[16:31]
	v_mfma_f32_32x32x16_bf16 v[32:47], v[66:69], v[108:111], v[32:47]
	v_mfma_f32_32x32x16_bf16 v[0:15], v[70:73], v[84:87], v[0:15]
	v_mfma_f32_32x32x16_bf16 v[48:63], v[70:73], v[92:95], v[48:63]
	v_mfma_f32_32x32x16_bf16 v[16:31], v[70:73], v[102:105], v[16:31]
	v_mfma_f32_32x32x16_bf16 v[32:47], v[70:73], v[112:115], v[32:47]
	s_setprio 0
	v_mov_b32_e32 v66, v64
	v_mbcnt_lo_u32_b32 v65, -1, 0
	v_mbcnt_hi_u32_b32 v65, -1, v65
	s_nop 1
	v_permlane32_swap_b32_e32 v64, v66
	v_and_b32_e32 v114, 63, v65
	v_and_b32_e32 v170, 31, v65
	v_cmp_gt_u32_e32 vcc, 32, v114
	s_and_saveexec_b64 s[2:3], vcc
	v_lshl_add_u32 v67, v170, 2, s0
	v_add_f32_e32 v64, v64, v66
	ds_write_b32 v67, v64
	s_or_b64 exec, exec, s[2:3]
	v_lshrrev_b32_e32 v64, 3, v65
	v_and_b32_e32 v69, 4, v64
	v_or_b32_e32 v102, s46, v69
	v_lshlrev_b32_e32 v130, 2, v170
	v_ashrrev_i32_e32 v103, 31, v102
	v_or_b32_e32 v66, 1, v102
	v_lshl_add_u64 v[92:93], s[54:55], 0, v[130:131]
	v_lshlrev_b64 v[156:157], 11, v[102:103]
	v_ashrrev_i32_e32 v67, 31, v66
	s_waitcnt lgkmcnt(0)
	v_lshl_add_u64 v[64:65], v[92:93], 0, v[156:157]
	v_lshlrev_b64 v[148:149], 11, v[66:67]
	v_lshl_add_u64 v[66:67], v[92:93], 0, v[148:149]
	global_load_dword v110, v[64:65], off
	global_load_dword v111, v[64:65], off offset:128
	global_load_dword v109, v[64:65], off offset:256
	global_load_dword v108, v[64:65], off offset:384
	global_load_dword v106, v[66:67], off
	global_load_dword v107, v[66:67], off offset:128
	global_load_dword v105, v[66:67], off offset:256
	global_load_dword v104, v[66:67], off offset:384
	v_or_b32_e32 v64, 2, v102
	v_or_b32_e32 v66, 3, v102
	v_ashrrev_i32_e32 v65, 31, v64
	v_ashrrev_i32_e32 v67, 31, v66
	v_lshlrev_b64 v[146:147], 11, v[64:65]
	v_lshlrev_b64 v[136:137], 11, v[66:67]
	v_lshl_add_u64 v[64:65], v[92:93], 0, v[146:147]
	v_lshl_add_u64 v[66:67], v[92:93], 0, v[136:137]
	global_load_dword v158, v[64:65], off
	global_load_dword v159, v[64:65], off offset:128
	global_load_dword v155, v[64:65], off offset:256
	global_load_dword v154, v[64:65], off offset:384
	global_load_dword v152, v[66:67], off
	global_load_dword v153, v[66:67], off offset:128
	global_load_dword v151, v[66:67], off offset:256
	global_load_dword v150, v[66:67], off offset:384
	v_or_b32_e32 v64, 8, v102
	v_or_b32_e32 v66, 9, v102
	v_ashrrev_i32_e32 v65, 31, v64
	v_ashrrev_i32_e32 v67, 31, v66
	v_lshlrev_b64 v[134:135], 11, v[64:65]
	v_lshlrev_b64 v[120:121], 11, v[66:67]
	v_lshl_add_u64 v[64:65], v[92:93], 0, v[134:135]
	v_lshl_add_u64 v[66:67], v[92:93], 0, v[120:121]
	global_load_dword v144, v[64:65], off
	global_load_dword v145, v[64:65], off offset:128
	global_load_dword v143, v[64:65], off offset:256
	global_load_dword v142, v[64:65], off offset:384
	global_load_dword v140, v[66:67], off
	global_load_dword v141, v[66:67], off offset:128
	global_load_dword v139, v[66:67], off offset:256
	global_load_dword v138, v[66:67], off offset:384
	v_or_b32_e32 v64, 10, v102
	v_or_b32_e32 v66, 11, v102
	v_ashrrev_i32_e32 v65, 31, v64
	v_ashrrev_i32_e32 v67, 31, v66
	v_lshlrev_b64 v[118:119], 11, v[64:65]
	v_lshlrev_b64 v[90:91], 11, v[66:67]
	v_lshl_add_u64 v[64:65], v[92:93], 0, v[118:119]
	v_lshl_add_u64 v[66:67], v[92:93], 0, v[90:91]
	global_load_dword v132, v[64:65], off
	global_load_dword v133, v[64:65], off offset:128
	global_load_dword v127, v[64:65], off offset:256
	global_load_dword v126, v[64:65], off offset:384
	global_load_dword v124, v[66:67], off
	global_load_dword v125, v[66:67], off offset:128
	global_load_dword v123, v[66:67], off offset:256
	global_load_dword v122, v[66:67], off offset:384
	v_or_b32_e32 v64, 16, v102
	v_or_b32_e32 v66, 17, v102
	v_ashrrev_i32_e32 v65, 31, v64
	v_ashrrev_i32_e32 v67, 31, v66
	v_lshlrev_b64 v[86:87], 11, v[64:65]
	v_lshlrev_b64 v[78:79], 11, v[66:67]
	v_lshl_add_u64 v[64:65], v[92:93], 0, v[86:87]
	v_lshl_add_u64 v[66:67], v[92:93], 0, v[78:79]
	global_load_dword v100, v[64:65], off
	global_load_dword v101, v[64:65], off offset:128
	global_load_dword v99, v[64:65], off offset:256
	global_load_dword v98, v[64:65], off offset:384
	global_load_dword v96, v[66:67], off
	global_load_dword v97, v[66:67], off offset:128
	global_load_dword v95, v[66:67], off offset:256
	global_load_dword v94, v[66:67], off offset:384
	v_or_b32_e32 v64, 18, v102
	v_or_b32_e32 v66, 19, v102
	v_ashrrev_i32_e32 v65, 31, v64
	v_ashrrev_i32_e32 v67, 31, v66
	v_lshlrev_b64 v[76:77], 11, v[64:65]
	v_lshlrev_b64 v[72:73], 11, v[66:67]
	v_lshl_add_u64 v[64:65], v[92:93], 0, v[76:77]
	v_lshl_add_u64 v[66:67], v[92:93], 0, v[72:73]
	v_lshl_add_u32 v169, v69, 2, s0
	global_load_dword v88, v[64:65], off
	global_load_dword v89, v[64:65], off offset:128
	global_load_dword v85, v[64:65], off offset:256
	global_load_dword v84, v[64:65], off offset:384
	global_load_dword v82, v[66:67], off
	global_load_dword v83, v[66:67], off offset:128
	global_load_dword v81, v[66:67], off offset:256
	global_load_dword v80, v[66:67], off offset:384
	ds_read_b128 v[64:67], v169
	v_or_b32_e32 v68, 24, v102
	v_ashrrev_i32_e32 v69, 31, v68
	v_lshlrev_b64 v[74:75], 11, v[68:69]
	ds_read_b128 v[68:71], v169 offset:32
	s_waitcnt lgkmcnt(0)
; DI unsigned short f2bf(float x) { unsigned u = __float_as_uint(x); u += 0x7fffu + ((u >> 16) & 1u); return (unsigned short)(u >> 16); }
; DI float shx(float v, int mask, int lane) { return __int_as_float(__builtin_amdgcn_ds_bpermute((lane ^ mask) << 2, __float_as_int(v))); }
; DI int crow(int r, int hi) { return (r & 3) + 8 * (r >> 2) + 4 * hi; }
; template <int DQK, int MODE, int LDQ, int LDK, int LDV> ...
;     ...
;     for (int r = 0; r < 16; ++r) { const int orow = wid * 32 + crow(r, hi); const float rl = __builtin_amdgcn_rcpf(li_l[crow(r, hi)]);
;         if constexpr (MODE == 0) {
; #pragma unroll
;             for (int d0 = 0; d0 < 4; ++d0) AOb[(size_t)orow * 1024 + d0 * 32 + r32] = f2bf(o[d0][r] * rl);
;         } else if constexpr (MODE == 1) {
; #pragma unroll
;             for (int d0 = 0; d0 < 4; ++d0) S0[(size_t)orow * 512 + d0 * 32 + r32] = o[d0][r] * rl;
;         } else {
;             float v[4]; float ss = 0.f;
; #pragma unroll
;             for (int d0 = 0; d0 < 4; ++d0) { v[d0] = s0v[r][d0] - lam * (o[d0][r] * rl); ss += v[d0] * v[d0]; }
; #pragma unroll
;             for (int mk = 1; mk <= 16; mk <<= 1) ss += shx(ss, mk, lane2);
;             const float rs = rsqrtf(ss * (1.f / 128.f) + EPS) * 0.8f;
; #pragma unroll
;             for (int d0 = 0; d0 < 4; ++d0) AOb[(size_t)orow * 1024 + d0 * 32 + r32] = f2bf(v[d0] * rs * gout[d0 * 32 + r32]);
	v_rcp_f32_e32 v64, v64
	v_mov_b32_e32 v162, v0
	v_mov_b32_e32 v163, v48
	v_rcp_f32_e32 v0, v65
	v_pk_mul_f32 v[162:163], v[162:163], v[64:65] op_sel_hi:[1,0]
	v_mov_b32_e32 v48, v1
	v_lshlrev_b32_e32 v166, 2, v114
	v_pk_mul_f32 v[48:49], v[48:49], v[0:1] op_sel_hi:[1,0]
	v_xor_b32_e32 v164, 4, v166
	v_xor_b32_e32 v165, 8, v166
	v_xor_b32_e32 v168, 16, v166
	v_xor_b32_e32 v167, 32, v166
	v_or_b32_e32 v116, 25, v102
	v_ashrrev_i32_e32 v117, 31, v116
	v_xor_b32_e32 v166, 64, v166
	v_lshl_add_u64 v[112:113], v[92:93], 0, v[74:75]
	s_add_u32 s1, s60, s58
	s_mov_b32 s0, 0x358637bd
	s_addc_u32 s3, s61, s59
	s_lshl_b32 s2, s87, 1
	s_add_u32 s2, s1, s2
	s_addc_u32 s3, s3, 0
	s_waitcnt vmcnt(0)
	v_pk_fma_f32 v[172:173], v[128:129], v[162:163], v[110:111] neg_lo:[1,0,0] neg_hi:[1,0,0]
	v_mov_b32_e32 v162, v32
	v_mov_b32_e32 v163, v16
	v_pk_mul_f32 v[162:163], v[162:163], v[64:65] op_sel_hi:[1,0]
	v_mov_b32_e32 v16, v33
	v_pk_fma_f32 v[174:175], v[128:129], v[162:163], v[108:109] neg_lo:[1,0,0] neg_hi:[1,0,0]
	global_load_dword v163, v130, s[50:51]
	global_load_dword v162, v130, s[50:51] offset:128
	global_load_dword v161, v130, s[50:51] offset:256
	s_nop 0
	global_load_dword v130, v130, s[50:51] offset:384
	v_pk_fma_f32 v[176:177], v[128:129], v[48:49], v[106:107] neg_lo:[1,0,0] neg_hi:[1,0,0]
	v_pk_mul_f32 v[0:1], v[16:17], v[0:1] op_sel_hi:[1,0]
	v_pk_mul_f32 v[110:111], v[172:173], v[172:173]
	v_pk_mul_f32 v[48:49], v[176:177], v[176:177]
	v_pk_fma_f32 v[0:1], v[128:129], v[0:1], v[104:105] neg_lo:[1,0,0] neg_hi:[1,0,0]
	v_pk_mul_f32 v[108:109], v[174:175], v[174:175]
	v_pk_mul_f32 v[16:17], v[0:1], v[0:1]
	v_mov_b32_e32 v32, v48
	v_mov_b32_e32 v33, v110
	v_mov_b32_e32 v110, v49
	v_pk_add_f32 v[32:33], v[32:33], v[110:111]
	v_mov_b32_e32 v48, v17
	v_mov_b32_e32 v49, v109
	v_pk_add_f32 v[32:33], v[48:49], v[32:33]
	v_mov_b32_e32 v17, v108
	v_pk_add_f32 v[16:17], v[16:17], v[32:33]
	ds_bpermute_b32 v33, v164, v17
	ds_bpermute_b32 v32, v164, v16
	v_lshlrev_b64 v[64:65], 11, v[116:117]
	v_lshl_add_u64 v[48:49], v[92:93], 0, v[64:65]
	global_load_dword v116, v[112:113], off
	global_load_dword v117, v[112:113], off offset:128
	global_load_dword v115, v[112:113], off offset:256
	global_load_dword v114, v[112:113], off offset:384
	s_nop 0
	global_load_dword v112, v[48:49], off
	global_load_dword v113, v[48:49], off offset:128
	global_load_dword v111, v[48:49], off offset:256
	global_load_dword v110, v[48:49], off offset:384
	v_or_b32_e32 v48, 26, v102
	s_waitcnt lgkmcnt(0)
	v_pk_add_f32 v[16:17], v[16:17], v[32:33]
	ds_bpermute_b32 v33, v165, v17
	ds_bpermute_b32 v32, v165, v16
	v_or_b32_e32 v102, 27, v102
	v_ashrrev_i32_e32 v49, 31, v48
	v_ashrrev_i32_e32 v103, 31, v102
	v_lshlrev_b64 v[48:49], 11, v[48:49]
	s_waitcnt lgkmcnt(0)
	v_pk_add_f32 v[16:17], v[16:17], v[32:33]
	ds_bpermute_b32 v33, v168, v17
	ds_bpermute_b32 v32, v168, v16
	v_lshl_add_u64 v[104:105], v[92:93], 0, v[48:49]
	v_lshlrev_b32_e32 v170, 1, v170
	v_mov_b32_e32 v171, v131
	v_rcp_f32_e32 v66, v66
	s_waitcnt lgkmcnt(0)
	v_pk_add_f32 v[32:33], v[16:17], v[32:33]
	ds_bpermute_b32 v107, v167, v33
	ds_bpermute_b32 v106, v167, v32
	v_lshlrev_b64 v[16:17], 11, v[102:103]
	v_lshl_add_u64 v[92:93], v[92:93], 0, v[16:17]
	s_waitcnt lgkmcnt(0)
	v_pk_add_f32 v[32:33], v[32:33], v[106:107]
	ds_bpermute_b32 v179, v166, v33
	ds_bpermute_b32 v178, v166, v32
	global_load_dword v108, v[104:105], off
	global_load_dword v109, v[104:105], off offset:128
	global_load_dword v107, v[104:105], off offset:256
	global_load_dword v106, v[104:105], off offset:384
	s_nop 0
	global_load_dword v104, v[92:93], off
	global_load_dword v105, v[92:93], off offset:128
	global_load_dword v103, v[92:93], off offset:256
	global_load_dword v102, v[92:93], off offset:384
	v_mov_b64_e32 v[92:93], s[0:1]
	s_waitcnt lgkmcnt(0)
	v_pk_add_f32 v[32:33], v[32:33], v[178:179]
	s_nop 0
	v_pk_fma_f32 v[178:179], v[32:33], s[24:25], v[92:93] op_sel_hi:[1,0,0]
	s_nop 0
	v_mul_f32_e32 v32, 0x4b800000, v179
	v_cmp_gt_f32_e32 vcc, s67, v179
	s_nop 1
	v_cndmask_b32_e32 v32, v179, v32, vcc
	v_rsq_f32_e32 v179, v32
	v_lshl_add_u64 v[32:33], s[2:3], 0, v[170:171]
	v_lshl_add_u64 v[156:157], v[32:33], 0, v[156:157]
	v_lshl_add_u64 v[148:149], v[32:33], 0, v[148:149]
	v_mul_f32_e32 v170, 0x45800000, v179
	v_cndmask_b32_e32 v170, v179, v170, vcc
	v_mul_f32_e32 v170, 0x3f4ccccd, v170
	v_mul_f32_e32 v171, v172, v170
	v_cmp_gt_f32_e32 vcc, s67, v178
	s_mov_b64 s[2:3], 0
	s_waitcnt vmcnt(19)
	v_mul_f32_e32 v171, v163, v171
	v_bfe_u32 v172, v171, 16, 1
	v_add3_u32 v171, v171, v172, s68
	global_store_short_d16_hi v[156:157], v171, off offset:1024
	v_mul_f32_e32 v171, v173, v170
	s_waitcnt vmcnt(19)
	v_mul_f32_e32 v171, v162, v171
	v_bfe_u32 v172, v171, 16, 1
	v_add3_u32 v171, v171, v172, s68
	global_store_short_d16_hi v[156:157], v171, off offset:1088
	v_mul_f32_e32 v171, v175, v170
	s_waitcnt vmcnt(19)
	v_mul_f32_e32 v171, v161, v171
	v_bfe_u32 v172, v171, 16, 1
	v_add3_u32 v171, v171, v172, s68
	global_store_short_d16_hi v[156:157], v171, off offset:1152
	v_mul_f32_e32 v171, 0x4b800000, v178
	v_cndmask_b32_e32 v171, v178, v171, vcc
	v_mul_f32_e32 v170, v174, v170
	v_rsq_f32_e32 v171, v171
	s_waitcnt vmcnt(19)
; DI unsigned short f2bf(float x) { unsigned u = __float_as_uint(x); u += 0x7fffu + ((u >> 16) & 1u); return (unsigned short)(u >> 16); }
; DI float shx(float v, int mask, int lane) { return __int_as_float(__builtin_amdgcn_ds_bpermute((lane ^ mask) << 2, __float_as_int(v))); }
; DI int crow(int r, int hi) { return (r & 3) + 8 * (r >> 2) + 4 * hi; }
; template <int DQK, int MODE, int LDQ, int LDK, int LDV> ...
;     ...
;     for (int r = 0; r < 16; ++r) { const int orow = wid * 32 + crow(r, hi); const float rl = __builtin_amdgcn_rcpf(li_l[crow(r, hi)]);
;         if constexpr (MODE == 0) {
; #pragma unroll
;             for (int d0 = 0; d0 < 4; ++d0) AOb[(size_t)orow * 1024 + d0 * 32 + r32] = f2bf(o[d0][r] * rl);
;         } else if constexpr (MODE == 1) {
; #pragma unroll
;             for (int d0 = 0; d0 < 4; ++d0) S0[(size_t)orow * 512 + d0 * 32 + r32] = o[d0][r] * rl;
;         } else {
;             float v[4]; float ss = 0.f;
; #pragma unroll
;             for (int d0 = 0; d0 < 4; ++d0) { v[d0] = s0v[r][d0] - lam * (o[d0][r] * rl); ss += v[d0] * v[d0]; }
; #pragma unroll
;             for (int mk = 1; mk <= 16; mk <<= 1) ss += shx(ss, mk, lane2);
;             const float rs = rsqrtf(ss * (1.f / 128.f) + EPS) * 0.8f;
; #pragma unroll
;             for (int d0 = 0; d0 < 4; ++d0) AOb[(size_t)orow * 1024 + d0 * 32 + r32] = f2bf(v[d0] * rs * gout[d0 * 32 + r32]);
	v_mul_f32_e32 v170, v130, v170
	v_bfe_u32 v172, v170, 16, 1
	v_add3_u32 v170, v170, v172, s68
	global_store_short_d16_hi v[156:157], v170, off offset:1216
	v_mul_f32_e32 v156, 0x45800000, v171
	v_cndmask_b32_e32 v172, v171, v156, vcc
	v_mov_b32_e32 v156, v2
	v_rcp_f32_e32 v2, v67
	v_mov_b32_e32 v157, v50
	v_mov_b32_e32 v50, v3
	v_pk_mul_f32 v[156:157], v[156:157], v[66:67] op_sel_hi:[1,0]
	v_mov_b32_e32 v170, v34
	v_mov_b32_e32 v171, v18
	v_pk_mul_f32 v[50:51], v[50:51], v[2:3] op_sel_hi:[1,0]
	v_mov_b32_e32 v18, v35
	v_pk_fma_f32 v[156:157], v[128:129], v[156:157], v[158:159] neg_lo:[1,0,0] neg_hi:[1,0,0]
	v_pk_mul_f32 v[170:171], v[170:171], v[66:67] op_sel_hi:[1,0]
	v_pk_fma_f32 v[50:51], v[128:129], v[50:51], v[152:153] neg_lo:[1,0,0] neg_hi:[1,0,0]
	v_pk_mul_f32 v[2:3], v[18:19], v[2:3] op_sel_hi:[1,0]
	v_pk_mul_f32 v[158:159], v[156:157], v[156:157]
	v_pk_fma_f32 v[66:67], v[128:129], v[170:171], v[154:155] neg_lo:[1,0,0] neg_hi:[1,0,0]
	v_pk_mul_f32 v[152:153], v[50:51], v[50:51]
	v_pk_fma_f32 v[2:3], v[128:129], v[2:3], v[150:151] neg_lo:[1,0,0] neg_hi:[1,0,0]
	v_pk_mul_f32 v[154:155], v[66:67], v[66:67]
	v_pk_mul_f32 v[18:19], v[2:3], v[2:3]
	v_mov_b32_e32 v34, v152
	v_mov_b32_e32 v35, v158
	v_mov_b32_e32 v158, v153
	v_pk_add_f32 v[34:35], v[34:35], v[158:159]
	v_mov_b32_e32 v150, v19
	v_mov_b32_e32 v151, v155
	v_pk_add_f32 v[34:35], v[150:151], v[34:35]
	v_mov_b32_e32 v19, v154
	v_pk_add_f32 v[18:19], v[18:19], v[34:35]
	ds_bpermute_b32 v35, v164, v19
	ds_bpermute_b32 v34, v164, v18
	v_mul_f32_e32 v150, 0x3f4ccccd, v172
	v_mul_f32_e32 v151, v176, v150
	v_mul_f32_e32 v151, v163, v151
	v_bfe_u32 v152, v151, 16, 1
	s_waitcnt lgkmcnt(0)
	v_pk_add_f32 v[18:19], v[18:19], v[34:35]
	ds_bpermute_b32 v35, v165, v19
	ds_bpermute_b32 v34, v165, v18
	v_add3_u32 v151, v151, v152, s68
	global_store_short_d16_hi v[148:149], v151, off offset:1024
	v_mul_f32_e32 v151, v177, v150
	v_mul_f32_e32 v151, v162, v151
	s_waitcnt lgkmcnt(0)
	v_pk_add_f32 v[18:19], v[18:19], v[34:35]
	ds_bpermute_b32 v35, v168, v19
	ds_bpermute_b32 v34, v168, v18
	v_bfe_u32 v152, v151, 16, 1
	v_mul_f32_e32 v1, v1, v150
	v_add3_u32 v151, v151, v152, s68
	v_mul_f32_e32 v1, v161, v1
	s_waitcnt lgkmcnt(0)
	v_pk_add_f32 v[18:19], v[18:19], v[34:35]
	ds_bpermute_b32 v35, v167, v19
	ds_bpermute_b32 v34, v167, v18
	global_store_short_d16_hi v[148:149], v151, off offset:1088
	v_bfe_u32 v151, v1, 16, 1
	v_add3_u32 v1, v1, v151, s68
	v_mul_f32_e32 v0, v0, v150
	s_waitcnt lgkmcnt(0)
	v_pk_add_f32 v[18:19], v[18:19], v[34:35]
	ds_bpermute_b32 v35, v166, v19
	ds_bpermute_b32 v34, v166, v18
	global_store_short_d16_hi v[148:149], v1, off offset:1152
	v_mul_f32_e32 v150, v130, v0
	v_bfe_u32 v151, v150, 16, 1
	s_waitcnt lgkmcnt(0)
	v_pk_add_f32 v[0:1], v[18:19], v[34:35]
	s_nop 0
	v_pk_fma_f32 v[0:1], v[0:1], s[24:25], v[92:93] op_sel_hi:[1,0,0]
	s_nop 0
	v_mul_f32_e32 v18, 0x4b800000, v1
	v_cmp_gt_f32_e32 vcc, s67, v1
	s_nop 1
	v_cndmask_b32_e32 v1, v1, v18, vcc
	v_rsq_f32_e32 v1, v1
	v_add3_u32 v18, v150, v151, s68
	global_store_short_d16_hi v[148:149], v18, off offset:1216
	v_lshl_add_u64 v[18:19], v[32:33], 0, v[146:147]
	v_mul_f32_e32 v34, 0x45800000, v1
	v_cndmask_b32_e32 v1, v1, v34, vcc
	v_mul_f32_e32 v1, 0x3f4ccccd, v1
	v_mul_f32_e32 v34, v156, v1
	v_mul_f32_e32 v34, v163, v34
	v_bfe_u32 v35, v34, 16, 1
	v_add3_u32 v34, v34, v35, s68
	global_store_short_d16_hi v[18:19], v34, off offset:1024
	v_mul_f32_e32 v34, v157, v1
	v_mul_f32_e32 v34, v162, v34
	v_bfe_u32 v35, v34, 16, 1
	v_add3_u32 v34, v34, v35, s68
	global_store_short_d16_hi v[18:19], v34, off offset:1088
	v_mul_f32_e32 v34, v67, v1
	v_mul_f32_e32 v34, v161, v34
	v_bfe_u32 v35, v34, 16, 1
	v_add3_u32 v34, v34, v35, s68
	global_store_short_d16_hi v[18:19], v34, off offset:1152
	v_mul_f32_e32 v1, v66, v1
	v_mul_f32_e32 v34, 0x4b800000, v0
	v_cmp_gt_f32_e32 vcc, s67, v0
	v_mul_f32_e32 v1, v130, v1
	v_mov_b32_e32 v66, v36
	v_cndmask_b32_e32 v0, v0, v34, vcc
	v_rsq_f32_e32 v34, v0
	v_bfe_u32 v0, v1, 16, 1
	v_add3_u32 v0, v1, v0, s68
	global_store_short_d16_hi v[18:19], v0, off offset:1216
	v_rcp_f32_e32 v0, v68
	v_mov_b32_e32 v18, v4
	v_rcp_f32_e32 v4, v69
	v_mul_f32_e32 v1, 0x45800000, v34
	v_mov_b32_e32 v19, v52
	v_mov_b32_e32 v52, v5
	v_pk_mul_f32 v[18:19], v[18:19], v[0:1] op_sel_hi:[1,0]
	v_mov_b32_e32 v67, v20
	v_pk_mul_f32 v[52:53], v[52:53], v[4:5] op_sel_hi:[1,0]
	v_mov_b32_e32 v20, v37
	v_cndmask_b32_e32 v146, v34, v1, vcc
	v_pk_fma_f32 v[18:19], v[128:129], v[18:19], v[144:145] neg_lo:[1,0,0] neg_hi:[1,0,0]
	v_pk_mul_f32 v[0:1], v[66:67], v[0:1] op_sel_hi:[1,0]
	v_pk_fma_f32 v[52:53], v[128:129], v[52:53], v[140:141] neg_lo:[1,0,0] neg_hi:[1,0,0]
	v_pk_mul_f32 v[4:5], v[20:21], v[4:5] op_sel_hi:[1,0]
	v_pk_mul_f32 v[34:35], v[18:19], v[18:19]
	v_pk_fma_f32 v[0:1], v[128:129], v[0:1], v[142:143] neg_lo:[1,0,0] neg_hi:[1,0,0]
	v_pk_mul_f32 v[68:69], v[52:53], v[52:53]
	v_pk_fma_f32 v[4:5], v[128:129], v[4:5], v[138:139] neg_lo:[1,0,0] neg_hi:[1,0,0]
	v_pk_mul_f32 v[66:67], v[0:1], v[0:1]
	v_pk_mul_f32 v[20:21], v[4:5], v[4:5]
	v_mov_b32_e32 v36, v68
	v_mov_b32_e32 v37, v34
	v_mov_b32_e32 v34, v69
	v_pk_add_f32 v[34:35], v[36:37], v[34:35]
	v_mov_b32_e32 v36, v21
	v_mov_b32_e32 v37, v67
	v_pk_add_f32 v[34:35], v[36:37], v[34:35]
	v_mov_b32_e32 v21, v66
	v_pk_add_f32 v[20:21], v[20:21], v[34:35]
	ds_bpermute_b32 v35, v164, v21
	ds_bpermute_b32 v34, v164, v20
	v_mul_f32_e32 v66, 0x3f4ccccd, v146
	v_mul_f32_e32 v50, v50, v66
	v_mul_f32_e32 v50, v163, v50
	v_bfe_u32 v67, v50, 16, 1
	s_waitcnt lgkmcnt(0)
; DI unsigned short f2bf(float x) { unsigned u = __float_as_uint(x); u += 0x7fffu + ((u >> 16) & 1u); return (unsigned short)(u >> 16); }
; DI float shx(float v, int mask, int lane) { return __int_as_float(__builtin_amdgcn_ds_bpermute((lane ^ mask) << 2, __float_as_int(v))); }
; DI int crow(int r, int hi) { return (r & 3) + 8 * (r >> 2) + 4 * hi; }
; template <int DQK, int MODE, int LDQ, int LDK, int LDV> ...
;     ...
;     for (int r = 0; r < 16; ++r) { const int orow = wid * 32 + crow(r, hi); const float rl = __builtin_amdgcn_rcpf(li_l[crow(r, hi)]);
;         if constexpr (MODE == 0) {
; #pragma unroll
;             for (int d0 = 0; d0 < 4; ++d0) AOb[(size_t)orow * 1024 + d0 * 32 + r32] = f2bf(o[d0][r] * rl);
;         } else if constexpr (MODE == 1) {
; #pragma unroll
;             for (int d0 = 0; d0 < 4; ++d0) S0[(size_t)orow * 512 + d0 * 32 + r32] = o[d0][r] * rl;
;         } else {
;             float v[4]; float ss = 0.f;
; #pragma unroll
;             for (int d0 = 0; d0 < 4; ++d0) { v[d0] = s0v[r][d0] - lam * (o[d0][r] * rl); ss += v[d0] * v[d0]; }
; #pragma unroll
;             for (int mk = 1; mk <= 16; mk <<= 1) ss += shx(ss, mk, lane2);
;             const float rs = rsqrtf(ss * (1.f / 128.f) + EPS) * 0.8f;
; #pragma unroll
;             for (int d0 = 0; d0 < 4; ++d0) AOb[(size_t)orow * 1024 + d0 * 32 + r32] = f2bf(v[d0] * rs * gout[d0 * 32 + r32]);
	v_pk_add_f32 v[20:21], v[20:21], v[34:35]
	ds_bpermute_b32 v35, v165, v21
	ds_bpermute_b32 v34, v165, v20
	v_lshl_add_u64 v[36:37], v[32:33], 0, v[136:137]
	v_add3_u32 v50, v50, v67, s68
	global_store_short_d16_hi v[36:37], v50, off offset:1024
	v_mul_f32_e32 v50, v51, v66
	s_waitcnt lgkmcnt(0)
	v_pk_add_f32 v[20:21], v[20:21], v[34:35]
	ds_bpermute_b32 v35, v168, v21
	ds_bpermute_b32 v34, v168, v20
	v_mul_f32_e32 v50, v162, v50
	v_bfe_u32 v51, v50, 16, 1
	v_mul_f32_e32 v3, v3, v66
	v_add3_u32 v50, v50, v51, s68
	s_waitcnt lgkmcnt(0)
	v_pk_add_f32 v[20:21], v[20:21], v[34:35]
	ds_bpermute_b32 v35, v167, v21
	ds_bpermute_b32 v34, v167, v20
	v_mul_f32_e32 v3, v161, v3
	global_store_short_d16_hi v[36:37], v50, off offset:1088
	v_bfe_u32 v50, v3, 16, 1
	v_add3_u32 v3, v3, v50, s68
	s_waitcnt lgkmcnt(0)
	v_pk_add_f32 v[20:21], v[20:21], v[34:35]
	ds_bpermute_b32 v35, v166, v21
	ds_bpermute_b32 v34, v166, v20
	v_mul_f32_e32 v2, v2, v66
	global_store_short_d16_hi v[36:37], v3, off offset:1152
	v_mul_f32_e32 v50, v130, v2
	v_bfe_u32 v51, v50, 16, 1
	s_waitcnt lgkmcnt(0)
	v_pk_add_f32 v[2:3], v[20:21], v[34:35]
	s_nop 0
	v_pk_fma_f32 v[2:3], v[2:3], s[24:25], v[92:93] op_sel_hi:[1,0,0]
	s_nop 0
	v_mul_f32_e32 v20, 0x4b800000, v3
	v_cmp_gt_f32_e32 vcc, s67, v3
	s_nop 1
	v_cndmask_b32_e32 v3, v3, v20, vcc
	v_rsq_f32_e32 v3, v3
	v_add3_u32 v20, v50, v51, s68
	global_store_short_d16_hi v[36:37], v20, off offset:1216
	v_lshl_add_u64 v[20:21], v[32:33], 0, v[134:135]
	v_mul_f32_e32 v34, 0x45800000, v3
	v_cndmask_b32_e32 v3, v3, v34, vcc
	v_mul_f32_e32 v3, 0x3f4ccccd, v3
	v_mul_f32_e32 v18, v18, v3
	v_mul_f32_e32 v18, v163, v18
	v_bfe_u32 v34, v18, 16, 1
	v_add3_u32 v18, v18, v34, s68
	global_store_short_d16_hi v[20:21], v18, off offset:1024
	v_mul_f32_e32 v18, v19, v3
	v_mul_f32_e32 v18, v162, v18
	v_bfe_u32 v19, v18, 16, 1
	v_mul_f32_e32 v1, v1, v3
	v_add3_u32 v18, v18, v19, s68
	v_mul_f32_e32 v1, v161, v1
	global_store_short_d16_hi v[20:21], v18, off offset:1088
	v_bfe_u32 v18, v1, 16, 1
	v_add3_u32 v1, v1, v18, s68
	global_store_short_d16_hi v[20:21], v1, off offset:1152
	v_mul_f32_e32 v1, 0x4b800000, v2
	v_cmp_gt_f32_e32 vcc, s67, v2
	v_mul_f32_e32 v0, v0, v3
	v_mul_f32_e32 v0, v130, v0
	v_cndmask_b32_e32 v1, v2, v1, vcc
	v_rsq_f32_e32 v1, v1
	v_bfe_u32 v2, v0, 16, 1
	v_add3_u32 v0, v0, v2, s68
	global_store_short_d16_hi v[20:21], v0, off offset:1216
	v_mul_f32_e32 v2, 0x45800000, v1
	v_rcp_f32_e32 v0, v70
	v_cndmask_b32_e32 v66, v1, v2, vcc
	v_mov_b32_e32 v2, v6
	v_rcp_f32_e32 v6, v71
	v_mov_b32_e32 v3, v54
	v_mov_b32_e32 v18, v38
	v_mov_b32_e32 v19, v22
	v_mov_b32_e32 v54, v7
	v_pk_mul_f32 v[2:3], v[2:3], v[0:1] op_sel_hi:[1,0]
	v_pk_mul_f32 v[0:1], v[18:19], v[0:1] op_sel_hi:[1,0]
	v_pk_mul_f32 v[18:19], v[54:55], v[6:7] op_sel_hi:[1,0]
	v_mov_b32_e32 v22, v39
	v_pk_fma_f32 v[2:3], v[128:129], v[2:3], v[132:133] neg_lo:[1,0,0] neg_hi:[1,0,0]
	v_pk_fma_f32 v[20:21], v[128:129], v[18:19], v[124:125] neg_lo:[1,0,0] neg_hi:[1,0,0]
	v_pk_mul_f32 v[6:7], v[22:23], v[6:7] op_sel_hi:[1,0]
	v_pk_mul_f32 v[34:35], v[2:3], v[2:3]
	v_pk_fma_f32 v[0:1], v[128:129], v[0:1], v[126:127] neg_lo:[1,0,0] neg_hi:[1,0,0]
	v_pk_mul_f32 v[50:51], v[20:21], v[20:21]
	v_pk_fma_f32 v[18:19], v[128:129], v[6:7], v[122:123] neg_lo:[1,0,0] neg_hi:[1,0,0]
	v_pk_mul_f32 v[36:37], v[0:1], v[0:1]
	v_pk_mul_f32 v[6:7], v[18:19], v[18:19]
	v_mov_b32_e32 v22, v50
	v_mov_b32_e32 v23, v34
	v_mov_b32_e32 v34, v51
	v_pk_add_f32 v[22:23], v[22:23], v[34:35]
	v_mov_b32_e32 v34, v7
	v_mov_b32_e32 v35, v37
	v_pk_add_f32 v[22:23], v[34:35], v[22:23]
	v_mov_b32_e32 v7, v36
	v_pk_add_f32 v[6:7], v[6:7], v[22:23]
	ds_bpermute_b32 v23, v164, v7
	ds_bpermute_b32 v22, v164, v6
	v_mul_f32_e32 v36, 0x3f4ccccd, v66
	v_mul_f32_e32 v37, v52, v36
	v_mul_f32_e32 v37, v163, v37
	v_bfe_u32 v38, v37, 16, 1
	s_waitcnt lgkmcnt(0)
	v_pk_add_f32 v[6:7], v[6:7], v[22:23]
	ds_bpermute_b32 v23, v165, v7
	ds_bpermute_b32 v22, v165, v6
	v_lshl_add_u64 v[34:35], v[32:33], 0, v[120:121]
	v_add3_u32 v37, v37, v38, s68
	global_store_short_d16_hi v[34:35], v37, off offset:1024
	v_mul_f32_e32 v37, v53, v36
	s_waitcnt lgkmcnt(0)
	v_pk_add_f32 v[6:7], v[6:7], v[22:23]
	ds_bpermute_b32 v23, v168, v7
	ds_bpermute_b32 v22, v168, v6
	v_mul_f32_e32 v37, v162, v37
	v_bfe_u32 v38, v37, 16, 1
	v_mul_f32_e32 v5, v5, v36
	v_add3_u32 v37, v37, v38, s68
	s_waitcnt lgkmcnt(0)
	v_pk_add_f32 v[6:7], v[6:7], v[22:23]
	ds_bpermute_b32 v23, v167, v7
	ds_bpermute_b32 v22, v167, v6
	v_mul_f32_e32 v5, v161, v5
	global_store_short_d16_hi v[34:35], v37, off offset:1088
	v_bfe_u32 v37, v5, 16, 1
	v_add3_u32 v5, v5, v37, s68
	s_waitcnt lgkmcnt(0)
	v_pk_add_f32 v[6:7], v[6:7], v[22:23]
	ds_bpermute_b32 v23, v166, v7
	ds_bpermute_b32 v22, v166, v6
	v_mul_f32_e32 v4, v4, v36
	global_store_short_d16_hi v[34:35], v5, off offset:1152
	v_mul_f32_e32 v36, v130, v4
	v_bfe_u32 v37, v36, 16, 1
	s_waitcnt lgkmcnt(0)
	v_pk_add_f32 v[4:5], v[6:7], v[22:23]
	v_lshl_add_u64 v[22:23], v[32:33], 0, v[118:119]
	v_pk_fma_f32 v[4:5], v[4:5], s[24:25], v[92:93] op_sel_hi:[1,0,0]
	s_nop 0
	v_mul_f32_e32 v6, 0x4b800000, v5
	v_cmp_gt_f32_e32 vcc, s67, v5
	s_nop 1
	v_cndmask_b32_e32 v5, v5, v6, vcc
	v_rsq_f32_e32 v5, v5
	v_add3_u32 v6, v36, v37, s68
	global_store_short_d16_hi v[34:35], v6, off offset:1216
	v_mov_b32_e32 v36, v40
	v_mul_f32_e32 v6, 0x45800000, v5
	v_cndmask_b32_e32 v5, v5, v6, vcc
	v_mul_f32_e32 v5, 0x3f4ccccd, v5
	v_mul_f32_e32 v2, v2, v5
	v_mul_f32_e32 v2, v163, v2
	v_bfe_u32 v6, v2, 16, 1
	v_add3_u32 v2, v2, v6, s68
	global_store_short_d16_hi v[22:23], v2, off offset:1024
	v_mul_f32_e32 v2, v3, v5
	v_mul_f32_e32 v2, v162, v2
	v_bfe_u32 v3, v2, 16, 1
	v_mul_f32_e32 v1, v1, v5
	v_add3_u32 v2, v2, v3, s68
	v_mul_f32_e32 v1, v161, v1
	global_store_short_d16_hi v[22:23], v2, off offset:1088
	v_bfe_u32 v2, v1, 16, 1
	v_add3_u32 v1, v1, v2, s68
	v_mul_f32_e32 v2, 0x4b800000, v4
	v_cmp_gt_f32_e32 vcc, s67, v4
	v_mul_f32_e32 v0, v0, v5
	v_mul_f32_e32 v0, v130, v0
	v_cndmask_b32_e32 v2, v4, v2, vcc
	ds_read_b128 v[4:7], v169 offset:64
	global_store_short_d16_hi v[22:23], v1, off offset:1152
	v_bfe_u32 v1, v0, 16, 1
	v_rsq_f32_e32 v34, v2
	v_add3_u32 v0, v0, v1, s68
	global_store_short_d16_hi v[22:23], v0, off offset:1216
	ds_read_b128 v[0:3], v169 offset:96
	s_waitcnt lgkmcnt(1)
; DI unsigned short f2bf(float x) { unsigned u = __float_as_uint(x); u += 0x7fffu + ((u >> 16) & 1u); return (unsigned short)(u >> 16); }
; DI float shx(float v, int mask, int lane) { return __int_as_float(__builtin_amdgcn_ds_bpermute((lane ^ mask) << 2, __float_as_int(v))); }
; DI int crow(int r, int hi) { return (r & 3) + 8 * (r >> 2) + 4 * hi; }
; template <int DQK, int MODE, int LDQ, int LDK, int LDV> ...
;     ...
;     for (int r = 0; r < 16; ++r) { const int orow = wid * 32 + crow(r, hi); const float rl = __builtin_amdgcn_rcpf(li_l[crow(r, hi)]);
;         if constexpr (MODE == 0) {
; #pragma unroll
;             for (int d0 = 0; d0 < 4; ++d0) AOb[(size_t)orow * 1024 + d0 * 32 + r32] = f2bf(o[d0][r] * rl);
;         } else if constexpr (MODE == 1) {
; #pragma unroll
;             for (int d0 = 0; d0 < 4; ++d0) S0[(size_t)orow * 512 + d0 * 32 + r32] = o[d0][r] * rl;
;         } else {
;             float v[4]; float ss = 0.f;
; #pragma unroll
;             for (int d0 = 0; d0 < 4; ++d0) { v[d0] = s0v[r][d0] - lam * (o[d0][r] * rl); ss += v[d0] * v[d0]; }
; #pragma unroll
;             for (int mk = 1; mk <= 16; mk <<= 1) ss += shx(ss, mk, lane2);
;             const float rs = rsqrtf(ss * (1.f / 128.f) + EPS) * 0.8f;
; #pragma unroll
;             for (int d0 = 0; d0 < 4; ++d0) AOb[(size_t)orow * 1024 + d0 * 32 + r32] = f2bf(v[d0] * rs * gout[d0 * 32 + r32]);
;         } }
	v_rcp_f32_e32 v4, v4
	v_mul_f32_e32 v22, 0x45800000, v34
	v_cndmask_b32_e32 v52, v34, v22, vcc
	v_mov_b32_e32 v22, v8
	v_mov_b32_e32 v23, v56
	v_mov_b32_e32 v37, v24
	v_pk_mul_f32 v[22:23], v[22:23], v[4:5] op_sel_hi:[1,0]
	v_pk_mul_f32 v[36:37], v[36:37], v[4:5] op_sel_hi:[1,0]
	v_rcp_f32_e32 v4, v5
	v_mov_b32_e32 v56, v9
	v_mov_b32_e32 v24, v41
	v_pk_fma_f32 v[22:23], v[128:129], v[22:23], v[100:101] neg_lo:[1,0,0] neg_hi:[1,0,0]
	v_pk_mul_f32 v[8:9], v[56:57], v[4:5] op_sel_hi:[1,0]
	v_pk_mul_f32 v[4:5], v[24:25], v[4:5] op_sel_hi:[1,0]
	v_pk_fma_f32 v[8:9], v[128:129], v[8:9], v[96:97] neg_lo:[1,0,0] neg_hi:[1,0,0]
	v_pk_mul_f32 v[34:35], v[22:23], v[22:23]
	v_pk_fma_f32 v[36:37], v[128:129], v[36:37], v[98:99] neg_lo:[1,0,0] neg_hi:[1,0,0]
	v_pk_mul_f32 v[50:51], v[8:9], v[8:9]
	v_pk_fma_f32 v[4:5], v[128:129], v[4:5], v[94:95] neg_lo:[1,0,0] neg_hi:[1,0,0]
	v_pk_mul_f32 v[38:39], v[36:37], v[36:37]
	v_pk_mul_f32 v[24:25], v[4:5], v[4:5]
	v_mov_b32_e32 v40, v50
	v_mov_b32_e32 v41, v34
	v_mov_b32_e32 v34, v51
	v_pk_add_f32 v[34:35], v[40:41], v[34:35]
	v_mov_b32_e32 v40, v25
	v_mov_b32_e32 v41, v39
	v_pk_add_f32 v[34:35], v[40:41], v[34:35]
	v_mov_b32_e32 v25, v38
	v_pk_add_f32 v[24:25], v[24:25], v[34:35]
	ds_bpermute_b32 v35, v164, v25
	ds_bpermute_b32 v34, v164, v24
	v_mul_f32_e32 v40, 0x3f4ccccd, v52
	v_mul_f32_e32 v20, v20, v40
	v_mul_f32_e32 v20, v163, v20
	v_bfe_u32 v41, v20, 16, 1
	s_waitcnt lgkmcnt(0)
	v_pk_add_f32 v[24:25], v[24:25], v[34:35]
	ds_bpermute_b32 v35, v165, v25
	ds_bpermute_b32 v34, v165, v24
	v_lshl_add_u64 v[38:39], v[32:33], 0, v[90:91]
	v_add3_u32 v20, v20, v41, s68
	global_store_short_d16_hi v[38:39], v20, off offset:1024
	v_mul_f32_e32 v41, v21, v40
	s_waitcnt lgkmcnt(0)
	v_pk_add_f32 v[20:21], v[24:25], v[34:35]
	ds_bpermute_b32 v25, v168, v21
	ds_bpermute_b32 v24, v168, v20
	v_mul_f32_e32 v34, v162, v41
	v_bfe_u32 v35, v34, 16, 1
	v_mul_f32_e32 v19, v19, v40
	v_add3_u32 v34, v34, v35, s68
	s_waitcnt lgkmcnt(0)
	v_pk_add_f32 v[20:21], v[20:21], v[24:25]
	ds_bpermute_b32 v25, v167, v21
	ds_bpermute_b32 v24, v167, v20
	v_mul_f32_e32 v19, v161, v19
	global_store_short_d16_hi v[38:39], v34, off offset:1088
	v_bfe_u32 v34, v19, 16, 1
	v_add3_u32 v19, v19, v34, s68
	s_waitcnt lgkmcnt(0)
	v_pk_add_f32 v[20:21], v[20:21], v[24:25]
	ds_bpermute_b32 v25, v166, v21
	ds_bpermute_b32 v24, v166, v20
	v_mul_f32_e32 v18, v18, v40
	global_store_short_d16_hi v[38:39], v19, off offset:1152
	v_mul_f32_e32 v34, v130, v18
	v_bfe_u32 v35, v34, 16, 1
	s_waitcnt lgkmcnt(0)
	v_pk_add_f32 v[18:19], v[20:21], v[24:25]
	v_rcp_f32_e32 v6, v6
	v_pk_fma_f32 v[18:19], v[18:19], s[24:25], v[92:93] op_sel_hi:[1,0,0]
	v_rcp_f32_e32 v0, v0
	v_mul_f32_e32 v20, 0x4b800000, v19
	v_cmp_gt_f32_e32 vcc, s67, v19
	v_rcp_f32_e32 v2, v2
	s_nop 0
	v_cndmask_b32_e32 v19, v19, v20, vcc
	v_rsq_f32_e32 v19, v19
	v_add3_u32 v20, v34, v35, s68
	global_store_short_d16_hi v[38:39], v20, off offset:1216
	v_lshl_add_u64 v[20:21], v[32:33], 0, v[86:87]
	v_mul_f32_e32 v24, 0x45800000, v19
	v_cndmask_b32_e32 v19, v19, v24, vcc
	v_mul_f32_e32 v19, 0x3f4ccccd, v19
	v_mul_f32_e32 v22, v22, v19
	v_mul_f32_e32 v22, v163, v22
	v_bfe_u32 v24, v22, 16, 1
	v_add3_u32 v22, v22, v24, s68
	global_store_short_d16_hi v[20:21], v22, off offset:1024
	v_mul_f32_e32 v22, v23, v19
	v_mul_f32_e32 v22, v162, v22
	v_bfe_u32 v23, v22, 16, 1
	v_add3_u32 v22, v22, v23, s68
	global_store_short_d16_hi v[20:21], v22, off offset:1088
	v_mul_f32_e32 v22, v37, v19
	v_mul_f32_e32 v22, v161, v22
	v_bfe_u32 v23, v22, 16, 1
	v_add3_u32 v22, v22, v23, s68
	global_store_short_d16_hi v[20:21], v22, off offset:1152
	v_mul_f32_e32 v22, 0x4b800000, v18
	v_cmp_gt_f32_e32 vcc, s67, v18
	v_mul_f32_e32 v19, v36, v19
	v_mul_f32_e32 v19, v130, v19
	v_cndmask_b32_e32 v18, v18, v22, vcc
	v_rsq_f32_e32 v18, v18
	v_bfe_u32 v22, v19, 16, 1
	v_add3_u32 v19, v19, v22, s68
	global_store_short_d16_hi v[20:21], v19, off offset:1216
	v_mul_f32_e32 v19, 0x45800000, v18
	v_cndmask_b32_e32 v38, v18, v19, vcc
	v_mov_b32_e32 v18, v10
	v_mov_b32_e32 v19, v58
	v_mov_b32_e32 v22, v42
	v_mov_b32_e32 v23, v26
	v_pk_mul_f32 v[18:19], v[18:19], v[6:7] op_sel_hi:[1,0]
	v_pk_mul_f32 v[22:23], v[22:23], v[6:7] op_sel_hi:[1,0]
	v_rcp_f32_e32 v6, v7
	v_mov_b32_e32 v58, v11
	v_mov_b32_e32 v26, v43
	v_pk_fma_f32 v[18:19], v[128:129], v[18:19], v[88:89] neg_lo:[1,0,0] neg_hi:[1,0,0]
	v_pk_mul_f32 v[10:11], v[58:59], v[6:7] op_sel_hi:[1,0]
	v_pk_mul_f32 v[6:7], v[26:27], v[6:7] op_sel_hi:[1,0]
	v_pk_fma_f32 v[10:11], v[128:129], v[10:11], v[82:83] neg_lo:[1,0,0] neg_hi:[1,0,0]
	v_pk_mul_f32 v[20:21], v[18:19], v[18:19]
	v_pk_fma_f32 v[22:23], v[128:129], v[22:23], v[84:85] neg_lo:[1,0,0] neg_hi:[1,0,0]
	v_pk_mul_f32 v[34:35], v[10:11], v[10:11]
	v_pk_fma_f32 v[6:7], v[128:129], v[6:7], v[80:81] neg_lo:[1,0,0] neg_hi:[1,0,0]
	v_pk_mul_f32 v[24:25], v[22:23], v[22:23]
	v_pk_mul_f32 v[26:27], v[6:7], v[6:7]
	v_mov_b32_e32 v36, v34
	v_mov_b32_e32 v37, v20
	v_mov_b32_e32 v20, v35
	v_pk_add_f32 v[20:21], v[36:37], v[20:21]
	v_mov_b32_e32 v34, v27
	v_mov_b32_e32 v35, v25
	v_pk_add_f32 v[20:21], v[34:35], v[20:21]
	v_mov_b32_e32 v27, v24
	v_pk_add_f32 v[20:21], v[26:27], v[20:21]
	ds_bpermute_b32 v25, v164, v21
	ds_bpermute_b32 v24, v164, v20
	v_mul_f32_e32 v34, 0x3f4ccccd, v38
	v_mul_f32_e32 v8, v8, v34
	v_mul_f32_e32 v8, v163, v8
	v_bfe_u32 v35, v8, 16, 1
	s_waitcnt lgkmcnt(0)
	v_pk_add_f32 v[20:21], v[20:21], v[24:25]
	ds_bpermute_b32 v25, v165, v21
	ds_bpermute_b32 v24, v165, v20
	v_lshl_add_u64 v[26:27], v[32:33], 0, v[78:79]
	v_add3_u32 v8, v8, v35, s68
	global_store_short_d16_hi v[26:27], v8, off offset:1024
	v_mul_f32_e32 v35, v9, v34
	s_waitcnt lgkmcnt(0)
; DI unsigned short f2bf(float x) { unsigned u = __float_as_uint(x); u += 0x7fffu + ((u >> 16) & 1u); return (unsigned short)(u >> 16); }
; DI float shx(float v, int mask, int lane) { return __int_as_float(__builtin_amdgcn_ds_bpermute((lane ^ mask) << 2, __float_as_int(v))); }
; DI int crow(int r, int hi) { return (r & 3) + 8 * (r >> 2) + 4 * hi; }
; template <int DQK, int MODE, int LDQ, int LDK, int LDV> ...
;     ...
;     for (int r = 0; r < 16; ++r) { const int orow = wid * 32 + crow(r, hi); const float rl = __builtin_amdgcn_rcpf(li_l[crow(r, hi)]);
;         if constexpr (MODE == 0) {
; #pragma unroll
;             for (int d0 = 0; d0 < 4; ++d0) AOb[(size_t)orow * 1024 + d0 * 32 + r32] = f2bf(o[d0][r] * rl);
;         } else if constexpr (MODE == 1) {
; #pragma unroll
;             for (int d0 = 0; d0 < 4; ++d0) S0[(size_t)orow * 512 + d0 * 32 + r32] = o[d0][r] * rl;
;         } else {
;             float v[4]; float ss = 0.f;
; #pragma unroll
;             for (int d0 = 0; d0 < 4; ++d0) { v[d0] = s0v[r][d0] - lam * (o[d0][r] * rl); ss += v[d0] * v[d0]; }
; #pragma unroll
;             for (int mk = 1; mk <= 16; mk <<= 1) ss += shx(ss, mk, lane2);
;             const float rs = rsqrtf(ss * (1.f / 128.f) + EPS) * 0.8f;
; #pragma unroll
;             for (int d0 = 0; d0 < 4; ++d0) AOb[(size_t)orow * 1024 + d0 * 32 + r32] = f2bf(v[d0] * rs * gout[d0 * 32 + r32]);
;         } }
	v_pk_add_f32 v[8:9], v[20:21], v[24:25]
	ds_bpermute_b32 v21, v168, v9
	ds_bpermute_b32 v20, v168, v8
	v_mul_f32_e32 v24, v162, v35
	v_bfe_u32 v25, v24, 16, 1
	v_mul_f32_e32 v5, v5, v34
	v_add3_u32 v24, v24, v25, s68
	s_waitcnt lgkmcnt(0)
	v_pk_add_f32 v[8:9], v[8:9], v[20:21]
	ds_bpermute_b32 v21, v167, v9
	ds_bpermute_b32 v20, v167, v8
	v_mul_f32_e32 v5, v161, v5
	global_store_short_d16_hi v[26:27], v24, off offset:1088
	v_bfe_u32 v24, v5, 16, 1
	v_add3_u32 v5, v5, v24, s68
	s_waitcnt lgkmcnt(0)
	v_pk_add_f32 v[8:9], v[8:9], v[20:21]
	ds_bpermute_b32 v21, v166, v9
	ds_bpermute_b32 v20, v166, v8
	v_mul_f32_e32 v4, v4, v34
	global_store_short_d16_hi v[26:27], v5, off offset:1152
	v_mul_f32_e32 v24, v130, v4
	v_bfe_u32 v25, v24, 16, 1
	s_waitcnt lgkmcnt(0)
	v_pk_add_f32 v[4:5], v[8:9], v[20:21]
	s_nop 0
	v_pk_fma_f32 v[4:5], v[4:5], s[24:25], v[92:93] op_sel_hi:[1,0,0]
	s_nop 0
	v_mul_f32_e32 v8, 0x4b800000, v5
	v_cmp_gt_f32_e32 vcc, s67, v5
	s_nop 1
	v_cndmask_b32_e32 v5, v5, v8, vcc
	v_rsq_f32_e32 v5, v5
	v_add3_u32 v8, v24, v25, s68
	global_store_short_d16_hi v[26:27], v8, off offset:1216
	v_lshl_add_u64 v[8:9], v[32:33], 0, v[76:77]
	v_mul_f32_e32 v20, 0x45800000, v5
	v_cndmask_b32_e32 v5, v5, v20, vcc
	v_mul_f32_e32 v5, 0x3f4ccccd, v5
	v_mul_f32_e32 v18, v18, v5
	v_mul_f32_e32 v18, v163, v18
	v_bfe_u32 v20, v18, 16, 1
	v_add3_u32 v18, v18, v20, s68
	global_store_short_d16_hi v[8:9], v18, off offset:1024
	v_mul_f32_e32 v18, v19, v5
	v_mul_f32_e32 v18, v162, v18
	v_bfe_u32 v19, v18, 16, 1
	v_add3_u32 v18, v18, v19, s68
	global_store_short_d16_hi v[8:9], v18, off offset:1088
	v_mul_f32_e32 v18, v23, v5
	v_mul_f32_e32 v18, v161, v18
	v_bfe_u32 v19, v18, 16, 1
	v_add3_u32 v18, v18, v19, s68
	global_store_short_d16_hi v[8:9], v18, off offset:1152
	v_mul_f32_e32 v18, 0x4b800000, v4
	v_cmp_gt_f32_e32 vcc, s67, v4
	v_mul_f32_e32 v5, v22, v5
	v_mul_f32_e32 v5, v130, v5
	v_cndmask_b32_e32 v4, v4, v18, vcc
	v_rsq_f32_e32 v4, v4
	v_bfe_u32 v18, v5, 16, 1
	v_add3_u32 v5, v5, v18, s68
	global_store_short_d16_hi v[8:9], v5, off offset:1216
	v_mul_f32_e32 v5, 0x45800000, v4
	v_cndmask_b32_e32 v34, v4, v5, vcc
	v_mov_b32_e32 v4, v12
	v_mov_b32_e32 v5, v60
	v_mov_b32_e32 v18, v44
	v_mov_b32_e32 v19, v28
	v_pk_mul_f32 v[4:5], v[4:5], v[0:1] op_sel_hi:[1,0]
	v_pk_mul_f32 v[18:19], v[18:19], v[0:1] op_sel_hi:[1,0]
	v_rcp_f32_e32 v0, v1
	v_mov_b32_e32 v60, v13
	v_mov_b32_e32 v28, v45
	s_waitcnt vmcnt(58)
	v_pk_fma_f32 v[4:5], v[128:129], v[4:5], v[116:117] neg_lo:[1,0,0] neg_hi:[1,0,0]
	v_pk_mul_f32 v[12:13], v[60:61], v[0:1] op_sel_hi:[1,0]
	v_pk_mul_f32 v[0:1], v[28:29], v[0:1] op_sel_hi:[1,0]
	s_waitcnt vmcnt(54)
	v_pk_fma_f32 v[12:13], v[128:129], v[12:13], v[112:113] neg_lo:[1,0,0] neg_hi:[1,0,0]
	v_pk_mul_f32 v[8:9], v[4:5], v[4:5]
	v_pk_fma_f32 v[18:19], v[128:129], v[18:19], v[114:115] neg_lo:[1,0,0] neg_hi:[1,0,0]
	v_pk_mul_f32 v[22:23], v[12:13], v[12:13]
	s_waitcnt vmcnt(52)
	v_pk_fma_f32 v[0:1], v[128:129], v[0:1], v[110:111] neg_lo:[1,0,0] neg_hi:[1,0,0]
	v_pk_mul_f32 v[20:21], v[18:19], v[18:19]
	v_pk_mul_f32 v[24:25], v[0:1], v[0:1]
	v_mov_b32_e32 v26, v22
	v_mov_b32_e32 v27, v8
	v_mov_b32_e32 v8, v23
	v_pk_add_f32 v[8:9], v[26:27], v[8:9]
	v_mov_b32_e32 v22, v25
	v_mov_b32_e32 v23, v21
	v_pk_add_f32 v[8:9], v[22:23], v[8:9]
	v_mov_b32_e32 v25, v20
	v_pk_add_f32 v[8:9], v[24:25], v[8:9]
	ds_bpermute_b32 v21, v164, v9
	ds_bpermute_b32 v20, v164, v8
	v_mul_f32_e32 v24, 0x3f4ccccd, v34
	v_mul_f32_e32 v10, v10, v24
	v_mul_f32_e32 v10, v163, v10
	v_bfe_u32 v25, v10, 16, 1
	s_waitcnt lgkmcnt(0)
	v_pk_add_f32 v[8:9], v[8:9], v[20:21]
	ds_bpermute_b32 v21, v165, v9
	ds_bpermute_b32 v20, v165, v8
	v_lshl_add_u64 v[22:23], v[32:33], 0, v[72:73]
	v_add3_u32 v10, v10, v25, s68
	global_store_short_d16_hi v[22:23], v10, off offset:1024
	v_mul_f32_e32 v25, v11, v24
	s_waitcnt lgkmcnt(0)
	v_pk_add_f32 v[8:9], v[8:9], v[20:21]
	ds_bpermute_b32 v11, v168, v9
	ds_bpermute_b32 v10, v168, v8
	v_mul_f32_e32 v20, v162, v25
	v_bfe_u32 v21, v20, 16, 1
	v_mul_f32_e32 v7, v7, v24
	v_add3_u32 v20, v20, v21, s68
	s_waitcnt lgkmcnt(0)
	v_pk_add_f32 v[8:9], v[8:9], v[10:11]
	ds_bpermute_b32 v11, v167, v9
	ds_bpermute_b32 v10, v167, v8
	v_mul_f32_e32 v7, v161, v7
	global_store_short_d16_hi v[22:23], v20, off offset:1088
	v_bfe_u32 v20, v7, 16, 1
	v_add3_u32 v7, v7, v20, s68
	s_waitcnt lgkmcnt(0)
	v_pk_add_f32 v[8:9], v[8:9], v[10:11]
	ds_bpermute_b32 v11, v166, v9
	ds_bpermute_b32 v10, v166, v8
	v_mul_f32_e32 v6, v6, v24
	global_store_short_d16_hi v[22:23], v7, off offset:1152
	v_mul_f32_e32 v20, v130, v6
	v_bfe_u32 v21, v20, 16, 1
	s_waitcnt lgkmcnt(0)
; DI unsigned short f2bf(float x) { unsigned u = __float_as_uint(x); u += 0x7fffu + ((u >> 16) & 1u); return (unsigned short)(u >> 16); }
; DI float shx(float v, int mask, int lane) { return __int_as_float(__builtin_amdgcn_ds_bpermute((lane ^ mask) << 2, __float_as_int(v))); }
; DI int crow(int r, int hi) { return (r & 3) + 8 * (r >> 2) + 4 * hi; }
; template <int DQK, int MODE, int LDQ, int LDK, int LDV> ...
;     ...
;     for (int r = 0; r < 16; ++r) { const int orow = wid * 32 + crow(r, hi); const float rl = __builtin_amdgcn_rcpf(li_l[crow(r, hi)]);
;         if constexpr (MODE == 0) {
; #pragma unroll
;             for (int d0 = 0; d0 < 4; ++d0) AOb[(size_t)orow * 1024 + d0 * 32 + r32] = f2bf(o[d0][r] * rl);
;         } else if constexpr (MODE == 1) {
; #pragma unroll
;             for (int d0 = 0; d0 < 4; ++d0) S0[(size_t)orow * 512 + d0 * 32 + r32] = o[d0][r] * rl;
;         } else {
;             float v[4]; float ss = 0.f;
; #pragma unroll
;             for (int d0 = 0; d0 < 4; ++d0) { v[d0] = s0v[r][d0] - lam * (o[d0][r] * rl); ss += v[d0] * v[d0]; }
; #pragma unroll
;             for (int mk = 1; mk <= 16; mk <<= 1) ss += shx(ss, mk, lane2);
;             const float rs = rsqrtf(ss * (1.f / 128.f) + EPS) * 0.8f;
; #pragma unroll
;             for (int d0 = 0; d0 < 4; ++d0) AOb[(size_t)orow * 1024 + d0 * 32 + r32] = f2bf(v[d0] * rs * gout[d0 * 32 + r32]);
;         } }
; DI void phase4(const Params& p, LAS unsigned char* lds, int wv) {
;     ...
;             __syncthreads();
	v_pk_add_f32 v[6:7], v[8:9], v[10:11]
	s_nop 0
	v_pk_fma_f32 v[6:7], v[6:7], s[24:25], v[92:93] op_sel_hi:[1,0,0]
	s_nop 0
	v_mul_f32_e32 v8, 0x4b800000, v7
	v_cmp_gt_f32_e32 vcc, s67, v7
	s_nop 1
	v_cndmask_b32_e32 v7, v7, v8, vcc
	v_rsq_f32_e32 v7, v7
	v_add3_u32 v8, v20, v21, s68
	global_store_short_d16_hi v[22:23], v8, off offset:1216
	v_lshl_add_u64 v[8:9], v[32:33], 0, v[74:75]
	v_mul_f32_e32 v10, 0x45800000, v7
	v_cndmask_b32_e32 v7, v7, v10, vcc
	v_mul_f32_e32 v7, 0x3f4ccccd, v7
	v_mul_f32_e32 v4, v4, v7
	v_mul_f32_e32 v4, v163, v4
	v_bfe_u32 v10, v4, 16, 1
	v_add3_u32 v4, v4, v10, s68
	global_store_short_d16_hi v[8:9], v4, off offset:1024
	v_mul_f32_e32 v4, v5, v7
	v_mul_f32_e32 v4, v162, v4
	v_bfe_u32 v5, v4, 16, 1
	v_add3_u32 v4, v4, v5, s68
	global_store_short_d16_hi v[8:9], v4, off offset:1088
	v_mul_f32_e32 v4, v19, v7
	v_mul_f32_e32 v4, v161, v4
	v_bfe_u32 v5, v4, 16, 1
	v_add3_u32 v4, v4, v5, s68
	v_mul_f32_e32 v5, 0x4b800000, v6
	v_cmp_gt_f32_e32 vcc, s67, v6
	global_store_short_d16_hi v[8:9], v4, off offset:1152
	v_mul_f32_e32 v4, v18, v7
	v_cndmask_b32_e32 v5, v6, v5, vcc
	v_rsq_f32_e32 v5, v5
	v_mul_f32_e32 v4, v130, v4
	v_bfe_u32 v6, v4, 16, 1
	v_add3_u32 v4, v4, v6, s68
	global_store_short_d16_hi v[8:9], v4, off offset:1216
	v_mul_f32_e32 v4, 0x45800000, v5
	v_cndmask_b32_e32 v24, v5, v4, vcc
	v_mov_b32_e32 v4, v14
	v_mov_b32_e32 v5, v62
	v_mov_b32_e32 v8, v46
	v_mov_b32_e32 v9, v30
	v_pk_mul_f32 v[4:5], v[4:5], v[2:3] op_sel_hi:[1,0]
	v_pk_mul_f32 v[8:9], v[8:9], v[2:3] op_sel_hi:[1,0]
	v_rcp_f32_e32 v2, v3
	v_mov_b32_e32 v62, v15
	v_mov_b32_e32 v30, v47
	s_waitcnt vmcnt(58)
	v_pk_fma_f32 v[4:5], v[128:129], v[4:5], v[108:109] neg_lo:[1,0,0] neg_hi:[1,0,0]
	v_pk_mul_f32 v[14:15], v[62:63], v[2:3] op_sel_hi:[1,0]
	v_pk_mul_f32 v[2:3], v[30:31], v[2:3] op_sel_hi:[1,0]
	s_waitcnt vmcnt(54)
	v_pk_fma_f32 v[14:15], v[128:129], v[14:15], v[104:105] neg_lo:[1,0,0] neg_hi:[1,0,0]
	v_pk_mul_f32 v[6:7], v[4:5], v[4:5]
	v_pk_fma_f32 v[8:9], v[128:129], v[8:9], v[106:107] neg_lo:[1,0,0] neg_hi:[1,0,0]
	v_pk_mul_f32 v[18:19], v[14:15], v[14:15]
	s_waitcnt vmcnt(52)
	v_pk_fma_f32 v[2:3], v[128:129], v[2:3], v[102:103] neg_lo:[1,0,0] neg_hi:[1,0,0]
	v_pk_mul_f32 v[10:11], v[8:9], v[8:9]
	v_pk_mul_f32 v[20:21], v[2:3], v[2:3]
	v_mov_b32_e32 v22, v18
	v_mov_b32_e32 v23, v6
	v_mov_b32_e32 v6, v19
	v_pk_add_f32 v[6:7], v[22:23], v[6:7]
	v_mov_b32_e32 v18, v21
	v_mov_b32_e32 v19, v11
	v_pk_add_f32 v[6:7], v[18:19], v[6:7]
	v_mov_b32_e32 v21, v10
	v_pk_add_f32 v[6:7], v[20:21], v[6:7]
	ds_bpermute_b32 v11, v164, v7
	ds_bpermute_b32 v10, v164, v6
	v_mul_f32_e32 v20, 0x3f4ccccd, v24
	v_mul_f32_e32 v12, v12, v20
	v_mul_f32_e32 v12, v163, v12
	v_bfe_u32 v21, v12, 16, 1
	s_waitcnt lgkmcnt(0)
	v_pk_add_f32 v[6:7], v[6:7], v[10:11]
	ds_bpermute_b32 v11, v165, v7
	ds_bpermute_b32 v10, v165, v6
	v_lshl_add_u64 v[18:19], v[32:33], 0, v[64:65]
	v_add3_u32 v12, v12, v21, s68
	global_store_short_d16_hi v[18:19], v12, off offset:1024
	v_mul_f32_e32 v12, v13, v20
	s_waitcnt lgkmcnt(0)
	v_pk_add_f32 v[6:7], v[6:7], v[10:11]
	ds_bpermute_b32 v11, v168, v7
	ds_bpermute_b32 v10, v168, v6
	v_mul_f32_e32 v12, v162, v12
	v_bfe_u32 v13, v12, 16, 1
	v_mul_f32_e32 v1, v1, v20
	v_add3_u32 v12, v12, v13, s68
	s_waitcnt lgkmcnt(0)
	v_pk_add_f32 v[6:7], v[6:7], v[10:11]
	ds_bpermute_b32 v11, v167, v7
	ds_bpermute_b32 v10, v167, v6
	v_mul_f32_e32 v1, v161, v1
	global_store_short_d16_hi v[18:19], v12, off offset:1088
	v_bfe_u32 v12, v1, 16, 1
	v_add3_u32 v1, v1, v12, s68
	s_waitcnt lgkmcnt(0)
	v_pk_add_f32 v[6:7], v[6:7], v[10:11]
	ds_bpermute_b32 v11, v166, v7
	ds_bpermute_b32 v10, v166, v6
	v_mul_f32_e32 v0, v0, v20
	global_store_short_d16_hi v[18:19], v1, off offset:1152
	v_mul_f32_e32 v12, v130, v0
	v_bfe_u32 v13, v12, 16, 1
	s_waitcnt lgkmcnt(0)
	v_pk_add_f32 v[0:1], v[6:7], v[10:11]
	s_nop 0
	v_pk_fma_f32 v[0:1], v[0:1], s[24:25], v[92:93] op_sel_hi:[1,0,0]
	s_nop 0
	v_mul_f32_e32 v6, 0x4b800000, v1
	v_cmp_gt_f32_e32 vcc, s67, v1
	s_nop 1
	v_cndmask_b32_e32 v1, v1, v6, vcc
	v_rsq_f32_e32 v1, v1
	v_add3_u32 v6, v12, v13, s68
	global_store_short_d16_hi v[18:19], v6, off offset:1216
	v_lshl_add_u64 v[6:7], v[32:33], 0, v[48:49]
	v_mul_f32_e32 v10, 0x45800000, v1
	v_cndmask_b32_e32 v1, v1, v10, vcc
	v_mul_f32_e32 v1, 0x3f4ccccd, v1
	v_mul_f32_e32 v4, v4, v1
	v_mul_f32_e32 v4, v163, v4
	v_bfe_u32 v10, v4, 16, 1
	v_add3_u32 v4, v4, v10, s68
	global_store_short_d16_hi v[6:7], v4, off offset:1024
	v_mul_f32_e32 v4, v5, v1
	v_mul_f32_e32 v4, v162, v4
	v_bfe_u32 v5, v4, 16, 1
	v_add3_u32 v4, v4, v5, s68
	global_store_short_d16_hi v[6:7], v4, off offset:1088
	v_mul_f32_e32 v4, v9, v1
	v_mul_f32_e32 v4, v161, v4
	v_bfe_u32 v5, v4, 16, 1
	v_add3_u32 v4, v4, v5, s68
	global_store_short_d16_hi v[6:7], v4, off offset:1152
	v_mul_f32_e32 v4, 0x4b800000, v0
	v_cmp_gt_f32_e32 vcc, s67, v0
	v_mul_f32_e32 v1, v8, v1
	v_mul_f32_e32 v1, v130, v1
	v_cndmask_b32_e32 v0, v0, v4, vcc
	v_rsq_f32_e32 v0, v0
	v_bfe_u32 v4, v1, 16, 1
	v_add3_u32 v1, v1, v4, s68
	global_store_short_d16_hi v[6:7], v1, off offset:1216
	v_mul_f32_e32 v1, 0x45800000, v0
	v_cndmask_b32_e32 v0, v0, v1, vcc
	v_mul_f32_e32 v4, 0x3f4ccccd, v0
	v_mul_f32_e32 v5, v14, v4
	v_mul_f32_e32 v5, v163, v5
	v_bfe_u32 v6, v5, 16, 1
	v_lshl_add_u64 v[0:1], v[32:33], 0, v[16:17]
	v_add3_u32 v5, v5, v6, s68
	global_store_short_d16_hi v[0:1], v5, off offset:1024
	v_mul_f32_e32 v5, v15, v4
	v_mul_f32_e32 v5, v162, v5
	v_bfe_u32 v6, v5, 16, 1
	v_mul_f32_e32 v3, v3, v4
	v_add3_u32 v5, v5, v6, s68
	v_mul_f32_e32 v3, v161, v3
	global_store_short_d16_hi v[0:1], v5, off offset:1088
	v_bfe_u32 v5, v3, 16, 1
	v_mul_f32_e32 v2, v2, v4
	v_add3_u32 v3, v3, v5, s68
	v_mul_f32_e32 v2, v130, v2
	global_store_short_d16_hi v[0:1], v3, off offset:1152
	v_bfe_u32 v3, v2, 16, 1
	v_add3_u32 v2, v2, v3, s68
	global_store_short_d16_hi v[0:1], v2, off offset:1216
	s_waitcnt vmcnt(63) expcnt(7) lgkmcnt(15)
	s_barrier

; #define SBAR() __builtin_amdgcn_sched_barrier(0)
; #define ATT_DMA_K(t) do { const bf16_t* kg_ = Kh + (size_t)(t) * 64 * LDK; LAS unsigned char* sb_ = lds + ((t) & 3) * KBUF; \
;     _Pragma("unroll") for (int i_ = 0; i_ < NKP; ++i_) __builtin_amdgcn_global_load_lds((const unsigned*)(kg_ + kgo[i_]), (LAS unsigned*)(sb_ + (wid + 8 * i_) * 1024), 16, 0, 0); } while (0)
; #define ATT_DMA_V(t, vs) do { const bf16_t* vg_ = Vh + (size_t)(t) * 64 * LDV; LAS unsigned char* sb_ = lds + V_OFF + (vs) * SHM_V; \
;     _Pragma("unroll") for (int i_ = 0; i_ < 2; ++i_) __builtin_amdgcn_global_load_lds((const unsigned*)(vg_ + vgo[i_]), (LAS unsigned*)(sb_ + (2 * wid + i_) * 1024), 16, 0, 0); } while (0)
; #define ATT_SEG(t) do { if constexpr (MODE != 0) { if (((t) == tL && tL > 0) || (t) == tR) { const float f_ = (t) == tR ? fR : fL; l_reg *= f_; \
;     _Pragma("unroll") for (int d = 0; d < 4; ++d) _Pragma("unroll") for (int r = 0; r < 16; ++r) o[d][r] *= f_; } } } while (0)
; #define ATT_TOP(N) do { asm volatile("s_waitcnt vmcnt(%0)" :: "n"(N) : "memory"); __builtin_amdgcn_s_barrier(); asm volatile("" ::: "memory"); } while (0)
; DI void expsum(f32x16& p, float& l_reg, bf16x8& pa0, bf16x8& pa1) {
; #pragma unroll
;     for (int r = 0; r < 16; ++r) p[r] = __builtin_amdgcn_exp2f(p[r]);
;     float ps = 0.f;
; #pragma unroll
;     for (int r = 0; r < 16; ++r) ps += p[r];
;     l_reg += ps; asm volatile("" : "+v"(l_reg));
;     ...
;     ATT_PK4(p, 0, pa0); ATT_PK4(p, 8, pa1);
;     ...
; }
; template <int DQK, int MODE, int LDQ, int LDK, int LDV> ...
;     ...
;     f32x16 pA, pB; bf16x8 pa0, pa1;
;     int v0 = 0, v1 = 1, v2 = 2;
;     ATT_TOP(NKP + 2);
;     { bf16x8 kf[NDA]; k_reads<DQK, 0, NDA>(kf, lds, 0, r32, hi); ATT_LGKM0(); qk_mma<0, NDA>(pA, kf, qr);
;       if constexpr (ND0 > NDA) { bf16x8 kg[ND0 - NDA]; k_reads<DQK, NDA, ND0>(kg, lds, 0, r32, hi); ATT_LGKM0(); qk_mma<NDA, ND0>(pA, kg, qr); }
;       ATT_BIAS(pA, 0, 0); }
;     if (wid >= 4) __builtin_amdgcn_s_setprio(1);
;     for (int j = 0; j < NT; ++j) {
;         if (j + 2 < NT) ATT_TOP(NKP + 2); else ATT_TOP(0);
;         if (j + 3 < NT) ATT_DMA_K(j + 3);
;         if (j + 2 < NT) ATT_DMA_V(j + 2, v2);
;         ATT_SEG(j); SBAR();
;         ATT_STEP(pA, pB, 0, v0, true, 1, j);
;         ATT_STEP(pB, pA, 1, v0, (j + 1 < NT), 0, j + 1);
;         { const int t_ = v0; v0 = v1; v1 = v2; v2 = t_; }
;     }
.Lstg_mla_t61_4:
	s_setprio 0
	v_lshl_add_u64 v[132:133], v[132:133], 1, s[0:1]
	s_mov_b32 m0, s6
	v_lshl_add_u64 v[134:135], v[134:135], 1, s[0:1]
	global_load_lds_dwordx4 v[132:133], off
	s_mov_b32 m0, s7
	s_nop 0
	global_load_lds_dwordx4 v[134:135], off
	ds_read_b128 v[132:135], v161 offset:36864
	ds_read_b128 v[136:139], v162 offset:36864
	ds_read_b128 v[140:143], v163 offset:36864
	ds_read_b128 v[174:177], v164 offset:36864
	ds_read_b128 v[178:181], v165 offset:36864
	ds_read_b128 v[182:185], v166 offset:36864
	v_lshl_add_u32 v144, s5, 14, v130
	ds_read_b64_tr_b16 v[186:187], v144 offset:0
	ds_read_b64_tr_b16 v[188:189], v144 offset:0x800
	ds_read_b64_tr_b16 v[190:191], v144 offset:0x1000
	ds_read_b64_tr_b16 v[192:193], v144 offset:0x1800
	ds_read_b64_tr_b16 v[194:195], v144 offset:0x200
	ds_read_b64_tr_b16 v[196:197], v144 offset:0xa00
	ds_read_b64_tr_b16 v[198:199], v144 offset:0x1200
	ds_read_b64_tr_b16 v[200:201], v144 offset:0x1a00
	ds_read_b64_tr_b16 v[202:203], v144 offset:0x400
	ds_read_b64_tr_b16 v[204:205], v144 offset:0xc00
	ds_read_b64_tr_b16 v[206:207], v144 offset:0x1400
	ds_read_b64_tr_b16 v[208:209], v144 offset:0x1c00
	ds_read_b64_tr_b16 v[210:211], v144 offset:0x600
	ds_read_b64_tr_b16 v[212:213], v144 offset:0xe00
	ds_read_b64_tr_b16 v[214:215], v144 offset:0x1600
	ds_read_b64_tr_b16 v[216:217], v144 offset:0x1e00
	s_setprio 1
	v_exp_f32_e32 v64, v64
	v_exp_f32_e32 v65, v65
	v_exp_f32_e32 v66, v66
	v_exp_f32_e32 v67, v67
	v_exp_f32_e32 v68, v68
	v_exp_f32_e32 v69, v69
	v_add_f32_e32 v145, v65, v64
	v_exp_f32_e32 v70, v70
	v_add_f32_e32 v145, v66, v145
	v_exp_f32_e32 v71, v71
	v_add_f32_e32 v145, v67, v145
	v_exp_f32_e32 v72, v72
	v_add_f32_e32 v145, v68, v145
	v_exp_f32_e32 v73, v73
	v_add_f32_e32 v145, v69, v145
	v_exp_f32_e32 v74, v74
	v_add_f32_e32 v145, v70, v145
	v_exp_f32_e32 v75, v75
	v_add_f32_e32 v145, v71, v145
	v_exp_f32_e32 v76, v76
	v_add_f32_e32 v145, v72, v145
	v_exp_f32_e32 v77, v77
	v_add_f32_e32 v145, v73, v145
	v_exp_f32_e32 v78, v78
	v_add_f32_e32 v145, v74, v145
	v_exp_f32_e32 v79, v79
	v_add_f32_e32 v145, v75, v145
	v_add_f32_e32 v145, v76, v145
	v_add_f32_e32 v145, v77, v145
	v_add_f32_e32 v145, v78, v145
	v_add_f32_e32 v145, v79, v145
	v_add_f32_e32 v145, v173, v145
	v_cvt_pk_bf16_f32 v64, v64, v65
	v_cvt_pk_bf16_f32 v65, v66, v67
	v_cvt_pk_bf16_f32 v66, v68, v69
	v_cvt_pk_bf16_f32 v67, v70, v71
	v_cvt_pk_bf16_f32 v68, v72, v73
	v_cvt_pk_bf16_f32 v69, v74, v75
	v_cvt_pk_bf16_f32 v70, v76, v77
	v_cvt_pk_bf16_f32 v71, v78, v79
	s_waitcnt lgkmcnt(0)
	ds_read_b128 v[218:221], v167 offset:36864
	ds_read_b128 v[222:225], v168 offset:36864
	ds_read_b128 v[226:229], v169 offset:36864
	ds_read_b128 v[230:233], v170 offset:36864
	ds_read_b128 v[234:237], v171 offset:36864
	ds_read_b128 v[238:241], v172 offset:36864
	s_setprio 2
	v_mfma_f32_32x32x16_bf16 v[48:63], v[64:67], v[186:189], v[48:63]
	v_mfma_f32_32x32x16_bf16 v[32:47], v[64:67], v[194:197], v[32:47]
	v_mfma_f32_32x32x16_bf16 v[16:31], v[64:67], v[202:205], v[16:31]
	v_mfma_f32_32x32x16_bf16 v[0:15], v[64:67], v[210:213], v[0:15]
	v_mfma_f32_32x32x16_bf16 v[48:63], v[68:71], v[190:193], v[48:63]
	v_mfma_f32_32x32x16_bf16 v[32:47], v[68:71], v[198:201], v[32:47]
	v_mfma_f32_32x32x16_bf16 v[16:31], v[68:71], v[206:209], v[16:31]
	v_mfma_f32_32x32x16_bf16 v[0:15], v[68:71], v[214:217], v[0:15]
	s_waitcnt lgkmcnt(0)
	v_mfma_f32_32x32x16_bf16 v[64:79], v[132:135], v[80:83], 0
	v_mfma_f32_32x32x16_bf16 v[64:79], v[136:139], v[84:87], v[64:79]
	v_mfma_f32_32x32x16_bf16 v[64:79], v[140:143], v[88:91], v[64:79]
	v_mfma_f32_32x32x16_bf16 v[64:79], v[174:177], v[92:95], v[64:79]
	v_mfma_f32_32x32x16_bf16 v[64:79], v[178:181], v[96:99], v[64:79]
	v_mfma_f32_32x32x16_bf16 v[64:79], v[182:185], v[100:103], v[64:79]
	s_waitcnt lgkmcnt(0)
	v_mfma_f32_32x32x16_bf16 v[64:79], v[218:221], v[104:107], v[64:79]
	v_mfma_f32_32x32x16_bf16 v[64:79], v[222:225], v[108:111], v[64:79]
	v_mfma_f32_32x32x16_bf16 v[64:79], v[226:229], v[112:115], v[64:79]
	v_mfma_f32_32x32x16_bf16 v[64:79], v[230:233], v[116:119], v[64:79]
	v_mfma_f32_32x32x16_bf16 v[64:79], v[234:237], v[120:123], v[64:79]
	v_mfma_f32_32x32x16_bf16 v[64:79], v[238:241], v[124:127], v[64:79]
	s_setprio 0
	ds_read_b128 v[132:135], v161 offset:49152
	ds_read_b128 v[136:139], v162 offset:49152
	ds_read_b128 v[140:143], v163 offset:49152
	ds_read_b128 v[174:177], v164 offset:49152
	ds_read_b128 v[178:181], v165 offset:49152
	ds_read_b128 v[182:185], v166 offset:49152
	ds_read_b64_tr_b16 v[186:187], v144 offset:0x2000
	ds_read_b64_tr_b16 v[188:189], v144 offset:0x2800
	ds_read_b64_tr_b16 v[190:191], v144 offset:0x3000
	ds_read_b64_tr_b16 v[192:193], v144 offset:0x3800
	ds_read_b64_tr_b16 v[194:195], v144 offset:0x2200
	ds_read_b64_tr_b16 v[196:197], v144 offset:0x2a00
	ds_read_b64_tr_b16 v[198:199], v144 offset:0x3200
	ds_read_b64_tr_b16 v[200:201], v144 offset:0x3a00
	ds_read_b64_tr_b16 v[202:203], v144 offset:0x2400
	ds_read_b64_tr_b16 v[204:205], v144 offset:0x2c00
	ds_read_b64_tr_b16 v[206:207], v144 offset:0x3400
	ds_read_b64_tr_b16 v[208:209], v144 offset:0x3c00
	ds_read_b64_tr_b16 v[210:211], v144 offset:0x2600
	ds_read_b64_tr_b16 v[212:213], v144 offset:0x2e00
	ds_read_b64_tr_b16 v[214:215], v144 offset:0x3600
	ds_read_b64_tr_b16 v[216:217], v144 offset:0x3e00
	s_nop 5
	s_setprio 1
	v_exp_f32_e32 v64, v64
	v_exp_f32_e32 v65, v65
	v_exp_f32_e32 v66, v66
	v_exp_f32_e32 v67, v67
	v_exp_f32_e32 v68, v68
	v_exp_f32_e32 v69, v69
	v_add_f32_e32 v144, v65, v64
	v_exp_f32_e32 v70, v70
	v_add_f32_e32 v144, v66, v144
	v_exp_f32_e32 v71, v71
	v_add_f32_e32 v144, v67, v144
	v_exp_f32_e32 v72, v72
	v_add_f32_e32 v144, v68, v144
	v_exp_f32_e32 v73, v73
	v_add_f32_e32 v144, v69, v144
	v_exp_f32_e32 v74, v74
	v_add_f32_e32 v144, v70, v144
	v_exp_f32_e32 v75, v75
	v_add_f32_e32 v144, v71, v144
	v_exp_f32_e32 v76, v76
	v_add_f32_e32 v144, v72, v144
	v_exp_f32_e32 v77, v77
	v_add_f32_e32 v144, v73, v144
	v_exp_f32_e32 v78, v78
	v_add_f32_e32 v144, v74, v144
	v_exp_f32_e32 v79, v79
	v_add_f32_e32 v144, v75, v144
	v_add_f32_e32 v144, v76, v144
	v_add_f32_e32 v144, v77, v144
	v_add_f32_e32 v144, v78, v144
	v_add_f32_e32 v144, v79, v144
	v_add_f32_e32 v144, v145, v144
	v_cvt_pk_bf16_f32 v64, v64, v65
	v_cvt_pk_bf16_f32 v65, v66, v67
	v_cvt_pk_bf16_f32 v66, v68, v69
	v_cvt_pk_bf16_f32 v67, v70, v71
	v_cvt_pk_bf16_f32 v68, v72, v73
	v_cvt_pk_bf16_f32 v69, v74, v75
	v_cvt_pk_bf16_f32 v70, v76, v77
	v_cvt_pk_bf16_f32 v71, v78, v79
	s_waitcnt lgkmcnt(0)
	ds_read_b128 v[218:221], v167 offset:49152
	ds_read_b128 v[222:225], v168 offset:49152
	ds_read_b128 v[226:229], v169 offset:49152
	ds_read_b128 v[230:233], v170 offset:49152
	ds_read_b128 v[234:237], v171 offset:49152
	ds_read_b128 v[238:241], v172 offset:49152
	s_setprio 2
	s_cmp_lt_u32 s33, 0x100
	s_cbranch_scc1 .Lstg_mla_m61_5
	s_waitcnt vmcnt(0)
	s_barrier

; #define SBAR() __builtin_amdgcn_sched_barrier(0)
; #define ATT_DMA_K(t) do { const bf16_t* kg_ = Kh + (size_t)(t) * 64 * LDK; LAS unsigned char* sb_ = lds + ((t) & 3) * KBUF; \
;     _Pragma("unroll") for (int i_ = 0; i_ < NKP; ++i_) __builtin_amdgcn_global_load_lds((const unsigned*)(kg_ + kgo[i_]), (LAS unsigned*)(sb_ + (wid + 8 * i_) * 1024), 16, 0, 0); } while (0)
; #define ATT_DMA_V(t, vs) do { const bf16_t* vg_ = Vh + (size_t)(t) * 64 * LDV; LAS unsigned char* sb_ = lds + V_OFF + (vs) * SHM_V; \
;     _Pragma("unroll") for (int i_ = 0; i_ < 2; ++i_) __builtin_amdgcn_global_load_lds((const unsigned*)(vg_ + vgo[i_]), (LAS unsigned*)(sb_ + (2 * wid + i_) * 1024), 16, 0, 0); } while (0)
; #define ATT_SEG(t) do { if constexpr (MODE != 0) { if (((t) == tL && tL > 0) || (t) == tR) { const float f_ = (t) == tR ? fR : fL; l_reg *= f_; \
;     _Pragma("unroll") for (int d = 0; d < 4; ++d) _Pragma("unroll") for (int r = 0; r < 16; ++r) o[d][r] *= f_; } } } while (0)
; #define ATT_TOP(N) do { asm volatile("s_waitcnt vmcnt(%0)" :: "n"(N) : "memory"); __builtin_amdgcn_s_barrier(); asm volatile("" ::: "memory"); } while (0)
; DI void expsum(f32x16& p, float& l_reg, bf16x8& pa0, bf16x8& pa1) {
; #pragma unroll
;     for (int r = 0; r < 16; ++r) p[r] = __builtin_amdgcn_exp2f(p[r]);
;     float ps = 0.f;
; #pragma unroll
;     for (int r = 0; r < 16; ++r) ps += p[r];
;     l_reg += ps; asm volatile("" : "+v"(l_reg));
;     ...
;     ATT_PK4(p, 0, pa0); ATT_PK4(p, 8, pa1);
;     ...
; }
; template <int DQK, int MODE, int LDQ, int LDK, int LDV> ...
;     ...
;     f32x16 pA, pB; bf16x8 pa0, pa1;
;     int v0 = 0, v1 = 1, v2 = 2;
;     ATT_TOP(NKP + 2);
;     { bf16x8 kf[NDA]; k_reads<DQK, 0, NDA>(kf, lds, 0, r32, hi); ATT_LGKM0(); qk_mma<0, NDA>(pA, kf, qr);
;       if constexpr (ND0 > NDA) { bf16x8 kg[ND0 - NDA]; k_reads<DQK, NDA, ND0>(kg, lds, 0, r32, hi); ATT_LGKM0(); qk_mma<NDA, ND0>(pA, kg, qr); }
;       ATT_BIAS(pA, 0, 0); }
;     if (wid >= 4) __builtin_amdgcn_s_setprio(1);
;     for (int j = 0; j < NT; ++j) {
;         if (j + 2 < NT) ATT_TOP(NKP + 2); else ATT_TOP(0);
;         if (j + 3 < NT) ATT_DMA_K(j + 3);
;         if (j + 2 < NT) ATT_DMA_V(j + 2, v2);
;         ATT_SEG(j); SBAR();
;         ATT_STEP(pA, pB, 0, v0, true, 1, j);
;         ATT_STEP(pB, pA, 1, v0, (j + 1 < NT), 0, j + 1);
;         { const int t_ = v0; v0 = v1; v1 = v2; v2 = t_; }
;     }
.Lstg_mla_t62_6:
	s_setprio 0
	ds_read_b128 v[132:135], v161 offset:61440
	ds_read_b128 v[136:139], v162 offset:61440
	ds_read_b128 v[140:143], v163 offset:61440
	ds_read_b128 v[174:177], v164 offset:61440
	ds_read_b128 v[162:165], v165 offset:61440
	ds_read_b128 v[178:181], v166 offset:61440
	v_add_u32_e32 v145, 0x8000, v130
	ds_read_b64_tr_b16 v[182:183], v145 offset:0
	ds_read_b64_tr_b16 v[184:185], v145 offset:0x800
	ds_read_b64_tr_b16 v[186:187], v145 offset:0x1000
	ds_read_b64_tr_b16 v[188:189], v145 offset:0x1800
	ds_read_b64_tr_b16 v[190:191], v145 offset:0x200
	ds_read_b64_tr_b16 v[192:193], v145 offset:0xa00
	ds_read_b64_tr_b16 v[194:195], v145 offset:0x1200
	ds_read_b64_tr_b16 v[196:197], v145 offset:0x1a00
	ds_read_b64_tr_b16 v[198:199], v145 offset:0x400
	ds_read_b64_tr_b16 v[200:201], v145 offset:0xc00
	ds_read_b64_tr_b16 v[202:203], v145 offset:0x1400
	ds_read_b64_tr_b16 v[204:205], v145 offset:0x1c00
	ds_read_b64_tr_b16 v[206:207], v145 offset:0x600
	ds_read_b64_tr_b16 v[208:209], v145 offset:0xe00
	ds_read_b64_tr_b16 v[210:211], v145 offset:0x1600
	ds_read_b64_tr_b16 v[212:213], v145 offset:0x1e00
	s_nop 3
	s_setprio 1
	v_exp_f32_e32 v64, v64
	v_exp_f32_e32 v65, v65
	v_exp_f32_e32 v66, v66
	v_exp_f32_e32 v67, v67
	v_exp_f32_e32 v68, v68
	v_exp_f32_e32 v69, v69
	v_add_f32_e32 v161, v65, v64
	v_exp_f32_e32 v70, v70
	v_add_f32_e32 v161, v66, v161
	v_exp_f32_e32 v71, v71
	v_add_f32_e32 v161, v67, v161
	v_exp_f32_e32 v72, v72
	v_add_f32_e32 v161, v68, v161
	v_exp_f32_e32 v73, v73
	v_add_f32_e32 v161, v69, v161
	v_exp_f32_e32 v74, v74
	v_add_f32_e32 v161, v70, v161
	v_exp_f32_e32 v75, v75
	v_add_f32_e32 v161, v71, v161
	v_exp_f32_e32 v76, v76
	v_add_f32_e32 v161, v72, v161
	v_exp_f32_e32 v77, v77
	v_add_f32_e32 v161, v73, v161
	v_exp_f32_e32 v78, v78
	v_add_f32_e32 v161, v74, v161
	v_exp_f32_e32 v79, v79
	v_add_f32_e32 v161, v75, v161
	v_add_f32_e32 v161, v76, v161
	v_add_f32_e32 v161, v77, v161
	v_add_f32_e32 v161, v78, v161
	v_add_f32_e32 v161, v79, v161
	v_add_f32_e32 v144, v144, v161
	v_cvt_pk_bf16_f32 v64, v64, v65
	v_cvt_pk_bf16_f32 v65, v66, v67
	v_cvt_pk_bf16_f32 v66, v68, v69
	v_cvt_pk_bf16_f32 v67, v70, v71
	v_cvt_pk_bf16_f32 v68, v72, v73
	v_cvt_pk_bf16_f32 v69, v74, v75
	v_cvt_pk_bf16_f32 v70, v76, v77
	v_cvt_pk_bf16_f32 v71, v78, v79
	s_waitcnt lgkmcnt(0)
	ds_read_b128 v[214:217], v167 offset:61440
	ds_read_b128 v[218:221], v168 offset:61440
	ds_read_b128 v[166:169], v169 offset:61440
	ds_read_b128 v[222:225], v170 offset:61440
	ds_read_b128 v[226:229], v171 offset:61440
	ds_read_b128 v[170:173], v172 offset:61440
	s_setprio 2
	v_mfma_f32_32x32x16_bf16 v[48:63], v[64:67], v[182:185], v[48:63]
	v_mfma_f32_32x32x16_bf16 v[32:47], v[64:67], v[190:193], v[32:47]
	v_mfma_f32_32x32x16_bf16 v[16:31], v[64:67], v[198:201], v[16:31]
	v_mfma_f32_32x32x16_bf16 v[0:15], v[64:67], v[206:209], v[0:15]
	v_mfma_f32_32x32x16_bf16 v[48:63], v[68:71], v[186:189], v[48:63]
	v_mfma_f32_32x32x16_bf16 v[32:47], v[68:71], v[194:197], v[32:47]
	v_mfma_f32_32x32x16_bf16 v[16:31], v[68:71], v[202:205], v[16:31]
	v_mfma_f32_32x32x16_bf16 v[0:15], v[68:71], v[210:213], v[0:15]
	s_waitcnt lgkmcnt(0)
	v_mfma_f32_32x32x16_bf16 v[64:79], v[132:135], v[80:83], 0
	v_mfma_f32_32x32x16_bf16 v[64:79], v[136:139], v[84:87], v[64:79]
	v_mfma_f32_32x32x16_bf16 v[64:79], v[140:143], v[88:91], v[64:79]
	v_mfma_f32_32x32x16_bf16 v[64:79], v[174:177], v[92:95], v[64:79]
	v_mfma_f32_32x32x16_bf16 v[64:79], v[162:165], v[96:99], v[64:79]
	v_mfma_f32_32x32x16_bf16 v[64:79], v[178:181], v[100:103], v[64:79]
	s_waitcnt lgkmcnt(0)
	v_mfma_f32_32x32x16_bf16 v[64:79], v[214:217], v[104:107], v[64:79]
	v_mfma_f32_32x32x16_bf16 v[64:79], v[218:221], v[108:111], v[64:79]
	v_mfma_f32_32x32x16_bf16 v[64:79], v[166:169], v[112:115], v[64:79]
	v_mfma_f32_32x32x16_bf16 v[64:79], v[222:225], v[116:119], v[64:79]
	v_mfma_f32_32x32x16_bf16 v[64:79], v[226:229], v[120:123], v[64:79]
	v_mfma_f32_32x32x16_bf16 v[64:79], v[170:173], v[124:127], v[64:79]
	s_setprio 0
	v_add_u32_e32 v158, 0x12000, v158
	v_add_u32_e32 v132, v158, v151
	v_add_u32_e32 v136, v158, v149
	v_add_u32_e32 v140, v158, v148
	v_add_u32_e32 v161, v158, v147
	ds_read_b128 v[132:135], v132
	ds_read_b128 v[136:139], v136
	ds_read_b128 v[140:143], v140
	ds_read_b128 v[162:165], v161
	v_add_u32_e32 v161, v158, v146
	v_add_u32_e32 v170, v158, v150
	ds_read_b128 v[166:169], v161
	ds_read_b128 v[170:173], v170
	ds_read_b64_tr_b16 v[174:175], v145 offset:0x2000
	ds_read_b64_tr_b16 v[176:177], v145 offset:0x2800
	ds_read_b64_tr_b16 v[178:179], v145 offset:0x3000
	ds_read_b64_tr_b16 v[180:181], v145 offset:0x3800
	ds_read_b64_tr_b16 v[182:183], v145 offset:0x2200
	ds_read_b64_tr_b16 v[184:185], v145 offset:0x2a00
	ds_read_b64_tr_b16 v[186:187], v145 offset:0x3200
	ds_read_b64_tr_b16 v[188:189], v145 offset:0x3a00
	ds_read_b64_tr_b16 v[190:191], v145 offset:0x2400
	ds_read_b64_tr_b16 v[192:193], v145 offset:0x2c00
	ds_read_b64_tr_b16 v[194:195], v145 offset:0x3400
	ds_read_b64_tr_b16 v[196:197], v145 offset:0x3c00
	ds_read_b64_tr_b16 v[198:199], v145 offset:0x2600
	ds_read_b64_tr_b16 v[200:201], v145 offset:0x2e00
	ds_read_b64_tr_b16 v[202:203], v145 offset:0x3600
	ds_read_b64_tr_b16 v[204:205], v145 offset:0x3e00
	s_setprio 1
	v_exp_f32_e32 v64, v64
	v_exp_f32_e32 v65, v65
	v_exp_f32_e32 v66, v66
	v_exp_f32_e32 v67, v67
	v_exp_f32_e32 v68, v68
	v_exp_f32_e32 v69, v69
	v_add_f32_e32 v145, v65, v64
	v_exp_f32_e32 v70, v70
	v_add_f32_e32 v145, v66, v145
	v_exp_f32_e32 v71, v71
	v_add_f32_e32 v145, v67, v145
	v_exp_f32_e32 v72, v72
	v_add_f32_e32 v145, v68, v145
	v_exp_f32_e32 v73, v73
	v_add_f32_e32 v145, v69, v145
	v_exp_f32_e32 v74, v74
	v_add_f32_e32 v145, v70, v145
	v_exp_f32_e32 v75, v75
	v_add_f32_e32 v145, v71, v145
	v_exp_f32_e32 v76, v76
	v_add_f32_e32 v145, v72, v145
	v_exp_f32_e32 v77, v77
	v_add_f32_e32 v145, v73, v145
	v_exp_f32_e32 v78, v78
	v_add_f32_e32 v145, v74, v145
	v_exp_f32_e32 v79, v79
	v_add_f32_e32 v145, v75, v145
	v_add_f32_e32 v145, v76, v145
	v_add_f32_e32 v145, v77, v145
	v_add_f32_e32 v145, v78, v145
	v_add_f32_e32 v145, v79, v145
	v_add_f32_e32 v161, v144, v145
	v_cvt_pk_bf16_f32 v64, v64, v65
	v_cvt_pk_bf16_f32 v65, v66, v67
	v_cvt_pk_bf16_f32 v66, v68, v69
	v_cvt_pk_bf16_f32 v67, v70, v71
	v_cvt_pk_bf16_f32 v68, v72, v73
	v_cvt_pk_bf16_f32 v69, v74, v75
	v_cvt_pk_bf16_f32 v70, v76, v77
	v_cvt_pk_bf16_f32 v71, v78, v79
	s_waitcnt lgkmcnt(0)
	v_add_u32_e32 v72, v158, v152
	v_add_u32_e32 v73, v158, v153
	ds_read_b128 v[206:209], v72
	ds_read_b128 v[210:213], v73
	v_add_u32_e32 v72, v158, v154
	v_add_u32_e32 v73, v158, v155
	ds_read_b128 v[214:217], v72
	ds_read_b128 v[218:221], v73
	v_add_u32_e32 v72, v158, v156
	v_add_u32_e32 v73, v158, v157
	ds_read_b128 v[222:225], v72
	ds_read_b128 v[226:229], v73
	s_setprio 2
	s_cmp_lt_u32 s33, 0x100
	s_cbranch_scc1 .Lstg_mla_m62_7
	s_waitcnt vmcnt(0)
	s_barrier

; template <int TAG = 0> DI int fresh_tid(int wv) { int l; asm volatile("v_mbcnt_lo_u32_b32 %0, -1, 0\n\tv_mbcnt_hi_u32_b32 %0, -1, %0 ; site %1" : "=v"(l) : "n"(TAG)); return wv * 64 + l; }
; #define SBAR() __builtin_amdgcn_sched_barrier(0)
; DI float swap_sum(float v) { auto rr = __builtin_amdgcn_permlane32_swap(__float_as_uint(v), __float_as_uint(v), false, false); return __uint_as_float(rr[0]) + __uint_as_float(rr[1]); }
; #define ATT_DMA_K(t) do { const bf16_t* kg_ = Kh + (size_t)(t) * 64 * LDK; LAS unsigned char* sb_ = lds + ((t) & 3) * KBUF; \
;     _Pragma("unroll") for (int i_ = 0; i_ < NKP; ++i_) __builtin_amdgcn_global_load_lds((const unsigned*)(kg_ + kgo[i_]), (LAS unsigned*)(sb_ + (wid + 8 * i_) * 1024), 16, 0, 0); } while (0)
; #define ATT_TOP(N) do { asm volatile("s_waitcnt vmcnt(%0)" :: "n"(N) : "memory"); __builtin_amdgcn_s_barrier(); asm volatile("" ::: "memory"); } while (0)
; DI void expsum(f32x16& p, float& l_reg, bf16x8& pa0, bf16x8& pa1) {
; #pragma unroll
;     for (int r = 0; r < 16; ++r) p[r] = __builtin_amdgcn_exp2f(p[r]);
;     float ps = 0.f;
; #pragma unroll
;     for (int r = 0; r < 16; ++r) ps += p[r];
;     l_reg += ps; asm volatile("" : "+v"(l_reg));
;     ...
;     ATT_PK4(p, 0, pa0); ATT_PK4(p, 8, pa1);
;     ...
; }
; template <int DQK, int MODE, int LDQ, int LDK, int LDV> ...
;     ...
;     f32x16 pA, pB; bf16x8 pa0, pa1;
;     int v0 = 0, v1 = 1, v2 = 2;
;     ATT_TOP(NKP + 2);
;     { bf16x8 kf[NDA]; k_reads<DQK, 0, NDA>(kf, lds, 0, r32, hi); ATT_LGKM0(); qk_mma<0, NDA>(pA, kf, qr);
;       if constexpr (ND0 > NDA) { bf16x8 kg[ND0 - NDA]; k_reads<DQK, NDA, ND0>(kg, lds, 0, r32, hi); ATT_LGKM0(); qk_mma<NDA, ND0>(pA, kg, qr); }
;       ATT_BIAS(pA, 0, 0); }
;     if (wid >= 4) __builtin_amdgcn_s_setprio(1);
;     for (int j = 0; j < NT; ++j) {
;         if (j + 2 < NT) ATT_TOP(NKP + 2); else ATT_TOP(0);
;         if (j + 3 < NT) ATT_DMA_K(j + 3);
;         if (j + 2 < NT) ATT_DMA_V(j + 2, v2);
;         ATT_SEG(j); SBAR();
;         ATT_STEP(pA, pB, 0, v0, true, 1, j);
;         ATT_STEP(pB, pA, 1, v0, (j + 1 < NT), 0, j + 1);
;         { const int t_ = v0; v0 = v1; v1 = v2; v2 = t_; }
;     }
;     __builtin_amdgcn_s_setprio(0);
;     ...
;     l_reg = swap_sum(l_reg);
;     { const int lane2 = fresh_tid<110 + MODE>(wv) & 63, r32 = lane2 & 31, hi = lane2 >> 5;
;     if (hi == 0) li_l[r32] = l_reg;
.Lstg_mla_t63_8:
	s_setprio 0
	v_add_u32_e32 v158, s82, v159
	v_add_u32_e32 v132, v158, v151
	v_add_u32_e32 v136, v158, v149
	v_add_u32_e32 v140, v158, v148
	v_add_u32_e32 v144, v158, v147
	ds_read_b128 v[132:135], v132
	ds_read_b128 v[136:139], v136
	ds_read_b128 v[140:143], v140
	ds_read_b128 v[162:165], v144
	v_add_u32_e32 v144, v158, v146
	v_add_u32_e32 v148, v158, v150
	ds_read_b128 v[144:147], v144
	ds_read_b128 v[148:151], v148
	ds_read_b64_tr_b16 v[166:167], v130 offset:0
	ds_read_b64_tr_b16 v[168:169], v130 offset:0x800
	ds_read_b64_tr_b16 v[170:171], v130 offset:0x1000
	ds_read_b64_tr_b16 v[172:173], v130 offset:0x1800
	ds_read_b64_tr_b16 v[174:175], v130 offset:0x200
	ds_read_b64_tr_b16 v[176:177], v130 offset:0xa00
	ds_read_b64_tr_b16 v[178:179], v130 offset:0x1200
	ds_read_b64_tr_b16 v[180:181], v130 offset:0x1a00
	ds_read_b64_tr_b16 v[182:183], v130 offset:0x400
	ds_read_b64_tr_b16 v[184:185], v130 offset:0xc00
	ds_read_b64_tr_b16 v[186:187], v130 offset:0x1400
	ds_read_b64_tr_b16 v[188:189], v130 offset:0x1c00
	ds_read_b64_tr_b16 v[190:191], v130 offset:0x600
	ds_read_b64_tr_b16 v[192:193], v130 offset:0xe00
	ds_read_b64_tr_b16 v[194:195], v130 offset:0x1600
	ds_read_b64_tr_b16 v[196:197], v130 offset:0x1e00
	s_setprio 1
	v_exp_f32_e32 v64, v64
	v_exp_f32_e32 v65, v65
	v_exp_f32_e32 v66, v66
	v_exp_f32_e32 v67, v67
	v_exp_f32_e32 v68, v68
	v_exp_f32_e32 v69, v69
	v_add_f32_e32 v159, v65, v64
	v_exp_f32_e32 v70, v70
	v_add_f32_e32 v159, v66, v159
	v_exp_f32_e32 v71, v71
	v_add_f32_e32 v159, v67, v159
	v_exp_f32_e32 v72, v72
	v_add_f32_e32 v159, v68, v159
	v_exp_f32_e32 v73, v73
	v_add_f32_e32 v159, v69, v159
	v_exp_f32_e32 v74, v74
	v_add_f32_e32 v159, v70, v159
	v_exp_f32_e32 v75, v75
	v_add_f32_e32 v159, v71, v159
	v_exp_f32_e32 v76, v76
	v_add_f32_e32 v159, v72, v159
	v_exp_f32_e32 v77, v77
	v_add_f32_e32 v159, v73, v159
	v_exp_f32_e32 v78, v78
	v_add_f32_e32 v159, v74, v159
	v_exp_f32_e32 v79, v79
	v_add_f32_e32 v159, v75, v159
	v_add_f32_e32 v159, v76, v159
	v_add_f32_e32 v159, v77, v159
	v_add_f32_e32 v159, v78, v159
	v_add_f32_e32 v159, v79, v159
	v_add_f32_e32 v161, v161, v159
	v_cvt_pk_bf16_f32 v64, v64, v65
	v_cvt_pk_bf16_f32 v65, v66, v67
	v_cvt_pk_bf16_f32 v66, v68, v69
	v_cvt_pk_bf16_f32 v67, v70, v71
	v_cvt_pk_bf16_f32 v68, v72, v73
	v_cvt_pk_bf16_f32 v69, v74, v75
	v_cvt_pk_bf16_f32 v70, v76, v77
	v_cvt_pk_bf16_f32 v71, v78, v79
	s_waitcnt lgkmcnt(0)
	v_add_u32_e32 v72, v158, v152
	v_add_u32_e32 v73, v158, v153
	ds_read_b128 v[198:201], v72
	ds_read_b128 v[202:205], v73
	v_add_u32_e32 v72, v158, v154
	v_add_u32_e32 v73, v158, v155
	ds_read_b128 v[152:155], v72
	ds_read_b128 v[206:209], v73
	v_add_u32_e32 v72, v158, v156
	v_add_u32_e32 v73, v158, v157
	ds_read_b128 v[156:159], v72
	ds_read_b128 v[210:213], v73
	s_setprio 2
	v_mfma_f32_32x32x16_bf16 v[48:63], v[64:67], v[166:169], v[48:63]
	v_mfma_f32_32x32x16_bf16 v[32:47], v[64:67], v[174:177], v[32:47]
	v_mfma_f32_32x32x16_bf16 v[16:31], v[64:67], v[182:185], v[16:31]
	v_mfma_f32_32x32x16_bf16 v[0:15], v[64:67], v[190:193], v[0:15]
	v_mfma_f32_32x32x16_bf16 v[48:63], v[68:71], v[170:173], v[48:63]
	v_mfma_f32_32x32x16_bf16 v[32:47], v[68:71], v[178:181], v[32:47]
	v_mfma_f32_32x32x16_bf16 v[16:31], v[68:71], v[186:189], v[16:31]
	v_mfma_f32_32x32x16_bf16 v[0:15], v[68:71], v[194:197], v[0:15]
	s_waitcnt lgkmcnt(0)
	v_mfma_f32_32x32x16_bf16 v[64:79], v[132:135], v[80:83], 0
	v_mfma_f32_32x32x16_bf16 v[64:79], v[136:139], v[84:87], v[64:79]
	v_mfma_f32_32x32x16_bf16 v[64:79], v[140:143], v[88:91], v[64:79]
	v_mfma_f32_32x32x16_bf16 v[64:79], v[162:165], v[92:95], v[64:79]
	v_mfma_f32_32x32x16_bf16 v[64:79], v[144:147], v[96:99], v[64:79]
	v_mfma_f32_32x32x16_bf16 v[64:79], v[148:151], v[100:103], v[64:79]
	s_waitcnt lgkmcnt(0)
	v_mfma_f32_32x32x16_bf16 v[64:79], v[198:201], v[104:107], v[64:79]
	v_mfma_f32_32x32x16_bf16 v[64:79], v[202:205], v[108:111], v[64:79]
	v_mfma_f32_32x32x16_bf16 v[64:79], v[152:155], v[112:115], v[64:79]
	v_mfma_f32_32x32x16_bf16 v[64:79], v[206:209], v[116:119], v[64:79]
	v_mfma_f32_32x32x16_bf16 v[64:79], v[156:159], v[120:123], v[64:79]
	v_mfma_f32_32x32x16_bf16 v[64:79], v[210:213], v[124:127], v[64:79]
	s_setprio 0
	ds_read_b64_tr_b16 v[80:81], v130 offset:0x2000
	ds_read_b64_tr_b16 v[82:83], v130 offset:0x2800
	ds_read_b64_tr_b16 v[84:85], v130 offset:0x3000
	ds_read_b64_tr_b16 v[86:87], v130 offset:0x3800
	ds_read_b64_tr_b16 v[88:89], v130 offset:0x2200
	ds_read_b64_tr_b16 v[90:91], v130 offset:0x2a00
	ds_read_b64_tr_b16 v[92:93], v130 offset:0x3200
	ds_read_b64_tr_b16 v[94:95], v130 offset:0x3a00
	ds_read_b64_tr_b16 v[96:97], v130 offset:0x2400
	ds_read_b64_tr_b16 v[98:99], v130 offset:0x2c00
	ds_read_b64_tr_b16 v[100:101], v130 offset:0x3400
	ds_read_b64_tr_b16 v[102:103], v130 offset:0x3c00
	ds_read_b64_tr_b16 v[104:105], v130 offset:0x2600
	ds_read_b64_tr_b16 v[106:107], v130 offset:0x2e00
	ds_read_b64_tr_b16 v[108:109], v130 offset:0x3600
	ds_read_b64_tr_b16 v[110:111], v130 offset:0x3e00
	s_nop 11
	s_setprio 1
	v_exp_f32_e32 v112, v64
	v_exp_f32_e32 v65, v65
	v_exp_f32_e32 v113, v66
	v_exp_f32_e32 v67, v67
	v_exp_f32_e32 v68, v68
	v_exp_f32_e32 v69, v69
	v_add_f32_e32 v64, v65, v112
	v_exp_f32_e32 v70, v70
	v_add_f32_e32 v64, v113, v64
	v_exp_f32_e32 v71, v71
	v_add_f32_e32 v64, v67, v64
	v_exp_f32_e32 v72, v72
	v_add_f32_e32 v64, v68, v64
	v_exp_f32_e32 v73, v73
	v_add_f32_e32 v64, v69, v64
	v_exp_f32_e32 v74, v74
	v_add_f32_e32 v64, v70, v64
	v_exp_f32_e32 v75, v75
	v_add_f32_e32 v64, v71, v64
	v_exp_f32_e32 v76, v76
	v_add_f32_e32 v64, v72, v64
	v_exp_f32_e32 v77, v77
	v_add_f32_e32 v64, v73, v64
	v_exp_f32_e32 v78, v78
	v_add_f32_e32 v64, v74, v64
	v_exp_f32_e32 v79, v79
	v_add_f32_e32 v64, v75, v64
	v_add_f32_e32 v64, v76, v64
	v_add_f32_e32 v64, v77, v64
	v_add_f32_e32 v64, v78, v64
	v_add_f32_e32 v64, v79, v64
	v_add_f32_e32 v64, v161, v64
	v_cvt_pk_bf16_f32 v66, v112, v65
	v_cvt_pk_bf16_f32 v67, v113, v67
	v_cvt_pk_bf16_f32 v68, v68, v69
	v_cvt_pk_bf16_f32 v69, v70, v71
	v_cvt_pk_bf16_f32 v70, v72, v73
	v_cvt_pk_bf16_f32 v71, v74, v75
	v_cvt_pk_bf16_f32 v72, v76, v77
	v_cvt_pk_bf16_f32 v73, v78, v79
	s_waitcnt lgkmcnt(0)
	s_setprio 2
	v_mfma_f32_32x32x16_bf16 v[48:63], v[66:69], v[80:83], v[48:63]
	v_mfma_f32_32x32x16_bf16 v[32:47], v[66:69], v[88:91], v[32:47]
	v_mfma_f32_32x32x16_bf16 v[16:31], v[66:69], v[96:99], v[16:31]
	v_mfma_f32_32x32x16_bf16 v[0:15], v[66:69], v[104:107], v[0:15]
	v_mfma_f32_32x32x16_bf16 v[48:63], v[70:73], v[84:87], v[48:63]
	v_mfma_f32_32x32x16_bf16 v[32:47], v[70:73], v[92:95], v[32:47]
	v_mfma_f32_32x32x16_bf16 v[16:31], v[70:73], v[100:103], v[16:31]
	v_mfma_f32_32x32x16_bf16 v[0:15], v[70:73], v[108:111], v[0:15]
	s_setprio 0
	v_mbcnt_lo_u32_b32 v66, -1, 0
	v_mbcnt_hi_u32_b32 v66, -1, v66
	v_mov_b32_e32 v67, v64
	v_and_b32_e32 v65, 31, v66
	v_bfe_u32 v66, v66, 5, 1
	v_permlane32_swap_b32_e32 v64, v67
	v_cmp_eq_u32_e32 vcc, 0, v66
	s_and_saveexec_b64 s[2:3], vcc
	s_cbranch_execz .LBB0_1910
; template <int TAG = 0> DI int fresh_tid(int wv) { int l; asm volatile("v_mbcnt_lo_u32_b32 %0, -1, 0\n\tv_mbcnt_hi_u32_b32 %0, -1, %0 ; site %1" : "=v"(l) : "n"(TAG)); return wv * 64 + l; }
; DI float swap_sum(float v) { auto rr = __builtin_amdgcn_permlane32_swap(__float_as_uint(v), __float_as_uint(v), false, false); return __uint_as_float(rr[0]) + __uint_as_float(rr[1]); }
; template <int DQK, int MODE, int LDQ, int LDK, int LDV> ...
;     ...
;     l_reg = swap_sum(l_reg);
;     { const int lane2 = fresh_tid<110 + MODE>(wv) & 63, r32 = lane2 & 31, hi = lane2 >> 5;
;     if (hi == 0) li_l[r32] = l_reg;
;     asm volatile("s_waitcnt lgkmcnt(0)" ::: "memory");
	v_lshl_add_u32 v68, v65, 2, s4
	v_add_f32_e32 v64, v64, v67
	ds_write_b32 v68, v64
	s_branch .LBB0_1910
